# K-loop handoff: released wave delayed by s_nop 3 in phases 4/8 (short post-barrier path) to avoid MFMA overlap with partner's last MFMA
# speedup vs baseline: 1.0024x; 1.0024x over previous
; #define PG8_STAGE(bufoff, gbase, voff) do { _Pragma("unroll") for (int _i = 0; _i < 2; ++_i) \
;         __builtin_amdgcn_global_load_lds((const unsigned*)((const char*)(gbase) + (voff)[_i]), (LAS unsigned*)(lds + (bufoff) + ldsw + _i * 8192), 16, 0, 0); } while (0)
; #define PG8_LDA(dst, b, h) do { _Pragma("unroll") for (int m = 0; m < 4; ++m) _Pragma("unroll") for (int k = 0; k < 2; ++k) dst[m][k] = *(const LAS bf16x8*)(lds + PG8_SA(b, h) + aoff + m * 2048 + k * 1024); } while (0)
; #define PG8_LDB(dst, b, h) do { _Pragma("unroll") for (int n = 0; n < 2; ++n) _Pragma("unroll") for (int k = 0; k < 2; ++k) dst[n][k] = *(const LAS bf16x8*)(lds + PG8_SB(b, h) + boff + n * 2048 + k * 1024); } while (0)
; #define PG8_MMA(ai, bj, At, Bt) do { __builtin_amdgcn_s_setprio(1); _Pragma("unroll") for (int m = 0; m < 4; ++m) _Pragma("unroll") for (int n = 0; n < 2; ++n) _Pragma("unroll") for (int k = 0; k < 2; ++k) \
;         acc[ai][bj][m][n] = __builtin_amdgcn_mfma_f32_16x16x32_bf16(Bt[n][k], At[m][k], acc[ai][bj][m][n], 0, 0, 0); __builtin_amdgcn_s_setprio(0); } while (0)
; template <class Epi>
; __device__ __forceinline__ void gemm_phase(ldsp lds, const Gemm g, const StaticOrder& S, const Epi& E) {
;     ...
;             const bool last = (t == nt - 2);
;             const char* a1 = cA + (size_t)(t + 1) * kstep;
;             const char* a2 = last ? nA : cA + (size_t)(t + 2) * kstep; const char* b2 = last ? nB : cB + (size_t)(t + 2) * kstep;
;             const char* a3 = a2 + kstep; const char* b3 = b2 + kstep;
;             if constexpr (Epi::NPRE > 0) { if (last) E.pre(pre, cur, wr, fr); }
;             if constexpr (Epi::MID_T > 0) { if (t == Epi::MID_T) E.mid(acc, cur, wr, wc, fr, fq); }
;             PG8_LDB(B0, 0, 0); PG8_SCHED; PG8_LDA(At, 0, 0); PG8_STAGE(PG8_SA(1, 1), a1 + hstep, voffA);
;             PG8_WAIT_L(8); PG8_WAIT_V(10); PG8_BAR; PG8_WAIT_L(0); PG8_MMA(0, 0, At, B0); PG8_BAR; PG8_SCHED;
;             PG8_LDB(B1, 0, 1); PG8_STAGE(PG8_SB(0, 0), b2, voffB);
;             PG8_WAIT_V(10); PG8_BAR; PG8_WAIT_L(0); PG8_MMA(0, 1, At, B1); PG8_BAR;
;             PG8_LDA(At, 0, 1); PG8_STAGE(PG8_SA(0, 0), a2, voffA);
;             PG8_WAIT_V(10); PG8_BAR; PG8_WAIT_L(0); PG8_MMA(1, 0, At, B0); PG8_BAR; PG8_SCHED;
;             PG8_STAGE(PG8_SB(0, 1), b2 + hstep, voffB);
;             PG8_WAIT_V(10); PG8_BAR; PG8_MMA(1, 1, At, B1); PG8_BAR;
.LBB0_133:
	ds_read_b128 v[166:169], v247 offset:0
	ds_read_b128 v[170:173], v247 offset:1024
	ds_read_b128 v[174:177], v247 offset:2048
	ds_read_b128 v[184:187], v247 offset:3072
	s_add_u32 s38, s4, 0xfff80080
	s_addc_u32 s39, s5, -1
	s_and_b64 s[36:37], s[36:37], exec
	s_cselect_b32 s39, s7, s39
	s_cselect_b32 s38, s29, s38
	s_cselect_b32 s37, s27, s42
	s_cselect_b32 s36, s40, s41
	s_add_i32 m0, s45, 0xc000
	ds_read_b128 v[188:191], v183
	ds_read_b128 v[192:195], v183 offset:1024
	ds_read_b128 v[196:199], v183 offset:2048
	ds_read_b128 v[200:203], v183 offset:3072
	ds_read_b128 v[204:207], v183 offset:4096
	ds_read_b128 v[208:211], v183 offset:5120
	ds_read_b128 v[212:215], v183 offset:6144
	ds_read_b128 v[216:219], v183 offset:7168
	global_load_lds_dwordx4 v138, s[4:5]
	s_add_i32 m0, s45, 0xe000
	s_nop 0
	global_load_lds_dwordx4 v140, s[4:5]
	s_waitcnt lgkmcnt(8)
	s_waitcnt vmcnt(10)
	s_barrier
	s_waitcnt lgkmcnt(0)
	s_setprio 1
	s_waitcnt lgkmcnt(0)
	v_mfma_f32_16x16x32_bf16 v[60:63], v[166:169], v[188:191], v[60:63]
	v_mfma_f32_16x16x32_bf16 v[56:59], v[174:177], v[188:191], v[56:59]
	v_mfma_f32_16x16x32_bf16 v[52:55], v[166:169], v[196:199], v[52:55]
	v_mfma_f32_16x16x32_bf16 v[48:51], v[174:177], v[196:199], v[48:51]
	v_mfma_f32_16x16x32_bf16 v[44:47], v[166:169], v[204:207], v[44:47]
	v_mfma_f32_16x16x32_bf16 v[40:43], v[174:177], v[204:207], v[40:43]
	v_mfma_f32_16x16x32_bf16 v[36:39], v[166:169], v[212:215], v[36:39]
	v_mfma_f32_16x16x32_bf16 v[32:35], v[174:177], v[212:215], v[32:35]
	v_mfma_f32_16x16x32_bf16 v[60:63], v[170:173], v[192:195], v[60:63]
	v_mfma_f32_16x16x32_bf16 v[56:59], v[184:187], v[192:195], v[56:59]
	v_mfma_f32_16x16x32_bf16 v[52:55], v[170:173], v[200:203], v[52:55]
	v_mfma_f32_16x16x32_bf16 v[48:51], v[184:187], v[200:203], v[48:51]
	v_mfma_f32_16x16x32_bf16 v[44:47], v[170:173], v[208:211], v[44:47]
	v_mfma_f32_16x16x32_bf16 v[40:43], v[184:187], v[208:211], v[40:43]
	v_mfma_f32_16x16x32_bf16 v[36:39], v[170:173], v[216:219], v[36:39]
	s_barrier
	v_mfma_f32_16x16x32_bf16 v[32:35], v[184:187], v[216:219], v[32:35]
	s_setprio 0
	s_add_i32 s59, s57, s44
	s_add_u32 s98, s36, 0x80
	s_addc_u32 s99, s37, 0
	s_mov_b32 m0, s59
	ds_read_b128 v[222:225], v247 offset:16384
	ds_read_b128 v[226:229], v247 offset:17408
	ds_read_b128 v[230:233], v247 offset:18432
	ds_read_b128 v[234:237], v247 offset:19456
	global_load_lds_dwordx4 v130, s[36:37]
	s_add_i32 m0, s59, 0x2000
	s_nop 0
	global_load_lds_dwordx4 v134, s[36:37]
	s_waitcnt vmcnt(10)
	s_barrier
	s_waitcnt lgkmcnt(0)
	s_setprio 1
	s_waitcnt lgkmcnt(0)
	v_mfma_f32_16x16x32_bf16 v[124:127], v[222:225], v[188:191], v[124:127]
	v_mfma_f32_16x16x32_bf16 v[120:123], v[230:233], v[188:191], v[120:123]
	v_mfma_f32_16x16x32_bf16 v[116:119], v[222:225], v[196:199], v[116:119]
	v_mfma_f32_16x16x32_bf16 v[112:115], v[230:233], v[196:199], v[112:115]
	v_mfma_f32_16x16x32_bf16 v[108:111], v[222:225], v[204:207], v[108:111]
	v_mfma_f32_16x16x32_bf16 v[104:107], v[230:233], v[204:207], v[104:107]
	v_mfma_f32_16x16x32_bf16 v[100:103], v[222:225], v[212:215], v[100:103]
	v_mfma_f32_16x16x32_bf16 v[96:99], v[230:233], v[212:215], v[96:99]
	v_mfma_f32_16x16x32_bf16 v[124:127], v[226:229], v[192:195], v[124:127]
	v_mfma_f32_16x16x32_bf16 v[120:123], v[234:237], v[192:195], v[120:123]
	v_mfma_f32_16x16x32_bf16 v[116:119], v[226:229], v[200:203], v[116:119]
	v_mfma_f32_16x16x32_bf16 v[112:115], v[234:237], v[200:203], v[112:115]
	v_mfma_f32_16x16x32_bf16 v[108:111], v[226:229], v[208:211], v[108:111]
	v_mfma_f32_16x16x32_bf16 v[104:107], v[234:237], v[208:211], v[104:107]
	v_mfma_f32_16x16x32_bf16 v[100:103], v[226:229], v[216:219], v[100:103]
	s_barrier
	v_mfma_f32_16x16x32_bf16 v[96:99], v[234:237], v[216:219], v[96:99]
	s_setprio 0
	s_mov_b32 m0, s45
	s_add_u32 s100, s38, 0x80
	s_addc_u32 s101, s39, 0
	ds_read_b128 v[188:191], v183 offset:16384
	ds_read_b128 v[192:195], v183 offset:17408
	ds_read_b128 v[196:199], v183 offset:18432
	ds_read_b128 v[200:203], v183 offset:19456
	ds_read_b128 v[204:207], v183 offset:20480
	ds_read_b128 v[208:211], v183 offset:21504
	ds_read_b128 v[212:215], v183 offset:22528
	ds_read_b128 v[216:219], v183 offset:23552
	global_load_lds_dwordx4 v128, s[38:39]
	s_mov_b32 m0, s46
	s_nop 0
	global_load_lds_dwordx4 v132, s[38:39]
	s_waitcnt vmcnt(10)
	s_barrier
	s_waitcnt lgkmcnt(0)
	s_setprio 1
	s_waitcnt lgkmcnt(0)
	v_mfma_f32_16x16x32_bf16 v[28:31], v[166:169], v[188:191], v[28:31]
	v_mfma_f32_16x16x32_bf16 v[24:27], v[174:177], v[188:191], v[24:27]
	v_mfma_f32_16x16x32_bf16 v[20:23], v[166:169], v[196:199], v[20:23]
	v_mfma_f32_16x16x32_bf16 v[16:19], v[174:177], v[196:199], v[16:19]
	v_mfma_f32_16x16x32_bf16 v[12:15], v[166:169], v[204:207], v[12:15]
	v_mfma_f32_16x16x32_bf16 v[8:11], v[174:177], v[204:207], v[8:11]
	v_mfma_f32_16x16x32_bf16 v[4:7], v[166:169], v[212:215], v[4:7]
	v_mfma_f32_16x16x32_bf16 v[0:3], v[174:177], v[212:215], v[0:3]
	v_mfma_f32_16x16x32_bf16 v[28:31], v[170:173], v[192:195], v[28:31]
	v_mfma_f32_16x16x32_bf16 v[24:27], v[184:187], v[192:195], v[24:27]
	v_mfma_f32_16x16x32_bf16 v[20:23], v[170:173], v[200:203], v[20:23]
	v_mfma_f32_16x16x32_bf16 v[16:19], v[184:187], v[200:203], v[16:19]
	v_mfma_f32_16x16x32_bf16 v[12:15], v[170:173], v[208:211], v[12:15]
	v_mfma_f32_16x16x32_bf16 v[8:11], v[184:187], v[208:211], v[8:11]
	v_mfma_f32_16x16x32_bf16 v[4:7], v[170:173], v[216:219], v[4:7]
	s_barrier
	v_mfma_f32_16x16x32_bf16 v[0:3], v[184:187], v[216:219], v[0:3]
	s_setprio 0
	s_add_u32 s60, s36, 0x80000
	s_addc_u32 s61, s37, 0
	s_add_i32 s59, s58, s44
	s_mov_b32 m0, s59
	s_nop 0
	global_load_lds_dwordx4 v130, s[60:61]
	s_add_i32 m0, s59, 0x2000
	s_nop 0
	global_load_lds_dwordx4 v134, s[60:61]
	s_waitcnt vmcnt(10)
	s_barrier
; #define PG8_STAGE(bufoff, gbase, voff) do { _Pragma("unroll") for (int _i = 0; _i < 2; ++_i) \
;         __builtin_amdgcn_global_load_lds((const unsigned*)((const char*)(gbase) + (voff)[_i]), (LAS unsigned*)(lds + (bufoff) + ldsw + _i * 8192), 16, 0, 0); } while (0)
; #define PG8_LDA(dst, b, h) do { _Pragma("unroll") for (int m = 0; m < 4; ++m) _Pragma("unroll") for (int k = 0; k < 2; ++k) dst[m][k] = *(const LAS bf16x8*)(lds + PG8_SA(b, h) + aoff + m * 2048 + k * 1024); } while (0)
; #define PG8_LDB(dst, b, h) do { _Pragma("unroll") for (int n = 0; n < 2; ++n) _Pragma("unroll") for (int k = 0; k < 2; ++k) dst[n][k] = *(const LAS bf16x8*)(lds + PG8_SB(b, h) + boff + n * 2048 + k * 1024); } while (0)
; #define PG8_MMA(ai, bj, At, Bt) do { __builtin_amdgcn_s_setprio(1); _Pragma("unroll") for (int m = 0; m < 4; ++m) _Pragma("unroll") for (int n = 0; n < 2; ++n) _Pragma("unroll") for (int k = 0; k < 2; ++k) \
;         acc[ai][bj][m][n] = __builtin_amdgcn_mfma_f32_16x16x32_bf16(Bt[n][k], At[m][k], acc[ai][bj][m][n], 0, 0, 0); __builtin_amdgcn_s_setprio(0); } while (0)
; #define PG8_WAIT_V(n) asm volatile("s_waitcnt vmcnt(" #n ")" ::: "memory")
; #define PG8_WAIT_L(n) asm volatile("s_waitcnt lgkmcnt(" #n ")" ::: "memory")
; #define PG8_BAR __builtin_amdgcn_s_barrier()
; #define PG8_SCHED __builtin_amdgcn_sched_barrier(0)
; template <class Epi>
; __device__ __forceinline__ void gemm_phase(ldsp lds, const Gemm g, const StaticOrder& S, const Epi& E) {
;     ...
;             PG8_WAIT_V(10); PG8_BAR; PG8_MMA(1, 1, At, B1); PG8_BAR;
;             PG8_LDB(B0, 1, 0); PG8_SCHED; PG8_LDA(At, 1, 0); PG8_STAGE(PG8_SA(0, 1), a2 + hstep, voffA);
;             PG8_WAIT_L(8); PG8_WAIT_V(10); PG8_BAR; PG8_WAIT_L(0); PG8_MMA(0, 0, At, B0); PG8_BAR; PG8_SCHED;
;             PG8_LDB(B1, 1, 1); PG8_STAGE(PG8_SB(1, 0), b3, voffB);
;             PG8_WAIT_V(10); PG8_BAR; PG8_WAIT_L(0); PG8_MMA(0, 1, At, B1); PG8_BAR;
	s_nop 3
	s_setprio 1
	v_mfma_f32_16x16x32_bf16 v[92:95], v[222:225], v[188:191], v[92:95]
	v_mfma_f32_16x16x32_bf16 v[88:91], v[230:233], v[188:191], v[88:91]
	v_mfma_f32_16x16x32_bf16 v[84:87], v[222:225], v[196:199], v[84:87]
	v_mfma_f32_16x16x32_bf16 v[80:83], v[230:233], v[196:199], v[80:83]
	v_mfma_f32_16x16x32_bf16 v[76:79], v[222:225], v[204:207], v[76:79]
	v_mfma_f32_16x16x32_bf16 v[72:75], v[230:233], v[204:207], v[72:75]
	v_mfma_f32_16x16x32_bf16 v[68:71], v[222:225], v[212:215], v[68:71]
	v_mfma_f32_16x16x32_bf16 v[64:67], v[230:233], v[212:215], v[64:67]
	v_mfma_f32_16x16x32_bf16 v[92:95], v[226:229], v[192:195], v[92:95]
	v_mfma_f32_16x16x32_bf16 v[88:91], v[234:237], v[192:195], v[88:91]
	v_mfma_f32_16x16x32_bf16 v[84:87], v[226:229], v[200:203], v[84:87]
	v_mfma_f32_16x16x32_bf16 v[80:83], v[234:237], v[200:203], v[80:83]
	v_mfma_f32_16x16x32_bf16 v[76:79], v[226:229], v[208:211], v[76:79]
	v_mfma_f32_16x16x32_bf16 v[72:75], v[234:237], v[208:211], v[72:75]
	v_mfma_f32_16x16x32_bf16 v[68:71], v[226:229], v[216:219], v[68:71]
	s_barrier
	v_mfma_f32_16x16x32_bf16 v[64:67], v[234:237], v[216:219], v[64:67]
	s_setprio 0
	s_add_i32 s59, 0, 0x18000
	ds_read_b128 v[166:169], v247 offset:32768
	ds_read_b128 v[170:173], v247 offset:33792
	ds_read_b128 v[174:177], v247 offset:34816
	ds_read_b128 v[184:187], v247 offset:35840
	s_add_u32 s38, s38, 0x80000
	s_addc_u32 s39, s39, 0
	s_mov_b32 m0, s47
	ds_read_b128 v[188:191], v183 offset:32768
	ds_read_b128 v[192:195], v183 offset:33792
	ds_read_b128 v[196:199], v183 offset:34816
	ds_read_b128 v[200:203], v183 offset:35840
	ds_read_b128 v[204:207], v183 offset:36864
	ds_read_b128 v[208:211], v183 offset:37888
	ds_read_b128 v[212:215], v183 offset:38912
	ds_read_b128 v[216:219], v183 offset:39936
	global_load_lds_dwordx4 v128, s[38:39]
	s_mov_b32 m0, s50
	s_nop 0
	global_load_lds_dwordx4 v132, s[38:39]
	s_waitcnt lgkmcnt(8)
	s_waitcnt vmcnt(10)
	s_barrier
	s_waitcnt lgkmcnt(0)
	s_setprio 1
	s_waitcnt lgkmcnt(0)
	v_mfma_f32_16x16x32_bf16 v[60:63], v[166:169], v[188:191], v[60:63]
	v_mfma_f32_16x16x32_bf16 v[56:59], v[174:177], v[188:191], v[56:59]
	v_mfma_f32_16x16x32_bf16 v[52:55], v[166:169], v[196:199], v[52:55]
	v_mfma_f32_16x16x32_bf16 v[48:51], v[174:177], v[196:199], v[48:51]
	v_mfma_f32_16x16x32_bf16 v[44:47], v[166:169], v[204:207], v[44:47]
	v_mfma_f32_16x16x32_bf16 v[40:43], v[174:177], v[204:207], v[40:43]
	v_mfma_f32_16x16x32_bf16 v[36:39], v[166:169], v[212:215], v[36:39]
	v_mfma_f32_16x16x32_bf16 v[32:35], v[174:177], v[212:215], v[32:35]
	v_mfma_f32_16x16x32_bf16 v[60:63], v[170:173], v[192:195], v[60:63]
	v_mfma_f32_16x16x32_bf16 v[56:59], v[184:187], v[192:195], v[56:59]
	v_mfma_f32_16x16x32_bf16 v[52:55], v[170:173], v[200:203], v[52:55]
	v_mfma_f32_16x16x32_bf16 v[48:51], v[184:187], v[200:203], v[48:51]
	v_mfma_f32_16x16x32_bf16 v[44:47], v[170:173], v[208:211], v[44:47]
	v_mfma_f32_16x16x32_bf16 v[40:43], v[184:187], v[208:211], v[40:43]
	v_mfma_f32_16x16x32_bf16 v[36:39], v[170:173], v[216:219], v[36:39]
	s_barrier
	v_mfma_f32_16x16x32_bf16 v[32:35], v[184:187], v[216:219], v[32:35]
	s_setprio 0
	s_add_i32 s38, 0, 0x1c000
	s_add_i32 s39, s59, s44
	s_mov_b32 m0, s39
	ds_read_b128 v[222:225], v247 offset:49152
	ds_read_b128 v[226:229], v247 offset:50176
	ds_read_b128 v[230:233], v247 offset:51200
	ds_read_b128 v[234:237], v247 offset:52224
	global_load_lds_dwordx4 v130, s[98:99]
	s_add_i32 m0, s39, 0x2000
	s_nop 0
	global_load_lds_dwordx4 v134, s[98:99]
	s_waitcnt vmcnt(10)
	s_barrier
; #define PG8_STAGE(bufoff, gbase, voff) do { _Pragma("unroll") for (int _i = 0; _i < 2; ++_i) \
;         __builtin_amdgcn_global_load_lds((const unsigned*)((const char*)(gbase) + (voff)[_i]), (LAS unsigned*)(lds + (bufoff) + ldsw + _i * 8192), 16, 0, 0); } while (0)
; #define PG8_LDA(dst, b, h) do { _Pragma("unroll") for (int m = 0; m < 4; ++m) _Pragma("unroll") for (int k = 0; k < 2; ++k) dst[m][k] = *(const LAS bf16x8*)(lds + PG8_SA(b, h) + aoff + m * 2048 + k * 1024); } while (0)
; #define PG8_MMA(ai, bj, At, Bt) do { __builtin_amdgcn_s_setprio(1); _Pragma("unroll") for (int m = 0; m < 4; ++m) _Pragma("unroll") for (int n = 0; n < 2; ++n) _Pragma("unroll") for (int k = 0; k < 2; ++k) \
;         acc[ai][bj][m][n] = __builtin_amdgcn_mfma_f32_16x16x32_bf16(Bt[n][k], At[m][k], acc[ai][bj][m][n], 0, 0, 0); __builtin_amdgcn_s_setprio(0); } while (0)
; #define PG8_WAIT_V(n) asm volatile("s_waitcnt vmcnt(" #n ")" ::: "memory")
; #define PG8_WAIT_L(n) asm volatile("s_waitcnt lgkmcnt(" #n ")" ::: "memory")
; #define PG8_BAR __builtin_amdgcn_s_barrier()
; #define PG8_SCHED __builtin_amdgcn_sched_barrier(0)
; template <class Epi>
; __device__ __forceinline__ void gemm_phase(ldsp lds, const Gemm g, const StaticOrder& S, const Epi& E) {
;     ...
;             PG8_WAIT_V(10); PG8_BAR; PG8_WAIT_L(0); PG8_MMA(0, 1, At, B1); PG8_BAR;
;             PG8_LDA(At, 1, 1); PG8_STAGE(PG8_SA(1, 0), a3, voffA);
;             PG8_WAIT_V(10); PG8_BAR; PG8_WAIT_L(0); PG8_MMA(1, 0, At, B0); PG8_BAR; PG8_SCHED;
;             PG8_STAGE(PG8_SB(1, 1), b3 + hstep, voffB);
;             PG8_WAIT_V(10); PG8_BAR; PG8_MMA(1, 1, At, B1); PG8_BAR;
	s_waitcnt lgkmcnt(0)
	s_setprio 1
	s_waitcnt lgkmcnt(0)
	v_mfma_f32_16x16x32_bf16 v[124:127], v[222:225], v[188:191], v[124:127]
	v_mfma_f32_16x16x32_bf16 v[120:123], v[230:233], v[188:191], v[120:123]
	v_mfma_f32_16x16x32_bf16 v[116:119], v[222:225], v[196:199], v[116:119]
	v_mfma_f32_16x16x32_bf16 v[112:115], v[230:233], v[196:199], v[112:115]
	v_mfma_f32_16x16x32_bf16 v[108:111], v[222:225], v[204:207], v[108:111]
	v_mfma_f32_16x16x32_bf16 v[104:107], v[230:233], v[204:207], v[104:107]
	v_mfma_f32_16x16x32_bf16 v[100:103], v[222:225], v[212:215], v[100:103]
	v_mfma_f32_16x16x32_bf16 v[96:99], v[230:233], v[212:215], v[96:99]
	v_mfma_f32_16x16x32_bf16 v[124:127], v[226:229], v[192:195], v[124:127]
	v_mfma_f32_16x16x32_bf16 v[120:123], v[234:237], v[192:195], v[120:123]
	v_mfma_f32_16x16x32_bf16 v[116:119], v[226:229], v[200:203], v[116:119]
	v_mfma_f32_16x16x32_bf16 v[112:115], v[234:237], v[200:203], v[112:115]
	v_mfma_f32_16x16x32_bf16 v[108:111], v[226:229], v[208:211], v[108:111]
	v_mfma_f32_16x16x32_bf16 v[104:107], v[234:237], v[208:211], v[104:107]
	v_mfma_f32_16x16x32_bf16 v[100:103], v[226:229], v[216:219], v[100:103]
	s_barrier
	v_mfma_f32_16x16x32_bf16 v[96:99], v[234:237], v[216:219], v[96:99]
	s_setprio 0
	s_mov_b32 m0, s52
	ds_read_b128 v[188:191], v183 offset:49152
	ds_read_b128 v[192:195], v183 offset:50176
	ds_read_b128 v[196:199], v183 offset:51200
	ds_read_b128 v[200:203], v183 offset:52224
	ds_read_b128 v[204:207], v183 offset:53248
	ds_read_b128 v[208:211], v183 offset:54272
	ds_read_b128 v[212:215], v183 offset:55296
	ds_read_b128 v[216:219], v183 offset:56320
	global_load_lds_dwordx4 v128, s[100:101]
	s_mov_b32 m0, s53
	s_nop 0
	global_load_lds_dwordx4 v132, s[100:101]
	s_waitcnt vmcnt(10)
	s_barrier
	s_waitcnt lgkmcnt(0)
	s_setprio 1
	s_waitcnt lgkmcnt(0)
	v_mfma_f32_16x16x32_bf16 v[28:31], v[166:169], v[188:191], v[28:31]
	v_mfma_f32_16x16x32_bf16 v[24:27], v[174:177], v[188:191], v[24:27]
	v_mfma_f32_16x16x32_bf16 v[20:23], v[166:169], v[196:199], v[20:23]
	v_mfma_f32_16x16x32_bf16 v[16:19], v[174:177], v[196:199], v[16:19]
	v_mfma_f32_16x16x32_bf16 v[12:15], v[166:169], v[204:207], v[12:15]
	v_mfma_f32_16x16x32_bf16 v[8:11], v[174:177], v[204:207], v[8:11]
	v_mfma_f32_16x16x32_bf16 v[4:7], v[166:169], v[212:215], v[4:7]
	v_mfma_f32_16x16x32_bf16 v[0:3], v[174:177], v[212:215], v[0:3]
	v_mfma_f32_16x16x32_bf16 v[28:31], v[170:173], v[192:195], v[28:31]
	v_mfma_f32_16x16x32_bf16 v[24:27], v[184:187], v[192:195], v[24:27]
	v_mfma_f32_16x16x32_bf16 v[20:23], v[170:173], v[200:203], v[20:23]
	v_mfma_f32_16x16x32_bf16 v[16:19], v[184:187], v[200:203], v[16:19]
	v_mfma_f32_16x16x32_bf16 v[12:15], v[170:173], v[208:211], v[12:15]
	v_mfma_f32_16x16x32_bf16 v[8:11], v[184:187], v[208:211], v[8:11]
	v_mfma_f32_16x16x32_bf16 v[4:7], v[170:173], v[216:219], v[4:7]
	s_barrier
	v_mfma_f32_16x16x32_bf16 v[0:3], v[184:187], v[216:219], v[0:3]
	s_setprio 0
	s_add_u32 s36, s36, 0x80080
	s_addc_u32 s37, s37, 0
	s_add_i32 s38, s38, s44
	s_mov_b32 m0, s38
	s_nop 0
	global_load_lds_dwordx4 v130, s[36:37]
	s_add_i32 m0, s38, 0x2000
	s_nop 0
	global_load_lds_dwordx4 v134, s[36:37]
	s_waitcnt vmcnt(10)
	s_barrier
	s_nop 3
	s_setprio 1
	v_mfma_f32_16x16x32_bf16 v[92:95], v[222:225], v[188:191], v[92:95]
	v_mfma_f32_16x16x32_bf16 v[88:91], v[230:233], v[188:191], v[88:91]
	v_mfma_f32_16x16x32_bf16 v[84:87], v[222:225], v[196:199], v[84:87]
	v_mfma_f32_16x16x32_bf16 v[80:83], v[230:233], v[196:199], v[80:83]
	v_mfma_f32_16x16x32_bf16 v[76:79], v[222:225], v[204:207], v[76:79]
	v_mfma_f32_16x16x32_bf16 v[72:75], v[230:233], v[204:207], v[72:75]
	v_mfma_f32_16x16x32_bf16 v[68:71], v[222:225], v[212:215], v[68:71]
	v_mfma_f32_16x16x32_bf16 v[64:67], v[230:233], v[212:215], v[64:67]
	v_mfma_f32_16x16x32_bf16 v[92:95], v[226:229], v[192:195], v[92:95]
	v_mfma_f32_16x16x32_bf16 v[88:91], v[234:237], v[192:195], v[88:91]
	v_mfma_f32_16x16x32_bf16 v[84:87], v[226:229], v[200:203], v[84:87]
	v_mfma_f32_16x16x32_bf16 v[80:83], v[234:237], v[200:203], v[80:83]
	v_mfma_f32_16x16x32_bf16 v[76:79], v[226:229], v[208:211], v[76:79]
	v_mfma_f32_16x16x32_bf16 v[72:75], v[234:237], v[208:211], v[72:75]
	v_mfma_f32_16x16x32_bf16 v[68:71], v[226:229], v[216:219], v[68:71]
	s_barrier
	v_mfma_f32_16x16x32_bf16 v[64:67], v[234:237], v[216:219], v[64:67]
	s_setprio 0
	s_add_i32 s43, s43, 2
	s_add_u32 s4, s4, 0x100
	s_addc_u32 s5, s5, 0
	s_add_u32 s41, s41, 0x100
	s_addc_u32 s42, s42, 0
	s_cmp_gt_u32 s43, 29
	s_cbranch_scc1 .LBB0_136

; #define PG8_STAGE(bufoff, gbase, voff) do { _Pragma("unroll") for (int _i = 0; _i < 2; ++_i) \
;         __builtin_amdgcn_global_load_lds((const unsigned*)((const char*)(gbase) + (voff)[_i]), (LAS unsigned*)(lds + (bufoff) + ldsw + _i * 8192), 16, 0, 0); } while (0)
; #define PG8_LDA(dst, b, h) do { _Pragma("unroll") for (int m = 0; m < 4; ++m) _Pragma("unroll") for (int k = 0; k < 2; ++k) dst[m][k] = *(const LAS bf16x8*)(lds + PG8_SA(b, h) + aoff + m * 2048 + k * 1024); } while (0)
; #define PG8_LDB(dst, b, h) do { _Pragma("unroll") for (int n = 0; n < 2; ++n) _Pragma("unroll") for (int k = 0; k < 2; ++k) dst[n][k] = *(const LAS bf16x8*)(lds + PG8_SB(b, h) + boff + n * 2048 + k * 1024); } while (0)
; #define PG8_MMA(ai, bj, At, Bt) do { __builtin_amdgcn_s_setprio(1); _Pragma("unroll") for (int m = 0; m < 4; ++m) _Pragma("unroll") for (int n = 0; n < 2; ++n) _Pragma("unroll") for (int k = 0; k < 2; ++k) \
;         acc[ai][bj][m][n] = __builtin_amdgcn_mfma_f32_16x16x32_bf16(Bt[n][k], At[m][k], acc[ai][bj][m][n], 0, 0, 0); __builtin_amdgcn_s_setprio(0); } while (0)
; template <class Epi>
; __device__ __forceinline__ void gemm_phase(ldsp lds, const Gemm g, const StaticOrder& S, const Epi& E) {
;     ...
;             const bool last = (t == nt - 2);
;             const char* a1 = cA + (size_t)(t + 1) * kstep;
;             const char* a2 = last ? nA : cA + (size_t)(t + 2) * kstep; const char* b2 = last ? nB : cB + (size_t)(t + 2) * kstep;
;             const char* a3 = a2 + kstep; const char* b3 = b2 + kstep;
;             if constexpr (Epi::NPRE > 0) { if (last) E.pre(pre, cur, wr, fr); }
;             if constexpr (Epi::MID_T > 0) { if (t == Epi::MID_T) E.mid(acc, cur, wr, wc, fr, fq); }
;             PG8_LDB(B0, 0, 0); PG8_SCHED; PG8_LDA(At, 0, 0); PG8_STAGE(PG8_SA(1, 1), a1 + hstep, voffA);
;             PG8_WAIT_L(8); PG8_WAIT_V(10); PG8_BAR; PG8_WAIT_L(0); PG8_MMA(0, 0, At, B0); PG8_BAR; PG8_SCHED;
;             PG8_LDB(B1, 0, 1); PG8_STAGE(PG8_SB(0, 0), b2, voffB);
;             PG8_WAIT_V(10); PG8_BAR; PG8_WAIT_L(0); PG8_MMA(0, 1, At, B1); PG8_BAR;
;             PG8_LDA(At, 0, 1); PG8_STAGE(PG8_SA(0, 0), a2, voffA);
;             PG8_WAIT_V(10); PG8_BAR; PG8_WAIT_L(0); PG8_MMA(1, 0, At, B0); PG8_BAR; PG8_SCHED;
;             PG8_STAGE(PG8_SB(0, 1), b2 + hstep, voffB);
;             PG8_WAIT_V(10); PG8_BAR; PG8_MMA(1, 1, At, B1); PG8_BAR;
.LBB0_574:
	ds_read_b128 v[128:131], v219
	ds_read_b128 v[132:135], v219 offset:1024
	ds_read_b128 v[136:139], v219 offset:2048
	ds_read_b128 v[140:143], v219 offset:3072
	s_add_u32 s22, s20, 0xfffe0080
	s_addc_u32 s23, s21, -1
	s_cmp_eq_u32 s46, 4
	s_cselect_b32 s25, s13, s23
	s_cselect_b32 s24, s42, s22
	s_cselect_b32 s23, s11, s45
	s_cselect_b32 s22, s43, s44
	s_add_i32 m0, s19, 0xc000
	ds_read_b128 v[144:147], v221
	ds_read_b128 v[148:151], v221 offset:1024
	ds_read_b128 v[152:155], v221 offset:2048
	ds_read_b128 v[156:159], v221 offset:3072
	ds_read_b128 v[160:163], v221 offset:4096
	ds_read_b128 v[164:167], v221 offset:5120
	ds_read_b128 v[168:171], v221 offset:6144
	ds_read_b128 v[172:175], v221 offset:7168
	global_load_lds_dwordx4 v184, s[20:21]
	s_add_i32 m0, s19, 0xe000
	s_nop 0
	global_load_lds_dwordx4 v186, s[20:21]
	s_waitcnt lgkmcnt(8)
	s_waitcnt vmcnt(10)
	s_barrier
	s_waitcnt lgkmcnt(0)
	s_setprio 1
	s_waitcnt lgkmcnt(0)
	v_mfma_f32_16x16x32_bf16 v[124:127], v[128:131], v[144:147], v[124:127]
	v_mfma_f32_16x16x32_bf16 v[120:123], v[136:139], v[144:147], v[120:123]
	v_mfma_f32_16x16x32_bf16 v[116:119], v[128:131], v[152:155], v[116:119]
	v_mfma_f32_16x16x32_bf16 v[112:115], v[136:139], v[152:155], v[112:115]
	v_mfma_f32_16x16x32_bf16 v[108:111], v[128:131], v[160:163], v[108:111]
	v_mfma_f32_16x16x32_bf16 v[104:107], v[136:139], v[160:163], v[104:107]
	v_mfma_f32_16x16x32_bf16 v[100:103], v[128:131], v[168:171], v[100:103]
	v_mfma_f32_16x16x32_bf16 v[96:99], v[136:139], v[168:171], v[96:99]
	v_mfma_f32_16x16x32_bf16 v[124:127], v[132:135], v[148:151], v[124:127]
	v_mfma_f32_16x16x32_bf16 v[120:123], v[140:143], v[148:151], v[120:123]
	v_mfma_f32_16x16x32_bf16 v[116:119], v[132:135], v[156:159], v[116:119]
	v_mfma_f32_16x16x32_bf16 v[112:115], v[140:143], v[156:159], v[112:115]
	v_mfma_f32_16x16x32_bf16 v[108:111], v[132:135], v[164:167], v[108:111]
	v_mfma_f32_16x16x32_bf16 v[104:107], v[140:143], v[164:167], v[104:107]
	v_mfma_f32_16x16x32_bf16 v[100:103], v[132:135], v[172:175], v[100:103]
	s_barrier
	v_mfma_f32_16x16x32_bf16 v[96:99], v[140:143], v[172:175], v[96:99]
	s_setprio 0
	s_add_i32 s47, s38, s28
	s_add_u32 s98, s22, 0x80
	s_addc_u32 s99, s23, 0
	s_mov_b32 m0, s47
	ds_read_b128 v[192:195], v222
	ds_read_b128 v[196:199], v222 offset:1024
	ds_read_b128 v[200:203], v222 offset:2048
	ds_read_b128 v[204:207], v222 offset:3072
	global_load_lds_dwordx4 v178, s[22:23]
	s_add_i32 m0, s47, 0x2000
	s_nop 0
	global_load_lds_dwordx4 v182, s[22:23]
	s_waitcnt vmcnt(10)
	s_barrier
	s_waitcnt lgkmcnt(0)
	s_setprio 1
	s_waitcnt lgkmcnt(0)
	v_mfma_f32_16x16x32_bf16 v[60:63], v[192:195], v[144:147], v[60:63]
	v_mfma_f32_16x16x32_bf16 v[56:59], v[200:203], v[144:147], v[56:59]
	v_mfma_f32_16x16x32_bf16 v[52:55], v[192:195], v[152:155], v[52:55]
	v_mfma_f32_16x16x32_bf16 v[48:51], v[200:203], v[152:155], v[48:51]
	v_mfma_f32_16x16x32_bf16 v[44:47], v[192:195], v[160:163], v[44:47]
	v_mfma_f32_16x16x32_bf16 v[40:43], v[200:203], v[160:163], v[40:43]
	v_mfma_f32_16x16x32_bf16 v[36:39], v[192:195], v[168:171], v[36:39]
	v_mfma_f32_16x16x32_bf16 v[32:35], v[200:203], v[168:171], v[32:35]
	v_mfma_f32_16x16x32_bf16 v[60:63], v[196:199], v[148:151], v[60:63]
	v_mfma_f32_16x16x32_bf16 v[56:59], v[204:207], v[148:151], v[56:59]
	v_mfma_f32_16x16x32_bf16 v[52:55], v[196:199], v[156:159], v[52:55]
	v_mfma_f32_16x16x32_bf16 v[48:51], v[204:207], v[156:159], v[48:51]
	v_mfma_f32_16x16x32_bf16 v[44:47], v[196:199], v[164:167], v[44:47]
	v_mfma_f32_16x16x32_bf16 v[40:43], v[204:207], v[164:167], v[40:43]
	v_mfma_f32_16x16x32_bf16 v[36:39], v[196:199], v[172:175], v[36:39]
	s_barrier
	v_mfma_f32_16x16x32_bf16 v[32:35], v[204:207], v[172:175], v[32:35]
	s_setprio 0
	s_mov_b32 m0, s19
	s_add_u32 s100, s24, 0x80
	s_addc_u32 s101, s25, 0
	ds_read_b128 v[144:147], v221 offset:16384
	ds_read_b128 v[148:151], v221 offset:17408
	ds_read_b128 v[152:155], v221 offset:18432
	ds_read_b128 v[156:159], v221 offset:19456
	ds_read_b128 v[160:163], v221 offset:20480
	ds_read_b128 v[164:167], v221 offset:21504
	ds_read_b128 v[168:171], v221 offset:22528
	ds_read_b128 v[172:175], v221 offset:23552
	global_load_lds_dwordx4 v176, s[24:25]
	s_mov_b32 m0, s29
	s_nop 0
	global_load_lds_dwordx4 v180, s[24:25]
	s_waitcnt vmcnt(10)
	s_barrier
	s_waitcnt lgkmcnt(0)
	s_setprio 1
	s_waitcnt lgkmcnt(0)
	v_mfma_f32_16x16x32_bf16 v[92:95], v[128:131], v[144:147], v[92:95]
	v_mfma_f32_16x16x32_bf16 v[88:91], v[136:139], v[144:147], v[88:91]
	v_mfma_f32_16x16x32_bf16 v[84:87], v[128:131], v[152:155], v[84:87]
	v_mfma_f32_16x16x32_bf16 v[80:83], v[136:139], v[152:155], v[80:83]
	v_mfma_f32_16x16x32_bf16 v[76:79], v[128:131], v[160:163], v[76:79]
	v_mfma_f32_16x16x32_bf16 v[72:75], v[136:139], v[160:163], v[72:75]
	v_mfma_f32_16x16x32_bf16 v[68:71], v[128:131], v[168:171], v[68:71]
	v_mfma_f32_16x16x32_bf16 v[64:67], v[136:139], v[168:171], v[64:67]
	v_mfma_f32_16x16x32_bf16 v[92:95], v[132:135], v[148:151], v[92:95]
	v_mfma_f32_16x16x32_bf16 v[88:91], v[140:143], v[148:151], v[88:91]
	v_mfma_f32_16x16x32_bf16 v[84:87], v[132:135], v[156:159], v[84:87]
	v_mfma_f32_16x16x32_bf16 v[80:83], v[140:143], v[156:159], v[80:83]
	v_mfma_f32_16x16x32_bf16 v[76:79], v[132:135], v[164:167], v[76:79]
	v_mfma_f32_16x16x32_bf16 v[72:75], v[140:143], v[164:167], v[72:75]
	v_mfma_f32_16x16x32_bf16 v[68:71], v[132:135], v[172:175], v[68:71]
	s_barrier
	v_mfma_f32_16x16x32_bf16 v[64:67], v[140:143], v[172:175], v[64:67]
	s_setprio 0
	s_add_u32 s50, s22, 0x20000
	s_addc_u32 s51, s23, 0
	s_add_i32 s47, s39, s28
	s_mov_b32 m0, s47
	s_nop 0
	global_load_lds_dwordx4 v178, s[50:51]
	s_add_i32 m0, s47, 0x2000
	s_nop 0
	global_load_lds_dwordx4 v182, s[50:51]
	s_waitcnt vmcnt(10)
	s_barrier
; #define PG8_STAGE(bufoff, gbase, voff) do { _Pragma("unroll") for (int _i = 0; _i < 2; ++_i) \
;         __builtin_amdgcn_global_load_lds((const unsigned*)((const char*)(gbase) + (voff)[_i]), (LAS unsigned*)(lds + (bufoff) + ldsw + _i * 8192), 16, 0, 0); } while (0)
; #define PG8_LDA(dst, b, h) do { _Pragma("unroll") for (int m = 0; m < 4; ++m) _Pragma("unroll") for (int k = 0; k < 2; ++k) dst[m][k] = *(const LAS bf16x8*)(lds + PG8_SA(b, h) + aoff + m * 2048 + k * 1024); } while (0)
; #define PG8_LDB(dst, b, h) do { _Pragma("unroll") for (int n = 0; n < 2; ++n) _Pragma("unroll") for (int k = 0; k < 2; ++k) dst[n][k] = *(const LAS bf16x8*)(lds + PG8_SB(b, h) + boff + n * 2048 + k * 1024); } while (0)
; #define PG8_MMA(ai, bj, At, Bt) do { __builtin_amdgcn_s_setprio(1); _Pragma("unroll") for (int m = 0; m < 4; ++m) _Pragma("unroll") for (int n = 0; n < 2; ++n) _Pragma("unroll") for (int k = 0; k < 2; ++k) \
;         acc[ai][bj][m][n] = __builtin_amdgcn_mfma_f32_16x16x32_bf16(Bt[n][k], At[m][k], acc[ai][bj][m][n], 0, 0, 0); __builtin_amdgcn_s_setprio(0); } while (0)
; #define PG8_WAIT_V(n) asm volatile("s_waitcnt vmcnt(" #n ")" ::: "memory")
; #define PG8_WAIT_L(n) asm volatile("s_waitcnt lgkmcnt(" #n ")" ::: "memory")
; #define PG8_BAR __builtin_amdgcn_s_barrier()
; #define PG8_SCHED __builtin_amdgcn_sched_barrier(0)
; template <class Epi>
; __device__ __forceinline__ void gemm_phase(ldsp lds, const Gemm g, const StaticOrder& S, const Epi& E) {
;     ...
;             PG8_WAIT_V(10); PG8_BAR; PG8_MMA(1, 1, At, B1); PG8_BAR;
;             PG8_LDB(B0, 1, 0); PG8_SCHED; PG8_LDA(At, 1, 0); PG8_STAGE(PG8_SA(0, 1), a2 + hstep, voffA);
;             PG8_WAIT_L(8); PG8_WAIT_V(10); PG8_BAR; PG8_WAIT_L(0); PG8_MMA(0, 0, At, B0); PG8_BAR; PG8_SCHED;
;             PG8_LDB(B1, 1, 1); PG8_STAGE(PG8_SB(1, 0), b3, voffB);
;             PG8_WAIT_V(10); PG8_BAR; PG8_WAIT_L(0); PG8_MMA(0, 1, At, B1); PG8_BAR;
	s_nop 3
	s_setprio 1
	v_mfma_f32_16x16x32_bf16 v[28:31], v[192:195], v[144:147], v[28:31]
	v_mfma_f32_16x16x32_bf16 v[24:27], v[200:203], v[144:147], v[24:27]
	v_mfma_f32_16x16x32_bf16 v[20:23], v[192:195], v[152:155], v[20:23]
	v_mfma_f32_16x16x32_bf16 v[16:19], v[200:203], v[152:155], v[16:19]
	v_mfma_f32_16x16x32_bf16 v[12:15], v[192:195], v[160:163], v[12:15]
	v_mfma_f32_16x16x32_bf16 v[8:11], v[200:203], v[160:163], v[8:11]
	v_mfma_f32_16x16x32_bf16 v[4:7], v[192:195], v[168:171], v[4:7]
	v_mfma_f32_16x16x32_bf16 v[0:3], v[200:203], v[168:171], v[0:3]
	v_mfma_f32_16x16x32_bf16 v[28:31], v[196:199], v[148:151], v[28:31]
	v_mfma_f32_16x16x32_bf16 v[24:27], v[204:207], v[148:151], v[24:27]
	v_mfma_f32_16x16x32_bf16 v[20:23], v[196:199], v[156:159], v[20:23]
	v_mfma_f32_16x16x32_bf16 v[16:19], v[204:207], v[156:159], v[16:19]
	v_mfma_f32_16x16x32_bf16 v[12:15], v[196:199], v[164:167], v[12:15]
	v_mfma_f32_16x16x32_bf16 v[8:11], v[204:207], v[164:167], v[8:11]
	v_mfma_f32_16x16x32_bf16 v[4:7], v[196:199], v[172:175], v[4:7]
	s_barrier
	v_mfma_f32_16x16x32_bf16 v[0:3], v[204:207], v[172:175], v[0:3]
	s_setprio 0
	s_add_i32 s47, 0, 0x18000
	ds_read_b128 v[128:131], v247 offset:32768
	ds_read_b128 v[132:135], v247 offset:33792
	ds_read_b128 v[136:139], v247 offset:34816
	ds_read_b128 v[140:143], v247 offset:35840
	s_add_u32 s24, s24, 0x20000
	s_addc_u32 s25, s25, 0
	s_mov_b32 m0, s30
	ds_read_b128 v[144:147], v221 offset:32768
	ds_read_b128 v[148:151], v221 offset:33792
	ds_read_b128 v[152:155], v221 offset:34816
	ds_read_b128 v[156:159], v221 offset:35840
	ds_read_b128 v[160:163], v221 offset:36864
	ds_read_b128 v[164:167], v221 offset:37888
	ds_read_b128 v[168:171], v221 offset:38912
	ds_read_b128 v[172:175], v221 offset:39936
	global_load_lds_dwordx4 v176, s[24:25]
	s_mov_b32 m0, s31
	s_nop 0
	global_load_lds_dwordx4 v180, s[24:25]
	s_waitcnt lgkmcnt(8)
	s_waitcnt vmcnt(10)
	s_barrier
	s_waitcnt lgkmcnt(0)
	s_setprio 1
	s_waitcnt lgkmcnt(0)
	v_mfma_f32_16x16x32_bf16 v[124:127], v[128:131], v[144:147], v[124:127]
	v_mfma_f32_16x16x32_bf16 v[120:123], v[136:139], v[144:147], v[120:123]
	v_mfma_f32_16x16x32_bf16 v[116:119], v[128:131], v[152:155], v[116:119]
	v_mfma_f32_16x16x32_bf16 v[112:115], v[136:139], v[152:155], v[112:115]
	v_mfma_f32_16x16x32_bf16 v[108:111], v[128:131], v[160:163], v[108:111]
	v_mfma_f32_16x16x32_bf16 v[104:107], v[136:139], v[160:163], v[104:107]
	v_mfma_f32_16x16x32_bf16 v[100:103], v[128:131], v[168:171], v[100:103]
	v_mfma_f32_16x16x32_bf16 v[96:99], v[136:139], v[168:171], v[96:99]
	v_mfma_f32_16x16x32_bf16 v[124:127], v[132:135], v[148:151], v[124:127]
	v_mfma_f32_16x16x32_bf16 v[120:123], v[140:143], v[148:151], v[120:123]
	v_mfma_f32_16x16x32_bf16 v[116:119], v[132:135], v[156:159], v[116:119]
	v_mfma_f32_16x16x32_bf16 v[112:115], v[140:143], v[156:159], v[112:115]
	v_mfma_f32_16x16x32_bf16 v[108:111], v[132:135], v[164:167], v[108:111]
	v_mfma_f32_16x16x32_bf16 v[104:107], v[140:143], v[164:167], v[104:107]
	v_mfma_f32_16x16x32_bf16 v[100:103], v[132:135], v[172:175], v[100:103]
	s_barrier
	v_mfma_f32_16x16x32_bf16 v[96:99], v[140:143], v[172:175], v[96:99]
	s_setprio 0
	s_add_i32 s24, 0, 0x1c000
	s_add_i32 s25, s47, s28
	s_mov_b32 m0, s25
	ds_read_b128 v[192:195], v247 offset:49152
	ds_read_b128 v[196:199], v247 offset:50176
	ds_read_b128 v[200:203], v247 offset:51200
	ds_read_b128 v[204:207], v247 offset:52224
	global_load_lds_dwordx4 v178, s[98:99]
	s_add_i32 m0, s25, 0x2000
	s_nop 0
	global_load_lds_dwordx4 v182, s[98:99]
	s_waitcnt vmcnt(10)
	s_barrier
	s_waitcnt lgkmcnt(0)
	s_setprio 1
	s_waitcnt lgkmcnt(0)
	v_mfma_f32_16x16x32_bf16 v[60:63], v[192:195], v[144:147], v[60:63]
	v_mfma_f32_16x16x32_bf16 v[56:59], v[200:203], v[144:147], v[56:59]
	v_mfma_f32_16x16x32_bf16 v[52:55], v[192:195], v[152:155], v[52:55]
	v_mfma_f32_16x16x32_bf16 v[48:51], v[200:203], v[152:155], v[48:51]
	v_mfma_f32_16x16x32_bf16 v[44:47], v[192:195], v[160:163], v[44:47]
	v_mfma_f32_16x16x32_bf16 v[40:43], v[200:203], v[160:163], v[40:43]
	v_mfma_f32_16x16x32_bf16 v[36:39], v[192:195], v[168:171], v[36:39]
	v_mfma_f32_16x16x32_bf16 v[32:35], v[200:203], v[168:171], v[32:35]
	v_mfma_f32_16x16x32_bf16 v[60:63], v[196:199], v[148:151], v[60:63]
	v_mfma_f32_16x16x32_bf16 v[56:59], v[204:207], v[148:151], v[56:59]
	v_mfma_f32_16x16x32_bf16 v[52:55], v[196:199], v[156:159], v[52:55]
	v_mfma_f32_16x16x32_bf16 v[48:51], v[204:207], v[156:159], v[48:51]
	v_mfma_f32_16x16x32_bf16 v[44:47], v[196:199], v[164:167], v[44:47]
	v_mfma_f32_16x16x32_bf16 v[40:43], v[204:207], v[164:167], v[40:43]
	v_mfma_f32_16x16x32_bf16 v[36:39], v[196:199], v[172:175], v[36:39]
	s_barrier
	v_mfma_f32_16x16x32_bf16 v[32:35], v[204:207], v[172:175], v[32:35]
	s_setprio 0
	s_mov_b32 m0, s34
	ds_read_b128 v[144:147], v221 offset:49152
	ds_read_b128 v[148:151], v221 offset:50176
	ds_read_b128 v[152:155], v221 offset:51200
	ds_read_b128 v[156:159], v221 offset:52224
	ds_read_b128 v[160:163], v221 offset:53248
	ds_read_b128 v[164:167], v221 offset:54272
	ds_read_b128 v[168:171], v221 offset:55296
	ds_read_b128 v[172:175], v221 offset:56320
	global_load_lds_dwordx4 v176, s[100:101]
	s_mov_b32 m0, s35
	s_nop 0
	global_load_lds_dwordx4 v180, s[100:101]
	s_waitcnt vmcnt(10)
	s_barrier
; #define PG8_STAGE(bufoff, gbase, voff) do { _Pragma("unroll") for (int _i = 0; _i < 2; ++_i) \
;         __builtin_amdgcn_global_load_lds((const unsigned*)((const char*)(gbase) + (voff)[_i]), (LAS unsigned*)(lds + (bufoff) + ldsw + _i * 8192), 16, 0, 0); } while (0)
; #define PG8_LDA(dst, b, h) do { _Pragma("unroll") for (int m = 0; m < 4; ++m) _Pragma("unroll") for (int k = 0; k < 2; ++k) dst[m][k] = *(const LAS bf16x8*)(lds + PG8_SA(b, h) + aoff + m * 2048 + k * 1024); } while (0)
; #define PG8_MMA(ai, bj, At, Bt) do { __builtin_amdgcn_s_setprio(1); _Pragma("unroll") for (int m = 0; m < 4; ++m) _Pragma("unroll") for (int n = 0; n < 2; ++n) _Pragma("unroll") for (int k = 0; k < 2; ++k) \
;         acc[ai][bj][m][n] = __builtin_amdgcn_mfma_f32_16x16x32_bf16(Bt[n][k], At[m][k], acc[ai][bj][m][n], 0, 0, 0); __builtin_amdgcn_s_setprio(0); } while (0)
; #define PG8_WAIT_V(n) asm volatile("s_waitcnt vmcnt(" #n ")" ::: "memory")
; #define PG8_WAIT_L(n) asm volatile("s_waitcnt lgkmcnt(" #n ")" ::: "memory")
; #define PG8_BAR __builtin_amdgcn_s_barrier()
; #define PG8_SCHED __builtin_amdgcn_sched_barrier(0)
; template <class Epi>
; __device__ __forceinline__ void gemm_phase(ldsp lds, const Gemm g, const StaticOrder& S, const Epi& E) {
;     ...
;             PG8_WAIT_V(10); PG8_BAR; PG8_WAIT_L(0); PG8_MMA(0, 1, At, B1); PG8_BAR;
;             PG8_LDA(At, 1, 1); PG8_STAGE(PG8_SA(1, 0), a3, voffA);
;             PG8_WAIT_V(10); PG8_BAR; PG8_WAIT_L(0); PG8_MMA(1, 0, At, B0); PG8_BAR; PG8_SCHED;
;             PG8_STAGE(PG8_SB(1, 1), b3 + hstep, voffB);
;             PG8_WAIT_V(10); PG8_BAR; PG8_MMA(1, 1, At, B1); PG8_BAR;
;     __device__ __forceinline__ void operator()(EPI_ARGS) const {
;     ...
;         for (int bj = 0; bj < 2; ++bj) { const f32x4 b0 = *(const f32x4*)(bias + col0 + bj * 128), b1 = *(const f32x4*)(bias + col0 + bj * 128 + 4);
;             u32x4 hw[2][4];
; #pragma unroll
;             for (int ai = 0; ai < 2; ++ai)
; #pragma unroll
;                 for (int m = 0; m < 4; ++m) hw[ai][m] = *(const u32x4*)(H + (size_t)(row0 + ai * 128 + m * 16) * 512 + col0 + bj * 128);
	s_waitcnt lgkmcnt(0)
	s_setprio 1
	s_waitcnt lgkmcnt(0)
	v_mfma_f32_16x16x32_bf16 v[92:95], v[128:131], v[144:147], v[92:95]
	v_mfma_f32_16x16x32_bf16 v[88:91], v[136:139], v[144:147], v[88:91]
	v_mfma_f32_16x16x32_bf16 v[84:87], v[128:131], v[152:155], v[84:87]
	v_mfma_f32_16x16x32_bf16 v[80:83], v[136:139], v[152:155], v[80:83]
	v_mfma_f32_16x16x32_bf16 v[76:79], v[128:131], v[160:163], v[76:79]
	v_mfma_f32_16x16x32_bf16 v[72:75], v[136:139], v[160:163], v[72:75]
	v_mfma_f32_16x16x32_bf16 v[68:71], v[128:131], v[168:171], v[68:71]
	v_mfma_f32_16x16x32_bf16 v[64:67], v[136:139], v[168:171], v[64:67]
	v_mfma_f32_16x16x32_bf16 v[92:95], v[132:135], v[148:151], v[92:95]
	v_mfma_f32_16x16x32_bf16 v[88:91], v[140:143], v[148:151], v[88:91]
	v_mfma_f32_16x16x32_bf16 v[84:87], v[132:135], v[156:159], v[84:87]
	v_mfma_f32_16x16x32_bf16 v[80:83], v[140:143], v[156:159], v[80:83]
	v_mfma_f32_16x16x32_bf16 v[76:79], v[132:135], v[164:167], v[76:79]
	v_mfma_f32_16x16x32_bf16 v[72:75], v[140:143], v[164:167], v[72:75]
	v_mfma_f32_16x16x32_bf16 v[68:71], v[132:135], v[172:175], v[68:71]
	s_barrier
	v_mfma_f32_16x16x32_bf16 v[64:67], v[140:143], v[172:175], v[64:67]
	s_setprio 0
	s_add_u32 s22, s22, 0x20080
	s_addc_u32 s23, s23, 0
	s_add_i32 s24, s24, s28
	s_mov_b32 m0, s24
	s_nop 0
	global_load_lds_dwordx4 v178, s[22:23]
	s_add_i32 m0, s24, 0x2000
	s_nop 0
	global_load_lds_dwordx4 v182, s[22:23]
	s_waitcnt vmcnt(10)
	s_barrier
	s_nop 3
	s_setprio 1
	v_mfma_f32_16x16x32_bf16 v[28:31], v[192:195], v[144:147], v[28:31]
	v_mfma_f32_16x16x32_bf16 v[24:27], v[200:203], v[144:147], v[24:27]
	v_mfma_f32_16x16x32_bf16 v[20:23], v[192:195], v[152:155], v[20:23]
	v_mfma_f32_16x16x32_bf16 v[16:19], v[200:203], v[152:155], v[16:19]
	v_mfma_f32_16x16x32_bf16 v[12:15], v[192:195], v[160:163], v[12:15]
	v_mfma_f32_16x16x32_bf16 v[8:11], v[200:203], v[160:163], v[8:11]
	v_mfma_f32_16x16x32_bf16 v[4:7], v[192:195], v[168:171], v[4:7]
	v_mfma_f32_16x16x32_bf16 v[0:3], v[200:203], v[168:171], v[0:3]
	v_mfma_f32_16x16x32_bf16 v[28:31], v[196:199], v[148:151], v[28:31]
	v_mfma_f32_16x16x32_bf16 v[24:27], v[204:207], v[148:151], v[24:27]
	v_mfma_f32_16x16x32_bf16 v[20:23], v[196:199], v[156:159], v[20:23]
	v_mfma_f32_16x16x32_bf16 v[16:19], v[204:207], v[156:159], v[16:19]
	v_mfma_f32_16x16x32_bf16 v[12:15], v[196:199], v[164:167], v[12:15]
	v_mfma_f32_16x16x32_bf16 v[8:11], v[204:207], v[164:167], v[8:11]
	v_mfma_f32_16x16x32_bf16 v[4:7], v[196:199], v[172:175], v[4:7]
	s_barrier
	v_mfma_f32_16x16x32_bf16 v[0:3], v[204:207], v[172:175], v[0:3]
	s_setprio 0
	s_add_i32 s46, s46, 2
	s_add_u32 s20, s20, 0x100
	s_addc_u32 s21, s21, 0
	s_add_u32 s44, s44, 0x100
	s_addc_u32 s45, s45, 0
	s_cmp_gt_u32 s46, 5
	s_cbranch_scc0 .LBB0_574
	v_lshl_or_b32 v136, s41, 8, v218
	v_readlane_b32 s72, v246, 6
	v_ashrrev_i32_e32 v137, 31, v136
	v_readlane_b32 s86, v246, 20
	v_readlane_b32 s87, v246, 21
	v_lshl_add_u32 v140, s18, 8, v216
	v_ashrrev_i32_e32 v141, 31, v140
	v_lshl_add_u64 v[192:193], v[136:137], 2, s[86:87]
	v_lshlrev_b64 v[194:195], 1, v[136:137]
	global_load_dwordx4 v[132:135], v[192:193], off
	global_load_dwordx4 v[128:131], v[192:193], off offset:16
	v_lshlrev_b64 v[136:137], 10, v[140:141]
	v_lshl_add_u64 v[150:151], s[4:5], 0, v[194:195]
	v_lshl_add_u64 v[142:143], v[150:151], 0, v[136:137]
	global_load_dwordx4 v[136:139], v[142:143], off
	v_or_b32_e32 v210, 16, v140
	v_or_b32_e32 v206, 48, v140
	v_add_u32_e32 v204, 0x80, v140
	v_add_u32_e32 v198, 0xb0, v140
	v_ashrrev_i32_e32 v211, 31, v210
	v_ashrrev_i32_e32 v207, 31, v206
	v_ashrrev_i32_e32 v205, 31, v204
	v_ashrrev_i32_e32 v199, 31, v198
	v_lshlrev_b64 v[144:145], 10, v[210:211]
	v_lshlrev_b64 v[152:153], 10, v[206:207]
	v_lshlrev_b64 v[154:155], 10, v[204:205]
	v_lshlrev_b64 v[160:161], 10, v[198:199]
	v_lshl_add_u64 v[148:149], v[150:151], 0, v[144:145]
	v_lshl_add_u64 v[144:145], v[150:151], 0, v[152:153]
	v_lshl_add_u64 v[168:169], v[150:151], 0, v[154:155]
	v_lshl_add_u64 v[212:213], v[150:151], 0, v[160:161]
	global_load_dwordx4 v[152:155], v[148:149], off
	global_load_dwordx4 v[160:163], v[142:143], off offset:256
	v_or_b32_e32 v208, 32, v140
	v_add_u32_e32 v202, 0x90, v140
	v_add_u32_e32 v200, 0xa0, v140
	v_ashrrev_i32_e32 v209, 31, v208
	v_ashrrev_i32_e32 v203, 31, v202
	v_ashrrev_i32_e32 v201, 31, v200
	v_lshlrev_b64 v[146:147], 10, v[208:209]
	v_lshlrev_b64 v[156:157], 10, v[202:203]
	v_lshlrev_b64 v[158:159], 10, v[200:201]
	v_lshl_add_u64 v[146:147], v[150:151], 0, v[146:147]
	v_lshl_add_u64 v[166:167], v[150:151], 0, v[156:157]
	v_lshl_add_u64 v[164:165], v[150:151], 0, v[158:159]
	v_mov_b64_e32 v[196:197], s[6:7]
	s_and_b64 vcc, exec, s[2:3]
	s_mov_b32 s18, s12
	s_mov_b32 s41, s10
	s_mov_b64 s[22:23], s[16:17]
	v_readlane_b32 s73, v246, 7
	v_readlane_b32 s74, v246, 8
	v_readlane_b32 s75, v246, 9
	v_readlane_b32 s76, v246, 10
	v_readlane_b32 s77, v246, 11
	v_readlane_b32 s78, v246, 12
	v_readlane_b32 s79, v246, 13
	v_readlane_b32 s80, v246, 14
	v_readlane_b32 s81, v246, 15
	v_readlane_b32 s82, v246, 16
	v_readlane_b32 s83, v246, 17
	v_readlane_b32 s84, v246, 18
	v_readlane_b32 s85, v246, 19
	s_waitcnt vmcnt(0)
; __device__ __forceinline__ float sigm(float x) { return __builtin_amdgcn_rcpf(1.0f + __builtin_amdgcn_exp2f(-1.4426950408889634f * x)); }
;     __device__ __forceinline__ void operator()(EPI_ARGS) const {
;     ...
;             for (int ai = 0; ai < 2; ++ai)
; #pragma unroll
;                 for (int m = 0; m < 4; ++m) { const size_t off = (size_t)(row0 + ai * 128 + m * 16) * 512 + col0 + bj * 128;
;                     f32x4 h0, h1; unpack8(hw[ai][m], h0, h1);
;                     f32x4 v0 = acc[ai][bj][m][0] + b0, v1 = acc[ai][bj][m][1] + b1;
; #pragma unroll
;                     for (int j = 0; j < 4; ++j) { v0[j] = h0[j] * sigm(v0[j]); v1[j] = h1[j] * sigm(v1[j]); }
;                     *(u32x4*)(O + (size_t)(row0 + ai * 128 + m * 16) * KAB + 1024 + col0 + bj * 128) = pack8(v0, v1); } }
	v_pk_add_f32 v[124:125], v[124:125], v[132:133]
	v_pk_add_f32 v[126:127], v[126:127], v[134:135]
	v_pk_add_f32 v[122:123], v[122:123], v[130:131]
	v_pk_add_f32 v[120:121], v[120:121], v[128:129]
	v_mul_f32_e32 v124, 0xbfb8aa3b, v124
	v_mul_f32_e32 v125, 0xbfb8aa3b, v125
	v_mul_f32_e32 v120, 0xbfb8aa3b, v120
	v_mul_f32_e32 v141, 0xbfb8aa3b, v121
	v_mul_f32_e32 v126, 0xbfb8aa3b, v126
	v_mul_f32_e32 v142, 0xbfb8aa3b, v122
	v_mul_f32_e32 v127, 0xbfb8aa3b, v127
	v_mul_f32_e32 v143, 0xbfb8aa3b, v123
	v_exp_f32_e32 v150, v124
	v_exp_f32_e32 v156, v125
	v_exp_f32_e32 v151, v120
	v_lshlrev_b32_e32 v120, 16, v136
	v_and_b32_e32 v121, 0xffff0000, v136
	v_exp_f32_e32 v136, v141
	v_lshlrev_b32_e32 v122, 16, v138
	v_and_b32_e32 v123, 0xffff0000, v138
	v_exp_f32_e32 v138, v126
	v_exp_f32_e32 v141, v142
	v_exp_f32_e32 v142, v127
	v_lshlrev_b32_e32 v124, 16, v137
	v_and_b32_e32 v125, 0xffff0000, v137
	v_exp_f32_e32 v137, v143
	v_lshlrev_b32_e32 v126, 16, v139
	v_and_b32_e32 v127, 0xffff0000, v139
	v_add_f32_e32 v139, 1.0, v150
	v_add_f32_e32 v150, 1.0, v156
	v_add_f32_e32 v143, 1.0, v151
	v_add_f32_e32 v151, 1.0, v136
	v_add_f32_e32 v156, 1.0, v138
	v_add_f32_e32 v141, 1.0, v141
	v_add_f32_e32 v157, 1.0, v142
	v_add_f32_e32 v158, 1.0, v137
	v_rcp_f32_e32 v136, v139
	v_rcp_f32_e32 v137, v150
	v_rcp_f32_e32 v138, v143
	v_rcp_f32_e32 v139, v151
	v_rcp_f32_e32 v142, v156
	v_rcp_f32_e32 v150, v141
	v_rcp_f32_e32 v143, v157
	v_rcp_f32_e32 v151, v158
	v_pk_mul_f32 v[120:121], v[136:137], v[120:121]
	v_pk_mul_f32 v[122:123], v[138:139], v[122:123]
	v_pk_mul_f32 v[124:125], v[142:143], v[124:125]
	v_pk_mul_f32 v[126:127], v[150:151], v[126:127]
	v_cvt_pk_bf16_f32 v224, v120, v121
	v_mad_i64_i32 v[120:121], s[20:21], v140, s40, v[196:197]
	v_cvt_pk_bf16_f32 v225, v124, v125
	v_cvt_pk_bf16_f32 v226, v122, v123
	v_cvt_pk_bf16_f32 v227, v126, v127
	v_lshl_add_u64 v[214:215], v[120:121], 0, v[194:195]
	global_load_dwordx4 v[156:159], v[148:149], off offset:256
	global_load_dwordx4 v[228:231], v[146:147], off
	s_nop 0
	global_load_dwordx4 v[148:151], v[146:147], off offset:256
	global_load_dwordx4 v[232:235], v[144:145], off
	s_nop 0
	global_load_dwordx4 v[144:147], v[144:145], off offset:256
	s_nop 0
	global_load_dwordx4 v[236:239], v[168:169], off
	global_load_dwordx4 v[140:143], v[168:169], off offset:256
	global_load_dwordx4 v[172:175], v[166:167], off
	global_load_dwordx4 v[136:139], v[166:167], off offset:256
	s_nop 0
	global_load_dwordx4 v[168:171], v[164:165], off
	global_load_dwordx4 v[124:127], v[164:165], off offset:256
	s_nop 0
	global_load_dwordx4 v[164:167], v[212:213], off
	global_load_dwordx4 v[120:123], v[212:213], off offset:256
	v_pk_add_f32 v[116:117], v[116:117], v[132:133]
	v_pk_add_f32 v[114:115], v[114:115], v[130:131]
	v_mul_f32_e32 v116, 0xbfb8aa3b, v116
	v_mul_f32_e32 v117, 0xbfb8aa3b, v117
	v_exp_f32_e32 v116, v116
	v_exp_f32_e32 v117, v117
	v_pk_add_f32 v[118:119], v[118:119], v[134:135]
	v_pk_add_f32 v[112:113], v[112:113], v[128:129]
	v_add_f32_e32 v116, 1.0, v116
	v_add_f32_e32 v117, 1.0, v117
	v_rcp_f32_e32 v116, v116
	v_rcp_f32_e32 v117, v117
	v_mul_f32_e32 v114, 0xbfb8aa3b, v114
	v_mul_f32_e32 v112, 0xbfb8aa3b, v112
	v_mul_f32_e32 v113, 0xbfb8aa3b, v113
	v_lshlrev_b32_e32 v212, 16, v152
	v_and_b32_e32 v213, 0xffff0000, v152
	v_mul_f32_e32 v118, 0xbfb8aa3b, v118
	v_exp_f32_e32 v152, v114
	v_mul_f32_e32 v114, 0xbfb8aa3b, v119
	v_exp_f32_e32 v112, v112
	v_exp_f32_e32 v113, v113
	v_exp_f32_e32 v118, v118
	v_exp_f32_e32 v119, v114
	v_mul_f32_e32 v115, 0xbfb8aa3b, v115
	v_pk_mul_f32 v[116:117], v[116:117], v[212:213]
	v_lshlrev_b32_e32 v212, 16, v154
	v_and_b32_e32 v213, 0xffff0000, v154
	v_exp_f32_e32 v154, v115
	v_pk_add_f32 v[108:109], v[108:109], v[132:133]
	v_pk_add_f32 v[104:105], v[104:105], v[128:129]
	v_mul_f32_e32 v108, 0xbfb8aa3b, v108
	v_mul_f32_e32 v109, 0xbfb8aa3b, v109
	v_add_f32_e32 v112, 1.0, v112
	v_add_f32_e32 v113, 1.0, v113
	v_add_f32_e32 v118, 1.0, v118
	v_add_f32_e32 v119, 1.0, v119
	v_exp_f32_e32 v108, v108
	v_mul_f32_e32 v104, 0xbfb8aa3b, v104
	v_exp_f32_e32 v109, v109
	v_mul_f32_e32 v105, 0xbfb8aa3b, v105
	v_rcp_f32_e32 v112, v112
	v_rcp_f32_e32 v113, v113
	v_rcp_f32_e32 v114, v118
	v_add_f32_e32 v118, 1.0, v152
	v_rcp_f32_e32 v115, v119
	v_add_f32_e32 v119, 1.0, v154
	v_exp_f32_e32 v104, v104
	v_exp_f32_e32 v105, v105
	v_rcp_f32_e32 v118, v118
	v_rcp_f32_e32 v119, v119
	v_lshlrev_b32_e32 v152, 16, v153
	v_and_b32_e32 v153, 0xffff0000, v153
	v_add_f32_e32 v108, 1.0, v108
	v_add_f32_e32 v109, 1.0, v109
	v_pk_mul_f32 v[112:113], v[112:113], v[212:213]
	v_pk_mul_f32 v[152:153], v[114:115], v[152:153]
	v_lshlrev_b32_e32 v114, 16, v155
	v_and_b32_e32 v115, 0xffff0000, v155
	v_rcp_f32_e32 v108, v108
	v_add_f32_e32 v104, 1.0, v104
	v_rcp_f32_e32 v109, v109
	v_add_f32_e32 v105, 1.0, v105
	v_pk_mul_f32 v[118:119], v[118:119], v[114:115]
	v_cvt_pk_bf16_f32 v114, v116, v117
	v_cvt_pk_bf16_f32 v116, v112, v113
	v_mad_i64_i32 v[112:113], s[20:21], v210, s40, v[196:197]
	v_rcp_f32_e32 v104, v104
	v_rcp_f32_e32 v105, v105
	v_cvt_pk_bf16_f32 v115, v152, v153
	v_cvt_pk_bf16_f32 v117, v118, v119
	v_lshl_add_u64 v[112:113], v[112:113], 0, v[194:195]
	global_store_dwordx4 v[112:113], v[114:117], off offset:2048
	v_pk_add_f32 v[106:107], v[106:107], v[130:131]
	v_pk_add_f32 v[110:111], v[110:111], v[134:135]
	s_waitcnt vmcnt(0)
; __device__ __forceinline__ float sigm(float x) { return __builtin_amdgcn_rcpf(1.0f + __builtin_amdgcn_exp2f(-1.4426950408889634f * x)); }
;     __device__ __forceinline__ void operator()(EPI_ARGS) const {
;     ...
;             for (int ai = 0; ai < 2; ++ai)
; #pragma unroll
;                 for (int m = 0; m < 4; ++m) { const size_t off = (size_t)(row0 + ai * 128 + m * 16) * 512 + col0 + bj * 128;
;                     f32x4 h0, h1; unpack8(hw[ai][m], h0, h1);
;                     f32x4 v0 = acc[ai][bj][m][0] + b0, v1 = acc[ai][bj][m][1] + b1;
; #pragma unroll
;                     for (int j = 0; j < 4; ++j) { v0[j] = h0[j] * sigm(v0[j]); v1[j] = h1[j] * sigm(v1[j]); }
;                     *(u32x4*)(O + (size_t)(row0 + ai * 128 + m * 16) * KAB + 1024 + col0 + bj * 128) = pack8(v0, v1); } }
	v_lshlrev_b32_e32 v114, 16, v228
	v_and_b32_e32 v115, 0xffff0000, v228
	v_pk_mul_f32 v[108:109], v[108:109], v[114:115]
	v_lshlrev_b32_e32 v114, 16, v230
	v_and_b32_e32 v115, 0xffff0000, v230
	v_mul_f32_e32 v106, 0xbfb8aa3b, v106
	v_mul_f32_e32 v110, 0xbfb8aa3b, v110
	v_pk_mul_f32 v[104:105], v[104:105], v[114:115]
	v_exp_f32_e32 v114, v106
	v_mul_f32_e32 v106, 0xbfb8aa3b, v111
	v_exp_f32_e32 v110, v110
	v_exp_f32_e32 v111, v106
	v_mul_f32_e32 v107, 0xbfb8aa3b, v107
	v_exp_f32_e32 v116, v107
	v_pk_add_f32 v[100:101], v[100:101], v[132:133]
	v_pk_add_f32 v[96:97], v[96:97], v[128:129]
	v_mul_f32_e32 v100, 0xbfb8aa3b, v100
	v_mul_f32_e32 v101, 0xbfb8aa3b, v101
	v_add_f32_e32 v110, 1.0, v110
	v_add_f32_e32 v111, 1.0, v111
	v_exp_f32_e32 v100, v100
	v_mul_f32_e32 v96, 0xbfb8aa3b, v96
	v_exp_f32_e32 v101, v101
	v_mul_f32_e32 v97, 0xbfb8aa3b, v97
	v_rcp_f32_e32 v106, v110
	v_add_f32_e32 v110, 1.0, v114
	v_rcp_f32_e32 v107, v111
	v_add_f32_e32 v111, 1.0, v116
	v_exp_f32_e32 v96, v96
	v_exp_f32_e32 v97, v97
	v_rcp_f32_e32 v110, v110
	v_rcp_f32_e32 v111, v111
	v_lshlrev_b32_e32 v114, 16, v229
	v_and_b32_e32 v115, 0xffff0000, v229
	v_add_f32_e32 v100, 1.0, v100
	v_add_f32_e32 v101, 1.0, v101
	v_pk_mul_f32 v[114:115], v[106:107], v[114:115]
	v_lshlrev_b32_e32 v106, 16, v231
	v_and_b32_e32 v107, 0xffff0000, v231
	v_rcp_f32_e32 v100, v100
	v_add_f32_e32 v96, 1.0, v96
	v_rcp_f32_e32 v101, v101
	v_add_f32_e32 v97, 1.0, v97
	v_pk_mul_f32 v[110:111], v[110:111], v[106:107]
	v_cvt_pk_bf16_f32 v106, v108, v109
	v_cvt_pk_bf16_f32 v108, v104, v105
	v_mad_i64_i32 v[104:105], s[20:21], v208, s40, v[196:197]
	v_rcp_f32_e32 v96, v96
	v_rcp_f32_e32 v97, v97
	v_cvt_pk_bf16_f32 v107, v114, v115
	v_cvt_pk_bf16_f32 v109, v110, v111
	v_lshl_add_u64 v[104:105], v[104:105], 0, v[194:195]
	global_store_dwordx4 v[104:105], v[106:109], off offset:2048
	v_pk_add_f32 v[98:99], v[98:99], v[130:131]
	v_pk_add_f32 v[102:103], v[102:103], v[134:135]
	v_lshlrev_b32_e32 v106, 16, v232
	v_and_b32_e32 v107, 0xffff0000, v232
	v_pk_mul_f32 v[100:101], v[100:101], v[106:107]
	v_lshlrev_b32_e32 v106, 16, v234
	v_and_b32_e32 v107, 0xffff0000, v234
	v_mul_f32_e32 v98, 0xbfb8aa3b, v98
	v_mul_f32_e32 v102, 0xbfb8aa3b, v102
	v_pk_mul_f32 v[96:97], v[96:97], v[106:107]
	v_exp_f32_e32 v106, v98
	v_mul_f32_e32 v98, 0xbfb8aa3b, v103
	v_exp_f32_e32 v102, v102
	v_exp_f32_e32 v103, v98
	v_mul_f32_e32 v99, 0xbfb8aa3b, v99
	v_exp_f32_e32 v108, v99
	v_pk_add_f32 v[92:93], v[92:93], v[132:133]
	v_pk_add_f32 v[88:89], v[88:89], v[128:129]
	v_mul_f32_e32 v92, 0xbfb8aa3b, v92
	v_mul_f32_e32 v93, 0xbfb8aa3b, v93
	v_add_f32_e32 v102, 1.0, v102
	v_add_f32_e32 v103, 1.0, v103
	v_exp_f32_e32 v92, v92
	v_mul_f32_e32 v88, 0xbfb8aa3b, v88
	v_exp_f32_e32 v93, v93
	v_mul_f32_e32 v89, 0xbfb8aa3b, v89
	v_rcp_f32_e32 v98, v102
	v_add_f32_e32 v102, 1.0, v106
	v_rcp_f32_e32 v99, v103
	v_add_f32_e32 v103, 1.0, v108
	v_exp_f32_e32 v88, v88
	v_exp_f32_e32 v89, v89
	v_rcp_f32_e32 v102, v102
	v_rcp_f32_e32 v103, v103
	v_lshlrev_b32_e32 v106, 16, v233
	v_and_b32_e32 v107, 0xffff0000, v233
	v_add_f32_e32 v92, 1.0, v92
	v_add_f32_e32 v93, 1.0, v93
	v_pk_mul_f32 v[106:107], v[98:99], v[106:107]
	v_lshlrev_b32_e32 v98, 16, v235
	v_and_b32_e32 v99, 0xffff0000, v235
	v_rcp_f32_e32 v92, v92
	v_add_f32_e32 v88, 1.0, v88
	v_rcp_f32_e32 v93, v93
	v_add_f32_e32 v89, 1.0, v89
	v_pk_mul_f32 v[102:103], v[102:103], v[98:99]
	v_cvt_pk_bf16_f32 v98, v100, v101
	v_cvt_pk_bf16_f32 v100, v96, v97
	v_mad_i64_i32 v[96:97], s[20:21], v206, s40, v[196:197]
	v_rcp_f32_e32 v88, v88
	v_rcp_f32_e32 v89, v89
	v_cvt_pk_bf16_f32 v99, v106, v107
	v_cvt_pk_bf16_f32 v101, v102, v103
	v_lshl_add_u64 v[96:97], v[96:97], 0, v[194:195]
	global_store_dwordx4 v[96:97], v[98:101], off offset:2048
	v_pk_add_f32 v[90:91], v[90:91], v[130:131]
	v_pk_add_f32 v[94:95], v[94:95], v[134:135]
	v_lshlrev_b32_e32 v98, 16, v236
	v_and_b32_e32 v99, 0xffff0000, v236
	v_pk_mul_f32 v[92:93], v[92:93], v[98:99]
	v_lshlrev_b32_e32 v98, 16, v238
	v_and_b32_e32 v99, 0xffff0000, v238
	v_mul_f32_e32 v90, 0xbfb8aa3b, v90
	v_mul_f32_e32 v94, 0xbfb8aa3b, v94
	v_pk_mul_f32 v[88:89], v[88:89], v[98:99]
	v_exp_f32_e32 v98, v90
	v_mul_f32_e32 v90, 0xbfb8aa3b, v95
	v_exp_f32_e32 v94, v94
	v_exp_f32_e32 v95, v90
	v_mul_f32_e32 v91, 0xbfb8aa3b, v91
	v_exp_f32_e32 v100, v91
	v_pk_add_f32 v[84:85], v[84:85], v[132:133]
	v_pk_add_f32 v[80:81], v[80:81], v[128:129]
	v_mul_f32_e32 v84, 0xbfb8aa3b, v84
	v_mul_f32_e32 v85, 0xbfb8aa3b, v85
	v_add_f32_e32 v94, 1.0, v94
	v_add_f32_e32 v95, 1.0, v95
	v_exp_f32_e32 v84, v84
	v_mul_f32_e32 v80, 0xbfb8aa3b, v80
	v_exp_f32_e32 v85, v85
	v_mul_f32_e32 v81, 0xbfb8aa3b, v81
	v_rcp_f32_e32 v90, v94
	v_add_f32_e32 v94, 1.0, v98
	v_rcp_f32_e32 v91, v95
	v_add_f32_e32 v95, 1.0, v100
	v_exp_f32_e32 v80, v80
	v_exp_f32_e32 v81, v81
	v_rcp_f32_e32 v94, v94
	v_rcp_f32_e32 v95, v95
	v_lshlrev_b32_e32 v98, 16, v237
	v_and_b32_e32 v99, 0xffff0000, v237
	v_add_f32_e32 v84, 1.0, v84
	v_add_f32_e32 v85, 1.0, v85
	v_pk_mul_f32 v[98:99], v[90:91], v[98:99]
	v_lshlrev_b32_e32 v90, 16, v239
	v_and_b32_e32 v91, 0xffff0000, v239
	v_rcp_f32_e32 v84, v84
	v_add_f32_e32 v80, 1.0, v80
	v_rcp_f32_e32 v85, v85
	v_add_f32_e32 v81, 1.0, v81
	v_pk_mul_f32 v[94:95], v[94:95], v[90:91]
	v_cvt_pk_bf16_f32 v90, v92, v93
	v_cvt_pk_bf16_f32 v92, v88, v89
	v_mad_i64_i32 v[88:89], s[20:21], v204, s40, v[196:197]
	v_rcp_f32_e32 v80, v80
	v_rcp_f32_e32 v81, v81
	v_cvt_pk_bf16_f32 v91, v98, v99
	v_cvt_pk_bf16_f32 v93, v94, v95
	v_lshl_add_u64 v[88:89], v[88:89], 0, v[194:195]
	global_store_dwordx4 v[88:89], v[90:93], off offset:2048
	v_pk_add_f32 v[82:83], v[82:83], v[130:131]
; __device__ __forceinline__ float sigm(float x) { return __builtin_amdgcn_rcpf(1.0f + __builtin_amdgcn_exp2f(-1.4426950408889634f * x)); }
;     __device__ __forceinline__ void operator()(EPI_ARGS) const {
;     ...
;         for (int bj = 0; bj < 2; ++bj) { const f32x4 b0 = *(const f32x4*)(bias + col0 + bj * 128), b1 = *(const f32x4*)(bias + col0 + bj * 128 + 4);
;             u32x4 hw[2][4];
; #pragma unroll
;             for (int ai = 0; ai < 2; ++ai)
; #pragma unroll
;                 for (int m = 0; m < 4; ++m) hw[ai][m] = *(const u32x4*)(H + (size_t)(row0 + ai * 128 + m * 16) * 512 + col0 + bj * 128);
; #pragma unroll
;             for (int ai = 0; ai < 2; ++ai)
; #pragma unroll
;                 for (int m = 0; m < 4; ++m) { const size_t off = (size_t)(row0 + ai * 128 + m * 16) * 512 + col0 + bj * 128;
;                     f32x4 h0, h1; unpack8(hw[ai][m], h0, h1);
;                     f32x4 v0 = acc[ai][bj][m][0] + b0, v1 = acc[ai][bj][m][1] + b1;
; #pragma unroll
;                     for (int j = 0; j < 4; ++j) { v0[j] = h0[j] * sigm(v0[j]); v1[j] = h1[j] * sigm(v1[j]); }
;                     *(u32x4*)(O + (size_t)(row0 + ai * 128 + m * 16) * KAB + 1024 + col0 + bj * 128) = pack8(v0, v1); } }
	v_pk_add_f32 v[86:87], v[86:87], v[134:135]
	v_lshlrev_b32_e32 v90, 16, v172
	v_and_b32_e32 v91, 0xffff0000, v172
	v_pk_mul_f32 v[84:85], v[84:85], v[90:91]
	v_lshlrev_b32_e32 v90, 16, v174
	v_and_b32_e32 v91, 0xffff0000, v174
	v_mul_f32_e32 v82, 0xbfb8aa3b, v82
	v_mul_f32_e32 v86, 0xbfb8aa3b, v86
	v_pk_mul_f32 v[80:81], v[80:81], v[90:91]
	v_exp_f32_e32 v90, v82
	v_mul_f32_e32 v82, 0xbfb8aa3b, v87
	v_exp_f32_e32 v86, v86
	v_exp_f32_e32 v87, v82
	v_mul_f32_e32 v83, 0xbfb8aa3b, v83
	v_exp_f32_e32 v92, v83
	v_pk_add_f32 v[76:77], v[76:77], v[132:133]
	v_pk_add_f32 v[72:73], v[72:73], v[128:129]
	v_mul_f32_e32 v76, 0xbfb8aa3b, v76
	v_mul_f32_e32 v77, 0xbfb8aa3b, v77
	v_add_f32_e32 v86, 1.0, v86
	v_add_f32_e32 v87, 1.0, v87
	v_exp_f32_e32 v76, v76
	v_mul_f32_e32 v72, 0xbfb8aa3b, v72
	v_exp_f32_e32 v77, v77
	v_mul_f32_e32 v73, 0xbfb8aa3b, v73
	v_rcp_f32_e32 v82, v86
	v_add_f32_e32 v86, 1.0, v90
	v_rcp_f32_e32 v83, v87
	v_add_f32_e32 v87, 1.0, v92
	v_exp_f32_e32 v72, v72
	v_exp_f32_e32 v73, v73
	v_rcp_f32_e32 v86, v86
	v_rcp_f32_e32 v87, v87
	v_lshlrev_b32_e32 v90, 16, v173
	v_and_b32_e32 v91, 0xffff0000, v173
	v_add_f32_e32 v76, 1.0, v76
	v_add_f32_e32 v77, 1.0, v77
	v_pk_mul_f32 v[90:91], v[82:83], v[90:91]
	v_lshlrev_b32_e32 v82, 16, v175
	v_and_b32_e32 v83, 0xffff0000, v175
	v_rcp_f32_e32 v76, v76
	v_add_f32_e32 v72, 1.0, v72
	v_rcp_f32_e32 v77, v77
	v_add_f32_e32 v73, 1.0, v73
	v_pk_mul_f32 v[86:87], v[86:87], v[82:83]
	v_cvt_pk_bf16_f32 v82, v84, v85
	v_cvt_pk_bf16_f32 v84, v80, v81
	v_mad_i64_i32 v[80:81], s[20:21], v202, s40, v[196:197]
	v_rcp_f32_e32 v72, v72
	v_rcp_f32_e32 v73, v73
	v_cvt_pk_bf16_f32 v83, v90, v91
	v_cvt_pk_bf16_f32 v85, v86, v87
	v_lshl_add_u64 v[80:81], v[80:81], 0, v[194:195]
	global_store_dwordx4 v[80:81], v[82:85], off offset:2048
	v_pk_add_f32 v[74:75], v[74:75], v[130:131]
	v_pk_add_f32 v[78:79], v[78:79], v[134:135]
	v_lshlrev_b32_e32 v82, 16, v168
	v_and_b32_e32 v83, 0xffff0000, v168
	v_pk_mul_f32 v[76:77], v[76:77], v[82:83]
	v_lshlrev_b32_e32 v82, 16, v170
	v_and_b32_e32 v83, 0xffff0000, v170
	v_mul_f32_e32 v74, 0xbfb8aa3b, v74
	v_mul_f32_e32 v78, 0xbfb8aa3b, v78
	v_pk_mul_f32 v[72:73], v[72:73], v[82:83]
	v_exp_f32_e32 v82, v74
	v_mul_f32_e32 v74, 0xbfb8aa3b, v79
	v_exp_f32_e32 v78, v78
	v_exp_f32_e32 v79, v74
	v_mul_f32_e32 v75, 0xbfb8aa3b, v75
	v_exp_f32_e32 v84, v75
	v_pk_add_f32 v[68:69], v[68:69], v[132:133]
	v_pk_add_f32 v[64:65], v[64:65], v[128:129]
	v_mul_f32_e32 v68, 0xbfb8aa3b, v68
	v_mul_f32_e32 v69, 0xbfb8aa3b, v69
	v_exp_f32_e32 v68, v68
	v_mul_f32_e32 v64, 0xbfb8aa3b, v64
	v_exp_f32_e32 v69, v69
	v_mul_f32_e32 v65, 0xbfb8aa3b, v65
	v_add_f32_e32 v78, 1.0, v78
	v_add_f32_e32 v79, 1.0, v79
	v_exp_f32_e32 v64, v64
	v_exp_f32_e32 v65, v65
	v_rcp_f32_e32 v74, v78
	v_add_f32_e32 v78, 1.0, v82
	v_rcp_f32_e32 v75, v79
	v_add_f32_e32 v79, 1.0, v84
	v_rcp_f32_e32 v78, v78
	v_rcp_f32_e32 v79, v79
	v_add_f32_e32 v68, 1.0, v68
	v_add_f32_e32 v69, 1.0, v69
	v_lshlrev_b32_e32 v82, 16, v169
	v_and_b32_e32 v83, 0xffff0000, v169
	v_rcp_f32_e32 v68, v68
	v_add_f32_e32 v64, 1.0, v64
	v_rcp_f32_e32 v69, v69
	v_add_f32_e32 v65, 1.0, v65
	v_pk_mul_f32 v[74:75], v[74:75], v[82:83]
	v_lshlrev_b32_e32 v82, 16, v171
	v_and_b32_e32 v83, 0xffff0000, v171
	v_pk_add_f32 v[70:71], v[70:71], v[134:135]
	v_rcp_f32_e32 v64, v64
	v_rcp_f32_e32 v65, v65
	v_pk_mul_f32 v[82:83], v[78:79], v[82:83]
	v_cvt_pk_bf16_f32 v78, v72, v73
	v_mad_i64_i32 v[72:73], s[20:21], v200, s40, v[196:197]
	v_mul_f32_e32 v70, 0xbfb8aa3b, v70
	v_cvt_pk_bf16_f32 v76, v76, v77
	v_cvt_pk_bf16_f32 v77, v74, v75
	v_lshl_add_u64 v[74:75], v[72:73], 0, v[194:195]
	v_lshlrev_b32_e32 v72, 16, v164
	v_and_b32_e32 v73, 0xffff0000, v164
	v_exp_f32_e32 v70, v70
	v_pk_add_f32 v[66:67], v[66:67], v[130:131]
	v_pk_mul_f32 v[68:69], v[68:69], v[72:73]
	v_lshlrev_b32_e32 v72, 16, v166
	v_and_b32_e32 v73, 0xffff0000, v166
	v_pk_mul_f32 v[72:73], v[64:65], v[72:73]
	v_mul_f32_e32 v65, 0xbfb8aa3b, v66
	v_exp_f32_e32 v65, v65
	v_mul_f32_e32 v66, 0xbfb8aa3b, v71
	v_add_f32_e32 v64, 1.0, v70
	v_exp_f32_e32 v70, v66
	v_mul_f32_e32 v67, 0xbfb8aa3b, v67
	v_exp_f32_e32 v67, v67
	v_add_f32_e32 v65, 1.0, v65
	v_rcp_f32_e32 v66, v65
	v_add_f32_e32 v65, 1.0, v70
	v_rcp_f32_e32 v64, v64
	v_rcp_f32_e32 v65, v65
	v_add_f32_e32 v67, 1.0, v67
	v_rcp_f32_e32 v67, v67
	v_lshlrev_b32_e32 v70, 16, v165
	v_and_b32_e32 v71, 0xffff0000, v165
	v_cvt_pk_bf16_f32 v79, v82, v83
	v_pk_mul_f32 v[70:71], v[64:65], v[70:71]
	v_lshlrev_b32_e32 v64, 16, v167
	v_and_b32_e32 v65, 0xffff0000, v167
	global_store_dwordx4 v[74:75], v[76:79], off offset:2048
	global_store_dwordx4 v[214:215], v[224:227], off offset:2048
	s_nop 0
	v_pk_mul_f32 v[76:77], v[66:67], v[64:65]
	v_cvt_pk_bf16_f32 v64, v68, v69
	v_mad_i64_i32 v[68:69], s[20:21], v198, s40, v[196:197]
	v_cvt_pk_bf16_f32 v65, v70, v71
	v_cvt_pk_bf16_f32 v66, v72, v73
	v_cvt_pk_bf16_f32 v67, v76, v77
	v_lshl_add_u64 v[72:73], v[68:69], 0, v[194:195]
	global_store_dwordx4 v[72:73], v[64:67], off offset:2048
	global_load_dwordx4 v[68:71], v[192:193], off offset:512
	s_nop 0
	global_load_dwordx4 v[64:67], v[192:193], off offset:528
	v_lshlrev_b32_e32 v76, 16, v160
	v_and_b32_e32 v77, 0xffff0000, v160
	s_mov_b64 s[20:21], s[14:15]
	s_waitcnt vmcnt(0)
; __device__ __forceinline__ float sigm(float x) { return __builtin_amdgcn_rcpf(1.0f + __builtin_amdgcn_exp2f(-1.4426950408889634f * x)); }
;     __device__ __forceinline__ void operator()(EPI_ARGS) const {
;     ...
;             for (int ai = 0; ai < 2; ++ai)
; #pragma unroll
;                 for (int m = 0; m < 4; ++m) { const size_t off = (size_t)(row0 + ai * 128 + m * 16) * 512 + col0 + bj * 128;
;                     f32x4 h0, h1; unpack8(hw[ai][m], h0, h1);
;                     f32x4 v0 = acc[ai][bj][m][0] + b0, v1 = acc[ai][bj][m][1] + b1;
; #pragma unroll
;                     for (int j = 0; j < 4; ++j) { v0[j] = h0[j] * sigm(v0[j]); v1[j] = h1[j] * sigm(v1[j]); }
;                     *(u32x4*)(O + (size_t)(row0 + ai * 128 + m * 16) * KAB + 1024 + col0 + bj * 128) = pack8(v0, v1); } }
	v_pk_add_f32 v[60:61], v[60:61], v[68:69]
	s_nop 0
	v_mul_f32_e32 v60, 0xbfb8aa3b, v60
	v_pk_add_f32 v[56:57], v[56:57], v[64:65]
	v_mul_f32_e32 v61, 0xbfb8aa3b, v61
	v_exp_f32_e32 v60, v60
	v_mul_f32_e32 v56, 0xbfb8aa3b, v56
	v_exp_f32_e32 v61, v61
	v_mul_f32_e32 v57, 0xbfb8aa3b, v57
	v_exp_f32_e32 v56, v56
	v_exp_f32_e32 v57, v57
	v_add_f32_e32 v60, 1.0, v60
	v_add_f32_e32 v61, 1.0, v61
	v_rcp_f32_e32 v60, v60
	v_add_f32_e32 v56, 1.0, v56
	v_rcp_f32_e32 v61, v61
	v_add_f32_e32 v57, 1.0, v57
	v_pk_add_f32 v[62:63], v[62:63], v[70:71]
	v_rcp_f32_e32 v56, v56
	v_rcp_f32_e32 v57, v57
	v_mul_f32_e32 v62, 0xbfb8aa3b, v62
	v_exp_f32_e32 v62, v62
	v_pk_add_f32 v[58:59], v[58:59], v[66:67]
	v_pk_mul_f32 v[60:61], v[60:61], v[76:77]
	v_lshlrev_b32_e32 v76, 16, v162
	v_and_b32_e32 v77, 0xffff0000, v162
	v_pk_mul_f32 v[76:77], v[56:57], v[76:77]
	v_mul_f32_e32 v57, 0xbfb8aa3b, v58
	v_exp_f32_e32 v57, v57
	v_mul_f32_e32 v58, 0xbfb8aa3b, v63
	v_add_f32_e32 v56, 1.0, v62
	v_exp_f32_e32 v62, v58
	v_mul_f32_e32 v59, 0xbfb8aa3b, v59
	v_exp_f32_e32 v59, v59
	v_pk_add_f32 v[52:53], v[52:53], v[68:69]
	v_add_f32_e32 v57, 1.0, v57
	v_mul_f32_e32 v52, 0xbfb8aa3b, v52
	v_pk_add_f32 v[48:49], v[48:49], v[64:65]
	v_mul_f32_e32 v53, 0xbfb8aa3b, v53
	v_rcp_f32_e32 v58, v57
	v_add_f32_e32 v57, 1.0, v62
	v_exp_f32_e32 v52, v52
	v_mul_f32_e32 v48, 0xbfb8aa3b, v48
	v_exp_f32_e32 v53, v53
	v_mul_f32_e32 v49, 0xbfb8aa3b, v49
	v_rcp_f32_e32 v56, v56
	v_rcp_f32_e32 v57, v57
	v_add_f32_e32 v59, 1.0, v59
	v_exp_f32_e32 v48, v48
	v_exp_f32_e32 v49, v49
	v_rcp_f32_e32 v59, v59
	v_lshlrev_b32_e32 v62, 16, v161
	v_and_b32_e32 v63, 0xffff0000, v161
	v_add_f32_e32 v52, 1.0, v52
	v_add_f32_e32 v53, 1.0, v53
	v_pk_mul_f32 v[62:63], v[56:57], v[62:63]
	v_lshlrev_b32_e32 v56, 16, v163
	v_and_b32_e32 v57, 0xffff0000, v163
	v_rcp_f32_e32 v52, v52
	v_add_f32_e32 v48, 1.0, v48
	v_rcp_f32_e32 v53, v53
	v_add_f32_e32 v49, 1.0, v49
	v_pk_mul_f32 v[78:79], v[58:59], v[56:57]
	v_pk_add_f32 v[54:55], v[54:55], v[70:71]
	v_rcp_f32_e32 v48, v48
	v_rcp_f32_e32 v49, v49
	v_cvt_pk_bf16_f32 v56, v60, v61
	v_cvt_pk_bf16_f32 v57, v62, v63
	v_cvt_pk_bf16_f32 v58, v76, v77
	v_cvt_pk_bf16_f32 v59, v78, v79
	v_mul_f32_e32 v54, 0xbfb8aa3b, v54
	global_store_dwordx4 v[214:215], v[56:59], off offset:2304
	v_exp_f32_e32 v54, v54
	v_pk_add_f32 v[50:51], v[50:51], v[66:67]
	v_lshlrev_b32_e32 v56, 16, v156
	v_and_b32_e32 v57, 0xffff0000, v156
	v_pk_mul_f32 v[52:53], v[52:53], v[56:57]
	v_lshlrev_b32_e32 v56, 16, v158
	v_and_b32_e32 v57, 0xffff0000, v158
	v_pk_mul_f32 v[56:57], v[48:49], v[56:57]
	v_mul_f32_e32 v49, 0xbfb8aa3b, v50
	v_exp_f32_e32 v49, v49
	v_mul_f32_e32 v50, 0xbfb8aa3b, v55
	v_add_f32_e32 v48, 1.0, v54
	v_exp_f32_e32 v54, v50
	v_mul_f32_e32 v51, 0xbfb8aa3b, v51
	v_exp_f32_e32 v51, v51
	v_pk_add_f32 v[44:45], v[44:45], v[68:69]
	v_add_f32_e32 v49, 1.0, v49
	v_mul_f32_e32 v44, 0xbfb8aa3b, v44
	v_pk_add_f32 v[40:41], v[40:41], v[64:65]
	v_mul_f32_e32 v45, 0xbfb8aa3b, v45
	v_rcp_f32_e32 v50, v49
	v_add_f32_e32 v49, 1.0, v54
	v_exp_f32_e32 v44, v44
	v_mul_f32_e32 v40, 0xbfb8aa3b, v40
	v_exp_f32_e32 v45, v45
	v_mul_f32_e32 v41, 0xbfb8aa3b, v41
	v_rcp_f32_e32 v48, v48
	v_rcp_f32_e32 v49, v49
	v_add_f32_e32 v51, 1.0, v51
	v_exp_f32_e32 v40, v40
	v_exp_f32_e32 v41, v41
	v_rcp_f32_e32 v51, v51
	v_lshlrev_b32_e32 v54, 16, v157
	v_and_b32_e32 v55, 0xffff0000, v157
	v_add_f32_e32 v44, 1.0, v44
	v_add_f32_e32 v45, 1.0, v45
	v_pk_mul_f32 v[54:55], v[48:49], v[54:55]
	v_lshlrev_b32_e32 v48, 16, v159
	v_and_b32_e32 v49, 0xffff0000, v159
	v_rcp_f32_e32 v44, v44
	v_add_f32_e32 v40, 1.0, v40
	v_rcp_f32_e32 v45, v45
	v_add_f32_e32 v41, 1.0, v41
	v_pk_mul_f32 v[58:59], v[50:51], v[48:49]
	v_pk_add_f32 v[46:47], v[46:47], v[70:71]
	v_rcp_f32_e32 v40, v40
	v_rcp_f32_e32 v41, v41
	v_cvt_pk_bf16_f32 v48, v52, v53
	v_cvt_pk_bf16_f32 v49, v54, v55
	v_cvt_pk_bf16_f32 v50, v56, v57
	v_cvt_pk_bf16_f32 v51, v58, v59
	v_mul_f32_e32 v46, 0xbfb8aa3b, v46
	global_store_dwordx4 v[112:113], v[48:51], off offset:2304
	v_exp_f32_e32 v46, v46
	v_pk_add_f32 v[42:43], v[42:43], v[66:67]
	v_lshlrev_b32_e32 v48, 16, v148
	v_and_b32_e32 v49, 0xffff0000, v148
	v_pk_mul_f32 v[44:45], v[44:45], v[48:49]
	v_lshlrev_b32_e32 v48, 16, v150
	v_and_b32_e32 v49, 0xffff0000, v150
	v_pk_mul_f32 v[48:49], v[40:41], v[48:49]
	v_mul_f32_e32 v41, 0xbfb8aa3b, v42
	v_exp_f32_e32 v41, v41
	v_mul_f32_e32 v42, 0xbfb8aa3b, v47
	v_add_f32_e32 v40, 1.0, v46
	v_exp_f32_e32 v46, v42
	v_mul_f32_e32 v43, 0xbfb8aa3b, v43
	v_exp_f32_e32 v43, v43
	v_pk_add_f32 v[36:37], v[36:37], v[68:69]
	v_add_f32_e32 v41, 1.0, v41
	v_mul_f32_e32 v36, 0xbfb8aa3b, v36
	v_pk_add_f32 v[32:33], v[32:33], v[64:65]
	v_mul_f32_e32 v37, 0xbfb8aa3b, v37
	v_rcp_f32_e32 v42, v41
	v_add_f32_e32 v41, 1.0, v46
	v_exp_f32_e32 v36, v36
	v_mul_f32_e32 v32, 0xbfb8aa3b, v32
	v_exp_f32_e32 v37, v37
	v_mul_f32_e32 v33, 0xbfb8aa3b, v33
	v_rcp_f32_e32 v40, v40
	v_rcp_f32_e32 v41, v41
	v_add_f32_e32 v43, 1.0, v43
	v_exp_f32_e32 v32, v32
	v_exp_f32_e32 v33, v33
	v_rcp_f32_e32 v43, v43
	v_lshlrev_b32_e32 v46, 16, v149
	v_and_b32_e32 v47, 0xffff0000, v149
	v_add_f32_e32 v36, 1.0, v36
	v_add_f32_e32 v37, 1.0, v37
	v_pk_mul_f32 v[46:47], v[40:41], v[46:47]
	v_lshlrev_b32_e32 v40, 16, v151
	v_and_b32_e32 v41, 0xffff0000, v151
	v_rcp_f32_e32 v36, v36
	v_add_f32_e32 v32, 1.0, v32
	v_rcp_f32_e32 v37, v37
	v_add_f32_e32 v33, 1.0, v33
	v_pk_mul_f32 v[50:51], v[42:43], v[40:41]
	v_pk_add_f32 v[38:39], v[38:39], v[70:71]
	v_rcp_f32_e32 v32, v32
	v_rcp_f32_e32 v33, v33
	v_cvt_pk_bf16_f32 v40, v44, v45
	v_cvt_pk_bf16_f32 v41, v46, v47
	v_cvt_pk_bf16_f32 v42, v48, v49
	v_cvt_pk_bf16_f32 v43, v50, v51
	v_mul_f32_e32 v38, 0xbfb8aa3b, v38
; __device__ __forceinline__ float sigm(float x) { return __builtin_amdgcn_rcpf(1.0f + __builtin_amdgcn_exp2f(-1.4426950408889634f * x)); }
;     __device__ __forceinline__ void operator()(EPI_ARGS) const {
;     ...
;             for (int ai = 0; ai < 2; ++ai)
; #pragma unroll
;                 for (int m = 0; m < 4; ++m) { const size_t off = (size_t)(row0 + ai * 128 + m * 16) * 512 + col0 + bj * 128;
;                     f32x4 h0, h1; unpack8(hw[ai][m], h0, h1);
;                     f32x4 v0 = acc[ai][bj][m][0] + b0, v1 = acc[ai][bj][m][1] + b1;
; #pragma unroll
;                     for (int j = 0; j < 4; ++j) { v0[j] = h0[j] * sigm(v0[j]); v1[j] = h1[j] * sigm(v1[j]); }
;                     *(u32x4*)(O + (size_t)(row0 + ai * 128 + m * 16) * KAB + 1024 + col0 + bj * 128) = pack8(v0, v1); } }
	global_store_dwordx4 v[104:105], v[40:43], off offset:2304
	v_exp_f32_e32 v38, v38
	v_pk_add_f32 v[34:35], v[34:35], v[66:67]
	v_lshlrev_b32_e32 v40, 16, v144
	v_and_b32_e32 v41, 0xffff0000, v144
	v_pk_mul_f32 v[36:37], v[36:37], v[40:41]
	v_lshlrev_b32_e32 v40, 16, v146
	v_and_b32_e32 v41, 0xffff0000, v146
	v_pk_mul_f32 v[40:41], v[32:33], v[40:41]
	v_mul_f32_e32 v33, 0xbfb8aa3b, v34
	v_exp_f32_e32 v33, v33
	v_mul_f32_e32 v34, 0xbfb8aa3b, v39
	v_add_f32_e32 v32, 1.0, v38
	v_exp_f32_e32 v38, v34
	v_mul_f32_e32 v35, 0xbfb8aa3b, v35
	v_exp_f32_e32 v35, v35
	v_pk_add_f32 v[28:29], v[28:29], v[68:69]
	v_add_f32_e32 v33, 1.0, v33
	v_mul_f32_e32 v28, 0xbfb8aa3b, v28
	v_pk_add_f32 v[24:25], v[24:25], v[64:65]
	v_mul_f32_e32 v29, 0xbfb8aa3b, v29
	v_rcp_f32_e32 v34, v33
	v_add_f32_e32 v33, 1.0, v38
	v_exp_f32_e32 v28, v28
	v_mul_f32_e32 v24, 0xbfb8aa3b, v24
	v_exp_f32_e32 v29, v29
	v_mul_f32_e32 v25, 0xbfb8aa3b, v25
	v_rcp_f32_e32 v32, v32
	v_rcp_f32_e32 v33, v33
	v_add_f32_e32 v35, 1.0, v35
	v_exp_f32_e32 v24, v24
	v_exp_f32_e32 v25, v25
	v_rcp_f32_e32 v35, v35
	v_lshlrev_b32_e32 v38, 16, v145
	v_and_b32_e32 v39, 0xffff0000, v145
	v_add_f32_e32 v28, 1.0, v28
	v_add_f32_e32 v29, 1.0, v29
	v_pk_mul_f32 v[38:39], v[32:33], v[38:39]
	v_lshlrev_b32_e32 v32, 16, v147
	v_and_b32_e32 v33, 0xffff0000, v147
	v_rcp_f32_e32 v28, v28
	v_add_f32_e32 v24, 1.0, v24
	v_rcp_f32_e32 v29, v29
	v_add_f32_e32 v25, 1.0, v25
	v_pk_mul_f32 v[42:43], v[34:35], v[32:33]
	v_pk_add_f32 v[30:31], v[30:31], v[70:71]
	v_rcp_f32_e32 v24, v24
	v_rcp_f32_e32 v25, v25
	v_cvt_pk_bf16_f32 v32, v36, v37
	v_cvt_pk_bf16_f32 v33, v38, v39
	v_cvt_pk_bf16_f32 v34, v40, v41
	v_cvt_pk_bf16_f32 v35, v42, v43
	v_mul_f32_e32 v30, 0xbfb8aa3b, v30
	global_store_dwordx4 v[96:97], v[32:35], off offset:2304
	v_exp_f32_e32 v30, v30
	v_pk_add_f32 v[26:27], v[26:27], v[66:67]
	v_lshlrev_b32_e32 v32, 16, v140
	v_and_b32_e32 v33, 0xffff0000, v140
	v_pk_mul_f32 v[28:29], v[28:29], v[32:33]
	v_lshlrev_b32_e32 v32, 16, v142
	v_and_b32_e32 v33, 0xffff0000, v142
	v_pk_mul_f32 v[32:33], v[24:25], v[32:33]
	v_mul_f32_e32 v25, 0xbfb8aa3b, v26
	v_exp_f32_e32 v25, v25
	v_mul_f32_e32 v26, 0xbfb8aa3b, v31
	v_add_f32_e32 v24, 1.0, v30
	v_exp_f32_e32 v30, v26
	v_mul_f32_e32 v27, 0xbfb8aa3b, v27
	v_exp_f32_e32 v27, v27
	v_pk_add_f32 v[20:21], v[20:21], v[68:69]
	v_add_f32_e32 v25, 1.0, v25
	v_mul_f32_e32 v20, 0xbfb8aa3b, v20
	v_pk_add_f32 v[16:17], v[16:17], v[64:65]
	v_mul_f32_e32 v21, 0xbfb8aa3b, v21
	v_rcp_f32_e32 v26, v25
	v_add_f32_e32 v25, 1.0, v30
	v_exp_f32_e32 v20, v20
	v_mul_f32_e32 v16, 0xbfb8aa3b, v16
	v_exp_f32_e32 v21, v21
	v_mul_f32_e32 v17, 0xbfb8aa3b, v17
	v_rcp_f32_e32 v24, v24
	v_rcp_f32_e32 v25, v25
	v_add_f32_e32 v27, 1.0, v27
	v_exp_f32_e32 v16, v16
	v_exp_f32_e32 v17, v17
	v_rcp_f32_e32 v27, v27
	v_lshlrev_b32_e32 v30, 16, v141
	v_and_b32_e32 v31, 0xffff0000, v141
	v_add_f32_e32 v20, 1.0, v20
	v_add_f32_e32 v21, 1.0, v21
	v_pk_mul_f32 v[30:31], v[24:25], v[30:31]
	v_lshlrev_b32_e32 v24, 16, v143
	v_and_b32_e32 v25, 0xffff0000, v143
	v_rcp_f32_e32 v20, v20
	v_add_f32_e32 v16, 1.0, v16
	v_rcp_f32_e32 v21, v21
	v_add_f32_e32 v17, 1.0, v17
	v_pk_mul_f32 v[34:35], v[26:27], v[24:25]
	v_pk_add_f32 v[22:23], v[22:23], v[70:71]
	v_rcp_f32_e32 v16, v16
	v_rcp_f32_e32 v17, v17
	v_cvt_pk_bf16_f32 v24, v28, v29
	v_cvt_pk_bf16_f32 v25, v30, v31
	v_cvt_pk_bf16_f32 v26, v32, v33
	v_cvt_pk_bf16_f32 v27, v34, v35
	v_mul_f32_e32 v22, 0xbfb8aa3b, v22
	global_store_dwordx4 v[88:89], v[24:27], off offset:2304
	v_exp_f32_e32 v22, v22
	v_pk_add_f32 v[18:19], v[18:19], v[66:67]
	v_lshlrev_b32_e32 v24, 16, v136
	v_and_b32_e32 v25, 0xffff0000, v136
	v_pk_mul_f32 v[20:21], v[20:21], v[24:25]
	v_lshlrev_b32_e32 v24, 16, v138
	v_and_b32_e32 v25, 0xffff0000, v138
	v_pk_mul_f32 v[24:25], v[16:17], v[24:25]
	v_mul_f32_e32 v17, 0xbfb8aa3b, v18
	v_exp_f32_e32 v17, v17
	v_mul_f32_e32 v18, 0xbfb8aa3b, v23
	v_add_f32_e32 v16, 1.0, v22
	v_exp_f32_e32 v22, v18
	v_mul_f32_e32 v19, 0xbfb8aa3b, v19
	v_exp_f32_e32 v19, v19
; __device__ __forceinline__ float sigm(float x) { return __builtin_amdgcn_rcpf(1.0f + __builtin_amdgcn_exp2f(-1.4426950408889634f * x)); }
; #define PG8_WAIT_V(n) asm volatile("s_waitcnt vmcnt(" #n ")" ::: "memory")
; #define PG8_BAR __builtin_amdgcn_s_barrier()
; template <class Epi>
; __device__ __forceinline__ void gemm_phase(ldsp lds, const Gemm g, const StaticOrder& S, const Epi& E) {
;     ...
;     PG8_WAIT_V(0);
;     if (wr == 0) PG8_BAR;
;     PG8_BAR;
;     __device__ __forceinline__ void operator()(EPI_ARGS) const {
;     ...
;             for (int ai = 0; ai < 2; ++ai)
; #pragma unroll
;                 for (int m = 0; m < 4; ++m) { const size_t off = (size_t)(row0 + ai * 128 + m * 16) * 512 + col0 + bj * 128;
;                     f32x4 h0, h1; unpack8(hw[ai][m], h0, h1);
;                     f32x4 v0 = acc[ai][bj][m][0] + b0, v1 = acc[ai][bj][m][1] + b1;
; #pragma unroll
;                     for (int j = 0; j < 4; ++j) { v0[j] = h0[j] * sigm(v0[j]); v1[j] = h1[j] * sigm(v1[j]); }
;                     *(u32x4*)(O + (size_t)(row0 + ai * 128 + m * 16) * KAB + 1024 + col0 + bj * 128) = pack8(v0, v1); } }
	v_pk_add_f32 v[12:13], v[12:13], v[68:69]
	v_add_f32_e32 v17, 1.0, v17
	v_mul_f32_e32 v12, 0xbfb8aa3b, v12
	v_pk_add_f32 v[8:9], v[8:9], v[64:65]
	v_mul_f32_e32 v13, 0xbfb8aa3b, v13
	v_rcp_f32_e32 v18, v17
	v_add_f32_e32 v17, 1.0, v22
	v_exp_f32_e32 v12, v12
	v_mul_f32_e32 v8, 0xbfb8aa3b, v8
	v_exp_f32_e32 v13, v13
	v_mul_f32_e32 v9, 0xbfb8aa3b, v9
	v_rcp_f32_e32 v16, v16
	v_rcp_f32_e32 v17, v17
	v_add_f32_e32 v19, 1.0, v19
	v_exp_f32_e32 v8, v8
	v_exp_f32_e32 v9, v9
	v_rcp_f32_e32 v19, v19
	v_lshlrev_b32_e32 v22, 16, v137
	v_and_b32_e32 v23, 0xffff0000, v137
	v_add_f32_e32 v12, 1.0, v12
	v_add_f32_e32 v13, 1.0, v13
	v_pk_mul_f32 v[22:23], v[16:17], v[22:23]
	v_lshlrev_b32_e32 v16, 16, v139
	v_and_b32_e32 v17, 0xffff0000, v139
	v_rcp_f32_e32 v12, v12
	v_add_f32_e32 v8, 1.0, v8
	v_rcp_f32_e32 v13, v13
	v_add_f32_e32 v9, 1.0, v9
	v_pk_mul_f32 v[26:27], v[18:19], v[16:17]
	v_pk_add_f32 v[14:15], v[14:15], v[70:71]
	v_rcp_f32_e32 v8, v8
	v_rcp_f32_e32 v9, v9
	v_cvt_pk_bf16_f32 v16, v20, v21
	v_cvt_pk_bf16_f32 v17, v22, v23
	v_cvt_pk_bf16_f32 v18, v24, v25
	v_cvt_pk_bf16_f32 v19, v26, v27
	v_mul_f32_e32 v14, 0xbfb8aa3b, v14
	global_store_dwordx4 v[80:81], v[16:19], off offset:2304
	v_exp_f32_e32 v14, v14
	v_pk_add_f32 v[10:11], v[10:11], v[66:67]
	v_lshlrev_b32_e32 v16, 16, v124
	v_and_b32_e32 v17, 0xffff0000, v124
	v_pk_mul_f32 v[12:13], v[12:13], v[16:17]
	v_lshlrev_b32_e32 v16, 16, v126
	v_and_b32_e32 v17, 0xffff0000, v126
	v_pk_mul_f32 v[16:17], v[8:9], v[16:17]
	v_mul_f32_e32 v9, 0xbfb8aa3b, v10
	v_exp_f32_e32 v9, v9
	v_mul_f32_e32 v10, 0xbfb8aa3b, v15
	v_add_f32_e32 v8, 1.0, v14
	v_exp_f32_e32 v14, v10
	v_mul_f32_e32 v11, 0xbfb8aa3b, v11
	v_exp_f32_e32 v11, v11
	v_pk_add_f32 v[4:5], v[4:5], v[68:69]
	v_add_f32_e32 v9, 1.0, v9
	v_mul_f32_e32 v4, 0xbfb8aa3b, v4
	v_pk_add_f32 v[0:1], v[0:1], v[64:65]
	v_mul_f32_e32 v5, 0xbfb8aa3b, v5
	v_rcp_f32_e32 v10, v9
	v_add_f32_e32 v9, 1.0, v14
	v_exp_f32_e32 v4, v4
	v_mul_f32_e32 v0, 0xbfb8aa3b, v0
	v_exp_f32_e32 v5, v5
	v_mul_f32_e32 v1, 0xbfb8aa3b, v1
	v_rcp_f32_e32 v8, v8
	v_rcp_f32_e32 v9, v9
	v_add_f32_e32 v11, 1.0, v11
	v_exp_f32_e32 v0, v0
	v_exp_f32_e32 v1, v1
	v_rcp_f32_e32 v11, v11
	v_lshlrev_b32_e32 v14, 16, v125
	v_and_b32_e32 v15, 0xffff0000, v125
	v_add_f32_e32 v4, 1.0, v4
	v_add_f32_e32 v5, 1.0, v5
	v_pk_mul_f32 v[14:15], v[8:9], v[14:15]
	v_lshlrev_b32_e32 v8, 16, v127
	v_and_b32_e32 v9, 0xffff0000, v127
	v_rcp_f32_e32 v4, v4
	v_add_f32_e32 v0, 1.0, v0
	v_rcp_f32_e32 v5, v5
	v_add_f32_e32 v1, 1.0, v1
	v_pk_mul_f32 v[18:19], v[10:11], v[8:9]
	v_pk_add_f32 v[6:7], v[6:7], v[70:71]
	v_rcp_f32_e32 v0, v0
	v_rcp_f32_e32 v1, v1
	v_cvt_pk_bf16_f32 v8, v12, v13
	v_cvt_pk_bf16_f32 v9, v14, v15
	v_cvt_pk_bf16_f32 v10, v16, v17
	v_cvt_pk_bf16_f32 v11, v18, v19
	v_mul_f32_e32 v6, 0xbfb8aa3b, v6
	global_store_dwordx4 v[74:75], v[8:11], off offset:2304
	v_exp_f32_e32 v6, v6
	v_pk_add_f32 v[2:3], v[2:3], v[66:67]
	v_lshlrev_b32_e32 v8, 16, v120
	v_and_b32_e32 v9, 0xffff0000, v120
	v_pk_mul_f32 v[4:5], v[4:5], v[8:9]
	v_lshlrev_b32_e32 v8, 16, v122
	v_and_b32_e32 v9, 0xffff0000, v122
	v_pk_mul_f32 v[8:9], v[0:1], v[8:9]
	v_mul_f32_e32 v1, 0xbfb8aa3b, v2
	v_exp_f32_e32 v1, v1
	v_mul_f32_e32 v2, 0xbfb8aa3b, v7
	v_add_f32_e32 v0, 1.0, v6
	v_exp_f32_e32 v6, v2
	v_mul_f32_e32 v3, 0xbfb8aa3b, v3
	v_exp_f32_e32 v3, v3
	v_add_f32_e32 v1, 1.0, v1
	v_rcp_f32_e32 v2, v1
	v_add_f32_e32 v1, 1.0, v6
	v_rcp_f32_e32 v0, v0
	v_rcp_f32_e32 v1, v1
	v_add_f32_e32 v3, 1.0, v3
	v_rcp_f32_e32 v3, v3
	v_lshlrev_b32_e32 v6, 16, v121
	v_and_b32_e32 v7, 0xffff0000, v121
	v_pk_mul_f32 v[6:7], v[0:1], v[6:7]
	v_lshlrev_b32_e32 v0, 16, v123
	v_and_b32_e32 v1, 0xffff0000, v123
	v_pk_mul_f32 v[10:11], v[2:3], v[0:1]
	v_cvt_pk_bf16_f32 v0, v4, v5
	v_cvt_pk_bf16_f32 v1, v6, v7
	v_cvt_pk_bf16_f32 v2, v8, v9
	v_cvt_pk_bf16_f32 v3, v10, v11
	global_store_dwordx4 v[72:73], v[0:3], off offset:2304
	s_cbranch_vccz .LBB0_567
	s_waitcnt vmcnt(0)
	s_cmpk_gt_u32 s26, 0xff
	s_cbranch_scc1 .LBB0_578
	s_barrier

; #define PG8_STAGE(bufoff, gbase, voff) do { _Pragma("unroll") for (int _i = 0; _i < 2; ++_i) \
;         __builtin_amdgcn_global_load_lds((const unsigned*)((const char*)(gbase) + (voff)[_i]), (LAS unsigned*)(lds + (bufoff) + ldsw + _i * 8192), 16, 0, 0); } while (0)
; #define PG8_LDA(dst, b, h) do { _Pragma("unroll") for (int m = 0; m < 4; ++m) _Pragma("unroll") for (int k = 0; k < 2; ++k) dst[m][k] = *(const LAS bf16x8*)(lds + PG8_SA(b, h) + aoff + m * 2048 + k * 1024); } while (0)
; #define PG8_LDB(dst, b, h) do { _Pragma("unroll") for (int n = 0; n < 2; ++n) _Pragma("unroll") for (int k = 0; k < 2; ++k) dst[n][k] = *(const LAS bf16x8*)(lds + PG8_SB(b, h) + boff + n * 2048 + k * 1024); } while (0)
; #define PG8_MMA(ai, bj, At, Bt) do { __builtin_amdgcn_s_setprio(1); _Pragma("unroll") for (int m = 0; m < 4; ++m) _Pragma("unroll") for (int n = 0; n < 2; ++n) _Pragma("unroll") for (int k = 0; k < 2; ++k) \
;         acc[ai][bj][m][n] = __builtin_amdgcn_mfma_f32_16x16x32_bf16(Bt[n][k], At[m][k], acc[ai][bj][m][n], 0, 0, 0); __builtin_amdgcn_s_setprio(0); } while (0)
; #define PG8_WAIT_V(n) asm volatile("s_waitcnt vmcnt(" #n ")" ::: "memory")
; #define PG8_BAR __builtin_amdgcn_s_barrier()
; template <class Epi>
; __device__ __forceinline__ void gemm_phase(ldsp lds, const Gemm g, const StaticOrder& S, const Epi& E) {
;     ...
;             const bool last = (t == nt - 2);
;             const char* a1 = cA + (size_t)(t + 1) * kstep;
;             const char* a2 = last ? nA : cA + (size_t)(t + 2) * kstep; const char* b2 = last ? nB : cB + (size_t)(t + 2) * kstep;
;             const char* a3 = a2 + kstep; const char* b3 = b2 + kstep;
;             if constexpr (Epi::NPRE > 0) { if (last) E.pre(pre, cur, wr, fr); }
;             if constexpr (Epi::MID_T > 0) { if (t == Epi::MID_T) E.mid(acc, cur, wr, wc, fr, fq); }
;             PG8_LDB(B0, 0, 0); PG8_SCHED; PG8_LDA(At, 0, 0); PG8_STAGE(PG8_SA(1, 1), a1 + hstep, voffA);
;             PG8_WAIT_L(8); PG8_WAIT_V(10); PG8_BAR; PG8_WAIT_L(0); PG8_MMA(0, 0, At, B0); PG8_BAR; PG8_SCHED;
;             PG8_LDB(B1, 0, 1); PG8_STAGE(PG8_SB(0, 0), b2, voffB);
;             PG8_WAIT_V(10); PG8_BAR; PG8_WAIT_L(0); PG8_MMA(0, 1, At, B1); PG8_BAR;
;             PG8_LDA(At, 0, 1); PG8_STAGE(PG8_SA(0, 0), a2, voffA);
;             PG8_WAIT_V(10); PG8_BAR; PG8_WAIT_L(0); PG8_MMA(1, 0, At, B0); PG8_BAR; PG8_SCHED;
.LBB0_654:
	s_add_u32 s26, s22, s24
	ds_read_b128 v[128:131], v247 offset:0
	ds_read_b128 v[132:135], v247 offset:1024
	ds_read_b128 v[136:139], v247 offset:2048
	ds_read_b128 v[140:143], v247 offset:3072
	s_addc_u32 s27, s23, s25
	s_add_u32 s26, s26, 0x100
	s_addc_u32 s27, s27, 0
	s_add_u32 s54, s51, s24
	s_addc_u32 s55, s52, s25
	s_cmpk_eq_i32 s24, 0xb00
	s_cselect_b32 s29, s1, s27
	s_cselect_b32 s28, s0, s26
	s_cselect_b32 s27, s5, s55
	s_cselect_b32 s26, s4, s54
	v_lshl_add_u64 v[176:177], v[212:213], 0, s[24:25]
	s_add_i32 m0, s36, 0xc000
	s_waitcnt vmcnt(0)
	ds_read_b128 v[144:147], v224
	ds_read_b128 v[148:151], v224 offset:1024
	ds_read_b128 v[152:155], v224 offset:2048
	ds_read_b128 v[156:159], v224 offset:3072
	ds_read_b128 v[160:163], v224 offset:4096
	ds_read_b128 v[164:167], v224 offset:5120
	ds_read_b128 v[168:171], v224 offset:6144
	ds_read_b128 v[172:175], v224 offset:7168
	global_load_lds_dwordx4 v[176:177], off
	v_lshl_add_u64 v[176:177], v[214:215], 0, s[24:25]
	s_add_i32 m0, s36, 0xe000
	s_nop 0
	global_load_lds_dwordx4 v[176:177], off
	s_waitcnt lgkmcnt(8)
	s_waitcnt vmcnt(10)
	s_barrier
	s_waitcnt lgkmcnt(0)
	s_setprio 1
	s_waitcnt lgkmcnt(0)
	v_mfma_f32_16x16x32_bf16 v[124:127], v[128:131], v[144:147], v[124:127]
	v_mfma_f32_16x16x32_bf16 v[120:123], v[136:139], v[144:147], v[120:123]
	v_mfma_f32_16x16x32_bf16 v[116:119], v[128:131], v[152:155], v[116:119]
	v_mfma_f32_16x16x32_bf16 v[104:107], v[136:139], v[152:155], v[104:107]
	v_mfma_f32_16x16x32_bf16 v[96:99], v[128:131], v[160:163], v[96:99]
	v_mfma_f32_16x16x32_bf16 v[88:91], v[136:139], v[160:163], v[88:91]
	v_mfma_f32_16x16x32_bf16 v[80:83], v[128:131], v[168:171], v[80:83]
	v_mfma_f32_16x16x32_bf16 v[72:75], v[136:139], v[168:171], v[72:75]
	v_mfma_f32_16x16x32_bf16 v[124:127], v[132:135], v[148:151], v[124:127]
	v_mfma_f32_16x16x32_bf16 v[120:123], v[140:143], v[148:151], v[120:123]
	v_mfma_f32_16x16x32_bf16 v[116:119], v[132:135], v[156:159], v[116:119]
	v_mfma_f32_16x16x32_bf16 v[104:107], v[140:143], v[156:159], v[104:107]
	v_mfma_f32_16x16x32_bf16 v[96:99], v[132:135], v[164:167], v[96:99]
	v_mfma_f32_16x16x32_bf16 v[88:91], v[140:143], v[164:167], v[88:91]
	v_mfma_f32_16x16x32_bf16 v[80:83], v[132:135], v[172:175], v[80:83]
	s_barrier
	v_mfma_f32_16x16x32_bf16 v[72:75], v[140:143], v[172:175], v[72:75]
	s_setprio 0
	s_add_i32 s54, s45, s35
	s_add_u32 s98, s26, 0x80
	s_addc_u32 s99, s27, 0
	s_mov_b32 m0, s54
	ds_read_b128 v[176:179], v247 offset:16384
	ds_read_b128 v[180:183], v247 offset:17408
	ds_read_b128 v[184:187], v247 offset:18432
	ds_read_b128 v[188:191], v247 offset:19456
	global_load_lds_dwordx4 v194, s[26:27]
	s_add_i32 m0, s54, 0x2000
	s_nop 0
	global_load_lds_dwordx4 v198, s[26:27]
	s_waitcnt vmcnt(10)
	s_barrier
	s_waitcnt lgkmcnt(0)
	s_setprio 1
	s_waitcnt lgkmcnt(0)
	v_mfma_f32_16x16x32_bf16 v[112:115], v[176:179], v[144:147], v[112:115]
	v_mfma_f32_16x16x32_bf16 v[108:111], v[184:187], v[144:147], v[108:111]
	v_mfma_f32_16x16x32_bf16 v[100:103], v[176:179], v[152:155], v[100:103]
	v_mfma_f32_16x16x32_bf16 v[92:95], v[184:187], v[152:155], v[92:95]
	v_mfma_f32_16x16x32_bf16 v[84:87], v[176:179], v[160:163], v[84:87]
	v_mfma_f32_16x16x32_bf16 v[76:79], v[184:187], v[160:163], v[76:79]
	v_mfma_f32_16x16x32_bf16 v[68:71], v[176:179], v[168:171], v[68:71]
	v_mfma_f32_16x16x32_bf16 v[64:67], v[184:187], v[168:171], v[64:67]
	v_mfma_f32_16x16x32_bf16 v[112:115], v[180:183], v[148:151], v[112:115]
	v_mfma_f32_16x16x32_bf16 v[108:111], v[188:191], v[148:151], v[108:111]
	v_mfma_f32_16x16x32_bf16 v[100:103], v[180:183], v[156:159], v[100:103]
	v_mfma_f32_16x16x32_bf16 v[92:95], v[188:191], v[156:159], v[92:95]
	v_mfma_f32_16x16x32_bf16 v[84:87], v[180:183], v[164:167], v[84:87]
	v_mfma_f32_16x16x32_bf16 v[76:79], v[188:191], v[164:167], v[76:79]
	v_mfma_f32_16x16x32_bf16 v[68:71], v[180:183], v[172:175], v[68:71]
	s_barrier
	v_mfma_f32_16x16x32_bf16 v[64:67], v[188:191], v[172:175], v[64:67]
	s_setprio 0
	s_mov_b32 m0, s36
	s_add_u32 s100, s28, 0x80
	s_addc_u32 s101, s29, 0
	ds_read_b128 v[144:147], v224 offset:16384
	ds_read_b128 v[148:151], v224 offset:17408
	ds_read_b128 v[152:155], v224 offset:18432
	ds_read_b128 v[156:159], v224 offset:19456
	ds_read_b128 v[160:163], v224 offset:20480
	ds_read_b128 v[164:167], v224 offset:21504
	ds_read_b128 v[168:171], v224 offset:22528
	ds_read_b128 v[172:175], v224 offset:23552
	global_load_lds_dwordx4 v192, s[28:29]
	s_mov_b32 m0, s37
	s_nop 0
	global_load_lds_dwordx4 v196, s[28:29]
	s_waitcnt vmcnt(10)
	s_barrier
	s_waitcnt lgkmcnt(0)
	s_setprio 1
	s_waitcnt lgkmcnt(0)
	v_mfma_f32_16x16x32_bf16 v[60:63], v[128:131], v[144:147], v[60:63]
	v_mfma_f32_16x16x32_bf16 v[56:59], v[136:139], v[144:147], v[56:59]
	v_mfma_f32_16x16x32_bf16 v[48:51], v[128:131], v[152:155], v[48:51]
	v_mfma_f32_16x16x32_bf16 v[40:43], v[136:139], v[152:155], v[40:43]
	v_mfma_f32_16x16x32_bf16 v[32:35], v[128:131], v[160:163], v[32:35]
	v_mfma_f32_16x16x32_bf16 v[24:27], v[136:139], v[160:163], v[24:27]
	v_mfma_f32_16x16x32_bf16 v[16:19], v[128:131], v[168:171], v[16:19]
	v_mfma_f32_16x16x32_bf16 v[8:11], v[136:139], v[168:171], v[8:11]
	v_mfma_f32_16x16x32_bf16 v[60:63], v[132:135], v[148:151], v[60:63]
	v_mfma_f32_16x16x32_bf16 v[56:59], v[140:143], v[148:151], v[56:59]
	v_mfma_f32_16x16x32_bf16 v[48:51], v[132:135], v[156:159], v[48:51]
	v_mfma_f32_16x16x32_bf16 v[40:43], v[140:143], v[156:159], v[40:43]
	v_mfma_f32_16x16x32_bf16 v[32:35], v[132:135], v[164:167], v[32:35]
	v_mfma_f32_16x16x32_bf16 v[24:27], v[140:143], v[164:167], v[24:27]
	v_mfma_f32_16x16x32_bf16 v[16:19], v[132:135], v[172:175], v[16:19]
	s_barrier
; #define PG8_STAGE(bufoff, gbase, voff) do { _Pragma("unroll") for (int _i = 0; _i < 2; ++_i) \
;         __builtin_amdgcn_global_load_lds((const unsigned*)((const char*)(gbase) + (voff)[_i]), (LAS unsigned*)(lds + (bufoff) + ldsw + _i * 8192), 16, 0, 0); } while (0)
; #define PG8_LDA(dst, b, h) do { _Pragma("unroll") for (int m = 0; m < 4; ++m) _Pragma("unroll") for (int k = 0; k < 2; ++k) dst[m][k] = *(const LAS bf16x8*)(lds + PG8_SA(b, h) + aoff + m * 2048 + k * 1024); } while (0)
; #define PG8_LDB(dst, b, h) do { _Pragma("unroll") for (int n = 0; n < 2; ++n) _Pragma("unroll") for (int k = 0; k < 2; ++k) dst[n][k] = *(const LAS bf16x8*)(lds + PG8_SB(b, h) + boff + n * 2048 + k * 1024); } while (0)
; #define PG8_MMA(ai, bj, At, Bt) do { __builtin_amdgcn_s_setprio(1); _Pragma("unroll") for (int m = 0; m < 4; ++m) _Pragma("unroll") for (int n = 0; n < 2; ++n) _Pragma("unroll") for (int k = 0; k < 2; ++k) \
;         acc[ai][bj][m][n] = __builtin_amdgcn_mfma_f32_16x16x32_bf16(Bt[n][k], At[m][k], acc[ai][bj][m][n], 0, 0, 0); __builtin_amdgcn_s_setprio(0); } while (0)
; #define PG8_WAIT_V(n) asm volatile("s_waitcnt vmcnt(" #n ")" ::: "memory")
; #define PG8_WAIT_L(n) asm volatile("s_waitcnt lgkmcnt(" #n ")" ::: "memory")
; #define PG8_BAR __builtin_amdgcn_s_barrier()
; #define PG8_SCHED __builtin_amdgcn_sched_barrier(0)
; template <class Epi>
; __device__ __forceinline__ void gemm_phase(ldsp lds, const Gemm g, const StaticOrder& S, const Epi& E) {
;     ...
;             PG8_WAIT_V(10); PG8_BAR; PG8_WAIT_L(0); PG8_MMA(1, 0, At, B0); PG8_BAR; PG8_SCHED;
;             PG8_STAGE(PG8_SB(0, 1), b2 + hstep, voffB);
;             PG8_WAIT_V(10); PG8_BAR; PG8_MMA(1, 1, At, B1); PG8_BAR;
;             PG8_LDB(B0, 1, 0); PG8_SCHED; PG8_LDA(At, 1, 0); PG8_STAGE(PG8_SA(0, 1), a2 + hstep, voffA);
;             PG8_WAIT_L(8); PG8_WAIT_V(10); PG8_BAR; PG8_WAIT_L(0); PG8_MMA(0, 0, At, B0); PG8_BAR; PG8_SCHED;
;             PG8_LDB(B1, 1, 1); PG8_STAGE(PG8_SB(1, 0), b3, voffB);
;             PG8_WAIT_V(10); PG8_BAR; PG8_WAIT_L(0); PG8_MMA(0, 1, At, B1); PG8_BAR;
	v_mfma_f32_16x16x32_bf16 v[8:11], v[140:143], v[172:175], v[8:11]
	s_setprio 0
	s_add_u32 s54, s26, 0x60000
	s_addc_u32 s55, s27, 0
	s_add_i32 s56, s46, s35
	s_mov_b32 m0, s56
	s_nop 0
	global_load_lds_dwordx4 v194, s[54:55]
	s_add_i32 m0, s56, 0x2000
	s_nop 0
	global_load_lds_dwordx4 v198, s[54:55]
	s_waitcnt vmcnt(10)
	s_barrier
	s_nop 3
	s_setprio 1
	v_mfma_f32_16x16x32_bf16 v[52:55], v[176:179], v[144:147], v[52:55]
	v_mfma_f32_16x16x32_bf16 v[44:47], v[184:187], v[144:147], v[44:47]
	v_mfma_f32_16x16x32_bf16 v[36:39], v[176:179], v[152:155], v[36:39]
	v_mfma_f32_16x16x32_bf16 v[28:31], v[184:187], v[152:155], v[28:31]
	v_mfma_f32_16x16x32_bf16 v[20:23], v[176:179], v[160:163], v[20:23]
	v_mfma_f32_16x16x32_bf16 v[12:15], v[184:187], v[160:163], v[12:15]
	v_mfma_f32_16x16x32_bf16 v[4:7], v[176:179], v[168:171], v[4:7]
	v_mfma_f32_16x16x32_bf16 v[0:3], v[184:187], v[168:171], v[0:3]
	v_mfma_f32_16x16x32_bf16 v[52:55], v[180:183], v[148:151], v[52:55]
	v_mfma_f32_16x16x32_bf16 v[44:47], v[188:191], v[148:151], v[44:47]
	v_mfma_f32_16x16x32_bf16 v[36:39], v[180:183], v[156:159], v[36:39]
	v_mfma_f32_16x16x32_bf16 v[28:31], v[188:191], v[156:159], v[28:31]
	v_mfma_f32_16x16x32_bf16 v[20:23], v[180:183], v[164:167], v[20:23]
	v_mfma_f32_16x16x32_bf16 v[12:15], v[188:191], v[164:167], v[12:15]
	v_mfma_f32_16x16x32_bf16 v[4:7], v[180:183], v[172:175], v[4:7]
	s_barrier
	v_mfma_f32_16x16x32_bf16 v[0:3], v[188:191], v[172:175], v[0:3]
	s_setprio 0
	s_add_i32 s54, 0, 0x18000
	ds_read_b128 v[128:131], v247 offset:32768
	ds_read_b128 v[132:135], v247 offset:33792
	ds_read_b128 v[136:139], v247 offset:34816
	ds_read_b128 v[140:143], v247 offset:35840
	s_add_u32 s28, s28, 0x60000
	s_addc_u32 s29, s29, 0
	s_mov_b32 m0, s38
	ds_read_b128 v[144:147], v224 offset:32768
	ds_read_b128 v[148:151], v224 offset:33792
	ds_read_b128 v[152:155], v224 offset:34816
	ds_read_b128 v[156:159], v224 offset:35840
	ds_read_b128 v[160:163], v224 offset:36864
	ds_read_b128 v[164:167], v224 offset:37888
	ds_read_b128 v[168:171], v224 offset:38912
	ds_read_b128 v[172:175], v224 offset:39936
	global_load_lds_dwordx4 v192, s[28:29]
	s_mov_b32 m0, s39
	s_nop 0
	global_load_lds_dwordx4 v196, s[28:29]
	s_waitcnt lgkmcnt(8)
	s_waitcnt vmcnt(10)
	s_barrier
	s_waitcnt lgkmcnt(0)
	s_setprio 1
	s_waitcnt lgkmcnt(0)
	v_mfma_f32_16x16x32_bf16 v[124:127], v[128:131], v[144:147], v[124:127]
	v_mfma_f32_16x16x32_bf16 v[120:123], v[136:139], v[144:147], v[120:123]
	v_mfma_f32_16x16x32_bf16 v[116:119], v[128:131], v[152:155], v[116:119]
	v_mfma_f32_16x16x32_bf16 v[104:107], v[136:139], v[152:155], v[104:107]
	v_mfma_f32_16x16x32_bf16 v[96:99], v[128:131], v[160:163], v[96:99]
	v_mfma_f32_16x16x32_bf16 v[88:91], v[136:139], v[160:163], v[88:91]
	v_mfma_f32_16x16x32_bf16 v[80:83], v[128:131], v[168:171], v[80:83]
	v_mfma_f32_16x16x32_bf16 v[72:75], v[136:139], v[168:171], v[72:75]
	v_mfma_f32_16x16x32_bf16 v[124:127], v[132:135], v[148:151], v[124:127]
	v_mfma_f32_16x16x32_bf16 v[120:123], v[140:143], v[148:151], v[120:123]
	v_mfma_f32_16x16x32_bf16 v[116:119], v[132:135], v[156:159], v[116:119]
	v_mfma_f32_16x16x32_bf16 v[104:107], v[140:143], v[156:159], v[104:107]
	v_mfma_f32_16x16x32_bf16 v[96:99], v[132:135], v[164:167], v[96:99]
	v_mfma_f32_16x16x32_bf16 v[88:91], v[140:143], v[164:167], v[88:91]
	v_mfma_f32_16x16x32_bf16 v[80:83], v[132:135], v[172:175], v[80:83]
	s_barrier
	v_mfma_f32_16x16x32_bf16 v[72:75], v[140:143], v[172:175], v[72:75]
	s_setprio 0
	s_add_i32 s28, 0, 0x1c000
	s_add_i32 s29, s54, s35
	s_mov_b32 m0, s29
	ds_read_b128 v[176:179], v247 offset:49152
	ds_read_b128 v[180:183], v247 offset:50176
	ds_read_b128 v[184:187], v247 offset:51200
	ds_read_b128 v[188:191], v247 offset:52224
	global_load_lds_dwordx4 v194, s[98:99]
	s_add_i32 m0, s29, 0x2000
	s_nop 0
	global_load_lds_dwordx4 v198, s[98:99]
	s_waitcnt vmcnt(10)
	s_barrier
; #define PG8_STAGE(bufoff, gbase, voff) do { _Pragma("unroll") for (int _i = 0; _i < 2; ++_i) \
;         __builtin_amdgcn_global_load_lds((const unsigned*)((const char*)(gbase) + (voff)[_i]), (LAS unsigned*)(lds + (bufoff) + ldsw + _i * 8192), 16, 0, 0); } while (0)
; #define PG8_LDA(dst, b, h) do { _Pragma("unroll") for (int m = 0; m < 4; ++m) _Pragma("unroll") for (int k = 0; k < 2; ++k) dst[m][k] = *(const LAS bf16x8*)(lds + PG8_SA(b, h) + aoff + m * 2048 + k * 1024); } while (0)
; #define PG8_MMA(ai, bj, At, Bt) do { __builtin_amdgcn_s_setprio(1); _Pragma("unroll") for (int m = 0; m < 4; ++m) _Pragma("unroll") for (int n = 0; n < 2; ++n) _Pragma("unroll") for (int k = 0; k < 2; ++k) \
;         acc[ai][bj][m][n] = __builtin_amdgcn_mfma_f32_16x16x32_bf16(Bt[n][k], At[m][k], acc[ai][bj][m][n], 0, 0, 0); __builtin_amdgcn_s_setprio(0); } while (0)
; #define PG8_WAIT_V(n) asm volatile("s_waitcnt vmcnt(" #n ")" ::: "memory")
; #define PG8_WAIT_L(n) asm volatile("s_waitcnt lgkmcnt(" #n ")" ::: "memory")
; #define PG8_BAR __builtin_amdgcn_s_barrier()
; #define PG8_SCHED __builtin_amdgcn_sched_barrier(0)
; template <class Epi>
; __device__ __forceinline__ void gemm_phase(ldsp lds, const Gemm g, const StaticOrder& S, const Epi& E) {
;     ...
;             PG8_WAIT_V(10); PG8_BAR; PG8_WAIT_L(0); PG8_MMA(0, 1, At, B1); PG8_BAR;
;             PG8_LDA(At, 1, 1); PG8_STAGE(PG8_SA(1, 0), a3, voffA);
;             PG8_WAIT_V(10); PG8_BAR; PG8_WAIT_L(0); PG8_MMA(1, 0, At, B0); PG8_BAR; PG8_SCHED;
;             PG8_STAGE(PG8_SB(1, 1), b3 + hstep, voffB);
;             PG8_WAIT_V(10); PG8_BAR; PG8_MMA(1, 1, At, B1); PG8_BAR;
	s_waitcnt lgkmcnt(0)
	s_setprio 1
	s_waitcnt lgkmcnt(0)
	v_mfma_f32_16x16x32_bf16 v[112:115], v[176:179], v[144:147], v[112:115]
	v_mfma_f32_16x16x32_bf16 v[108:111], v[184:187], v[144:147], v[108:111]
	v_mfma_f32_16x16x32_bf16 v[100:103], v[176:179], v[152:155], v[100:103]
	v_mfma_f32_16x16x32_bf16 v[92:95], v[184:187], v[152:155], v[92:95]
	v_mfma_f32_16x16x32_bf16 v[84:87], v[176:179], v[160:163], v[84:87]
	v_mfma_f32_16x16x32_bf16 v[76:79], v[184:187], v[160:163], v[76:79]
	v_mfma_f32_16x16x32_bf16 v[68:71], v[176:179], v[168:171], v[68:71]
	v_mfma_f32_16x16x32_bf16 v[64:67], v[184:187], v[168:171], v[64:67]
	v_mfma_f32_16x16x32_bf16 v[112:115], v[180:183], v[148:151], v[112:115]
	v_mfma_f32_16x16x32_bf16 v[108:111], v[188:191], v[148:151], v[108:111]
	v_mfma_f32_16x16x32_bf16 v[100:103], v[180:183], v[156:159], v[100:103]
	v_mfma_f32_16x16x32_bf16 v[92:95], v[188:191], v[156:159], v[92:95]
	v_mfma_f32_16x16x32_bf16 v[84:87], v[180:183], v[164:167], v[84:87]
	v_mfma_f32_16x16x32_bf16 v[76:79], v[188:191], v[164:167], v[76:79]
	v_mfma_f32_16x16x32_bf16 v[68:71], v[180:183], v[172:175], v[68:71]
	s_barrier
	v_mfma_f32_16x16x32_bf16 v[64:67], v[188:191], v[172:175], v[64:67]
	s_setprio 0
	s_mov_b32 m0, s41
	ds_read_b128 v[144:147], v224 offset:49152
	ds_read_b128 v[148:151], v224 offset:50176
	ds_read_b128 v[152:155], v224 offset:51200
	ds_read_b128 v[156:159], v224 offset:52224
	ds_read_b128 v[160:163], v224 offset:53248
	ds_read_b128 v[164:167], v224 offset:54272
	ds_read_b128 v[168:171], v224 offset:55296
	ds_read_b128 v[172:175], v224 offset:56320
	global_load_lds_dwordx4 v192, s[100:101]
	s_mov_b32 m0, s42
	s_nop 0
	global_load_lds_dwordx4 v196, s[100:101]
	s_waitcnt vmcnt(10)
	s_barrier
	s_waitcnt lgkmcnt(0)
	s_setprio 1
	s_waitcnt lgkmcnt(0)
	v_mfma_f32_16x16x32_bf16 v[60:63], v[128:131], v[144:147], v[60:63]
	v_mfma_f32_16x16x32_bf16 v[56:59], v[136:139], v[144:147], v[56:59]
	v_mfma_f32_16x16x32_bf16 v[48:51], v[128:131], v[152:155], v[48:51]
	v_mfma_f32_16x16x32_bf16 v[40:43], v[136:139], v[152:155], v[40:43]
	v_mfma_f32_16x16x32_bf16 v[32:35], v[128:131], v[160:163], v[32:35]
	v_mfma_f32_16x16x32_bf16 v[24:27], v[136:139], v[160:163], v[24:27]
	v_mfma_f32_16x16x32_bf16 v[16:19], v[128:131], v[168:171], v[16:19]
	v_mfma_f32_16x16x32_bf16 v[8:11], v[136:139], v[168:171], v[8:11]
	v_mfma_f32_16x16x32_bf16 v[60:63], v[132:135], v[148:151], v[60:63]
	v_mfma_f32_16x16x32_bf16 v[56:59], v[140:143], v[148:151], v[56:59]
	v_mfma_f32_16x16x32_bf16 v[48:51], v[132:135], v[156:159], v[48:51]
	v_mfma_f32_16x16x32_bf16 v[40:43], v[140:143], v[156:159], v[40:43]
	v_mfma_f32_16x16x32_bf16 v[32:35], v[132:135], v[164:167], v[32:35]
	v_mfma_f32_16x16x32_bf16 v[24:27], v[140:143], v[164:167], v[24:27]
	v_mfma_f32_16x16x32_bf16 v[16:19], v[132:135], v[172:175], v[16:19]
	s_barrier
	v_mfma_f32_16x16x32_bf16 v[8:11], v[140:143], v[172:175], v[8:11]
	s_setprio 0
	s_add_u32 s26, s26, 0x60080
	s_addc_u32 s27, s27, 0
	s_add_i32 s28, s28, s35
	s_mov_b32 m0, s28
	s_nop 0
	global_load_lds_dwordx4 v194, s[26:27]
	s_add_i32 m0, s28, 0x2000
	s_nop 0
	global_load_lds_dwordx4 v198, s[26:27]
	s_waitcnt vmcnt(10)
	s_barrier
	s_nop 3
	s_setprio 1
	v_mfma_f32_16x16x32_bf16 v[52:55], v[176:179], v[144:147], v[52:55]
	v_mfma_f32_16x16x32_bf16 v[44:47], v[184:187], v[144:147], v[44:47]
	v_mfma_f32_16x16x32_bf16 v[36:39], v[176:179], v[152:155], v[36:39]
	v_mfma_f32_16x16x32_bf16 v[28:31], v[184:187], v[152:155], v[28:31]
	v_mfma_f32_16x16x32_bf16 v[20:23], v[176:179], v[160:163], v[20:23]
	v_mfma_f32_16x16x32_bf16 v[12:15], v[184:187], v[160:163], v[12:15]
	v_mfma_f32_16x16x32_bf16 v[4:7], v[176:179], v[168:171], v[4:7]
	v_mfma_f32_16x16x32_bf16 v[0:3], v[184:187], v[168:171], v[0:3]
	v_mfma_f32_16x16x32_bf16 v[52:55], v[180:183], v[148:151], v[52:55]
	v_mfma_f32_16x16x32_bf16 v[44:47], v[188:191], v[148:151], v[44:47]
	v_mfma_f32_16x16x32_bf16 v[36:39], v[180:183], v[156:159], v[36:39]
	v_mfma_f32_16x16x32_bf16 v[28:31], v[188:191], v[156:159], v[28:31]
	v_mfma_f32_16x16x32_bf16 v[20:23], v[180:183], v[164:167], v[20:23]
	v_mfma_f32_16x16x32_bf16 v[12:15], v[188:191], v[164:167], v[12:15]
	v_mfma_f32_16x16x32_bf16 v[4:7], v[180:183], v[172:175], v[4:7]
	s_barrier
	v_mfma_f32_16x16x32_bf16 v[0:3], v[188:191], v[172:175], v[0:3]
	s_setprio 0
	s_add_i32 s53, s53, 2
	s_add_u32 s24, s24, 0x100
	s_addc_u32 s25, s25, 0
	s_cmp_gt_u32 s53, 21
	s_cbranch_scc1 .LBB0_642

; #define PG8_STAGE(bufoff, gbase, voff) do { _Pragma("unroll") for (int _i = 0; _i < 2; ++_i) \
;         __builtin_amdgcn_global_load_lds((const unsigned*)((const char*)(gbase) + (voff)[_i]), (LAS unsigned*)(lds + (bufoff) + ldsw + _i * 8192), 16, 0, 0); } while (0)
; #define PG8_LDA(dst, b, h) do { _Pragma("unroll") for (int m = 0; m < 4; ++m) _Pragma("unroll") for (int k = 0; k < 2; ++k) dst[m][k] = *(const LAS bf16x8*)(lds + PG8_SA(b, h) + aoff + m * 2048 + k * 1024); } while (0)
; #define PG8_LDB(dst, b, h) do { _Pragma("unroll") for (int n = 0; n < 2; ++n) _Pragma("unroll") for (int k = 0; k < 2; ++k) dst[n][k] = *(const LAS bf16x8*)(lds + PG8_SB(b, h) + boff + n * 2048 + k * 1024); } while (0)
; #define PG8_MMA(ai, bj, At, Bt) do { __builtin_amdgcn_s_setprio(1); _Pragma("unroll") for (int m = 0; m < 4; ++m) _Pragma("unroll") for (int n = 0; n < 2; ++n) _Pragma("unroll") for (int k = 0; k < 2; ++k) \
;         acc[ai][bj][m][n] = __builtin_amdgcn_mfma_f32_16x16x32_bf16(Bt[n][k], At[m][k], acc[ai][bj][m][n], 0, 0, 0); __builtin_amdgcn_s_setprio(0); } while (0)
; #define PG8_WAIT_V(n) asm volatile("s_waitcnt vmcnt(" #n ")" ::: "memory")
; #define PG8_BAR __builtin_amdgcn_s_barrier()
; template <class Epi>
; __device__ __forceinline__ void gemm_phase(ldsp lds, const Gemm g, const StaticOrder& S, const Epi& E) {
;     ...
;             const bool last = (t == nt - 2);
;             const char* a1 = cA + (size_t)(t + 1) * kstep;
;             const char* a2 = last ? nA : cA + (size_t)(t + 2) * kstep; const char* b2 = last ? nB : cB + (size_t)(t + 2) * kstep;
;             const char* a3 = a2 + kstep; const char* b3 = b2 + kstep;
;             if constexpr (Epi::NPRE > 0) { if (last) E.pre(pre, cur, wr, fr); }
;             if constexpr (Epi::MID_T > 0) { if (t == Epi::MID_T) E.mid(acc, cur, wr, wc, fr, fq); }
;             PG8_LDB(B0, 0, 0); PG8_SCHED; PG8_LDA(At, 0, 0); PG8_STAGE(PG8_SA(1, 1), a1 + hstep, voffA);
;             PG8_WAIT_L(8); PG8_WAIT_V(10); PG8_BAR; PG8_WAIT_L(0); PG8_MMA(0, 0, At, B0); PG8_BAR; PG8_SCHED;
;             PG8_LDB(B1, 0, 1); PG8_STAGE(PG8_SB(0, 0), b2, voffB);
;             PG8_WAIT_V(10); PG8_BAR; PG8_WAIT_L(0); PG8_MMA(0, 1, At, B1); PG8_BAR;
;             PG8_LDA(At, 0, 1); PG8_STAGE(PG8_SA(0, 0), a2, voffA);
;             PG8_WAIT_V(10); PG8_BAR; PG8_WAIT_L(0); PG8_MMA(1, 0, At, B0); PG8_BAR; PG8_SCHED;
.LBB0_733:
	ds_read_b128 v[128:131], v211
	ds_read_b128 v[132:135], v211 offset:1024
	ds_read_b128 v[136:139], v211 offset:2048
	ds_read_b128 v[140:143], v211 offset:3072
	s_add_u32 s24, s22, 0xfff80080
	s_addc_u32 s25, s23, -1
	s_cmp_eq_u32 s46, 28
	s_cselect_b32 s27, s13, s25
	s_cselect_b32 s26, s19, s24
	s_cselect_b32 s25, s11, s45
	s_cselect_b32 s24, s43, s44
	s_add_i32 m0, s21, 0xc000
	ds_read_b128 v[144:147], v212
	ds_read_b128 v[148:151], v212 offset:1024
	ds_read_b128 v[152:155], v212 offset:2048
	ds_read_b128 v[156:159], v212 offset:3072
	ds_read_b128 v[160:163], v212 offset:4096
	ds_read_b128 v[164:167], v212 offset:5120
	ds_read_b128 v[168:171], v212 offset:6144
	ds_read_b128 v[172:175], v212 offset:7168
	global_load_lds_dwordx4 v184, s[22:23]
	s_add_i32 m0, s21, 0xe000
	s_nop 0
	global_load_lds_dwordx4 v186, s[22:23]
	s_waitcnt lgkmcnt(8)
	s_waitcnt vmcnt(10)
	s_barrier
	s_waitcnt lgkmcnt(0)
	s_setprio 1
	s_waitcnt lgkmcnt(0)
	v_mfma_f32_16x16x32_bf16 v[124:127], v[128:131], v[144:147], v[124:127]
	v_mfma_f32_16x16x32_bf16 v[120:123], v[136:139], v[144:147], v[120:123]
	v_mfma_f32_16x16x32_bf16 v[108:111], v[128:131], v[152:155], v[108:111]
	v_mfma_f32_16x16x32_bf16 v[104:107], v[136:139], v[152:155], v[104:107]
	v_mfma_f32_16x16x32_bf16 v[92:95], v[128:131], v[160:163], v[92:95]
	v_mfma_f32_16x16x32_bf16 v[88:91], v[136:139], v[160:163], v[88:91]
	v_mfma_f32_16x16x32_bf16 v[76:79], v[128:131], v[168:171], v[76:79]
	v_mfma_f32_16x16x32_bf16 v[72:75], v[136:139], v[168:171], v[72:75]
	v_mfma_f32_16x16x32_bf16 v[124:127], v[132:135], v[148:151], v[124:127]
	v_mfma_f32_16x16x32_bf16 v[120:123], v[140:143], v[148:151], v[120:123]
	v_mfma_f32_16x16x32_bf16 v[108:111], v[132:135], v[156:159], v[108:111]
	v_mfma_f32_16x16x32_bf16 v[104:107], v[140:143], v[156:159], v[104:107]
	v_mfma_f32_16x16x32_bf16 v[92:95], v[132:135], v[164:167], v[92:95]
	v_mfma_f32_16x16x32_bf16 v[88:91], v[140:143], v[164:167], v[88:91]
	v_mfma_f32_16x16x32_bf16 v[76:79], v[132:135], v[172:175], v[76:79]
	s_barrier
	v_mfma_f32_16x16x32_bf16 v[72:75], v[140:143], v[172:175], v[72:75]
	s_setprio 0
	s_add_i32 s47, s40, s29
	s_add_u32 s98, s24, 0x80
	s_addc_u32 s99, s25, 0
	s_mov_b32 m0, s47
	ds_read_b128 v[192:195], v213
	ds_read_b128 v[196:199], v213 offset:1024
	ds_read_b128 v[200:203], v213 offset:2048
	ds_read_b128 v[204:207], v213 offset:3072
	global_load_lds_dwordx4 v178, s[24:25]
	s_add_i32 m0, s47, 0x2000
	s_nop 0
	global_load_lds_dwordx4 v182, s[24:25]
	s_waitcnt vmcnt(10)
	s_barrier
	s_waitcnt lgkmcnt(0)
	s_setprio 1
	s_waitcnt lgkmcnt(0)
	v_mfma_f32_16x16x32_bf16 v[116:119], v[192:195], v[144:147], v[116:119]
	v_mfma_f32_16x16x32_bf16 v[112:115], v[200:203], v[144:147], v[112:115]
	v_mfma_f32_16x16x32_bf16 v[100:103], v[192:195], v[152:155], v[100:103]
	v_mfma_f32_16x16x32_bf16 v[96:99], v[200:203], v[152:155], v[96:99]
	v_mfma_f32_16x16x32_bf16 v[84:87], v[192:195], v[160:163], v[84:87]
	v_mfma_f32_16x16x32_bf16 v[80:83], v[200:203], v[160:163], v[80:83]
	v_mfma_f32_16x16x32_bf16 v[68:71], v[192:195], v[168:171], v[68:71]
	v_mfma_f32_16x16x32_bf16 v[64:67], v[200:203], v[168:171], v[64:67]
	v_mfma_f32_16x16x32_bf16 v[116:119], v[196:199], v[148:151], v[116:119]
	v_mfma_f32_16x16x32_bf16 v[112:115], v[204:207], v[148:151], v[112:115]
	v_mfma_f32_16x16x32_bf16 v[100:103], v[196:199], v[156:159], v[100:103]
	v_mfma_f32_16x16x32_bf16 v[96:99], v[204:207], v[156:159], v[96:99]
	v_mfma_f32_16x16x32_bf16 v[84:87], v[196:199], v[164:167], v[84:87]
	v_mfma_f32_16x16x32_bf16 v[80:83], v[204:207], v[164:167], v[80:83]
	v_mfma_f32_16x16x32_bf16 v[68:71], v[196:199], v[172:175], v[68:71]
	s_barrier
	v_mfma_f32_16x16x32_bf16 v[64:67], v[204:207], v[172:175], v[64:67]
	s_setprio 0
	s_mov_b32 m0, s21
	s_add_u32 s100, s26, 0x80
	s_addc_u32 s101, s27, 0
	ds_read_b128 v[144:147], v212 offset:16384
	ds_read_b128 v[148:151], v212 offset:17408
	ds_read_b128 v[152:155], v212 offset:18432
	ds_read_b128 v[156:159], v212 offset:19456
	ds_read_b128 v[160:163], v212 offset:20480
	ds_read_b128 v[164:167], v212 offset:21504
	ds_read_b128 v[168:171], v212 offset:22528
	ds_read_b128 v[172:175], v212 offset:23552
	global_load_lds_dwordx4 v176, s[26:27]
	s_mov_b32 m0, s30
	s_nop 0
	global_load_lds_dwordx4 v180, s[26:27]
	s_waitcnt vmcnt(10)
	s_barrier
	s_waitcnt lgkmcnt(0)
	s_setprio 1
	s_waitcnt lgkmcnt(0)
	v_mfma_f32_16x16x32_bf16 v[60:63], v[128:131], v[144:147], v[60:63]
	v_mfma_f32_16x16x32_bf16 v[56:59], v[136:139], v[144:147], v[56:59]
	v_mfma_f32_16x16x32_bf16 v[44:47], v[128:131], v[152:155], v[44:47]
	v_mfma_f32_16x16x32_bf16 v[40:43], v[136:139], v[152:155], v[40:43]
	v_mfma_f32_16x16x32_bf16 v[28:31], v[128:131], v[160:163], v[28:31]
	v_mfma_f32_16x16x32_bf16 v[24:27], v[136:139], v[160:163], v[24:27]
	v_mfma_f32_16x16x32_bf16 v[12:15], v[128:131], v[168:171], v[12:15]
	v_mfma_f32_16x16x32_bf16 v[8:11], v[136:139], v[168:171], v[8:11]
	v_mfma_f32_16x16x32_bf16 v[60:63], v[132:135], v[148:151], v[60:63]
	v_mfma_f32_16x16x32_bf16 v[56:59], v[140:143], v[148:151], v[56:59]
	v_mfma_f32_16x16x32_bf16 v[44:47], v[132:135], v[156:159], v[44:47]
	v_mfma_f32_16x16x32_bf16 v[40:43], v[140:143], v[156:159], v[40:43]
	v_mfma_f32_16x16x32_bf16 v[28:31], v[132:135], v[164:167], v[28:31]
	v_mfma_f32_16x16x32_bf16 v[24:27], v[140:143], v[164:167], v[24:27]
	v_mfma_f32_16x16x32_bf16 v[12:15], v[132:135], v[172:175], v[12:15]
	s_barrier
	v_mfma_f32_16x16x32_bf16 v[8:11], v[140:143], v[172:175], v[8:11]
	s_setprio 0
	s_add_u32 s50, s24, 0x80000
	s_addc_u32 s51, s25, 0
	s_add_i32 s47, s41, s29
	s_mov_b32 m0, s47
	s_nop 0
	global_load_lds_dwordx4 v178, s[50:51]
	s_add_i32 m0, s47, 0x2000
	s_nop 0
	global_load_lds_dwordx4 v182, s[50:51]
	s_waitcnt vmcnt(10)
	s_barrier
; #define PG8_STAGE(bufoff, gbase, voff) do { _Pragma("unroll") for (int _i = 0; _i < 2; ++_i) \
;         __builtin_amdgcn_global_load_lds((const unsigned*)((const char*)(gbase) + (voff)[_i]), (LAS unsigned*)(lds + (bufoff) + ldsw + _i * 8192), 16, 0, 0); } while (0)
; #define PG8_LDA(dst, b, h) do { _Pragma("unroll") for (int m = 0; m < 4; ++m) _Pragma("unroll") for (int k = 0; k < 2; ++k) dst[m][k] = *(const LAS bf16x8*)(lds + PG8_SA(b, h) + aoff + m * 2048 + k * 1024); } while (0)
; #define PG8_LDB(dst, b, h) do { _Pragma("unroll") for (int n = 0; n < 2; ++n) _Pragma("unroll") for (int k = 0; k < 2; ++k) dst[n][k] = *(const LAS bf16x8*)(lds + PG8_SB(b, h) + boff + n * 2048 + k * 1024); } while (0)
; #define PG8_MMA(ai, bj, At, Bt) do { __builtin_amdgcn_s_setprio(1); _Pragma("unroll") for (int m = 0; m < 4; ++m) _Pragma("unroll") for (int n = 0; n < 2; ++n) _Pragma("unroll") for (int k = 0; k < 2; ++k) \
;         acc[ai][bj][m][n] = __builtin_amdgcn_mfma_f32_16x16x32_bf16(Bt[n][k], At[m][k], acc[ai][bj][m][n], 0, 0, 0); __builtin_amdgcn_s_setprio(0); } while (0)
; #define PG8_WAIT_V(n) asm volatile("s_waitcnt vmcnt(" #n ")" ::: "memory")
; #define PG8_WAIT_L(n) asm volatile("s_waitcnt lgkmcnt(" #n ")" ::: "memory")
; #define PG8_BAR __builtin_amdgcn_s_barrier()
; #define PG8_SCHED __builtin_amdgcn_sched_barrier(0)
; template <class Epi>
; __device__ __forceinline__ void gemm_phase(ldsp lds, const Gemm g, const StaticOrder& S, const Epi& E) {
;     ...
;             PG8_WAIT_V(10); PG8_BAR; PG8_MMA(1, 1, At, B1); PG8_BAR;
;             PG8_LDB(B0, 1, 0); PG8_SCHED; PG8_LDA(At, 1, 0); PG8_STAGE(PG8_SA(0, 1), a2 + hstep, voffA);
;             PG8_WAIT_L(8); PG8_WAIT_V(10); PG8_BAR; PG8_WAIT_L(0); PG8_MMA(0, 0, At, B0); PG8_BAR; PG8_SCHED;
;             PG8_LDB(B1, 1, 1); PG8_STAGE(PG8_SB(1, 0), b3, voffB);
;             PG8_WAIT_V(10); PG8_BAR; PG8_WAIT_L(0); PG8_MMA(0, 1, At, B1); PG8_BAR;
;             PG8_LDA(At, 1, 1); PG8_STAGE(PG8_SA(1, 0), a3, voffA);
;             PG8_WAIT_V(10); PG8_BAR; PG8_WAIT_L(0); PG8_MMA(1, 0, At, B0); PG8_BAR; PG8_SCHED;
	s_nop 3
	s_setprio 1
	v_mfma_f32_16x16x32_bf16 v[52:55], v[192:195], v[144:147], v[52:55]
	v_mfma_f32_16x16x32_bf16 v[48:51], v[200:203], v[144:147], v[48:51]
	v_mfma_f32_16x16x32_bf16 v[36:39], v[192:195], v[152:155], v[36:39]
	v_mfma_f32_16x16x32_bf16 v[32:35], v[200:203], v[152:155], v[32:35]
	v_mfma_f32_16x16x32_bf16 v[20:23], v[192:195], v[160:163], v[20:23]
	v_mfma_f32_16x16x32_bf16 v[16:19], v[200:203], v[160:163], v[16:19]
	v_mfma_f32_16x16x32_bf16 v[4:7], v[192:195], v[168:171], v[4:7]
	v_mfma_f32_16x16x32_bf16 v[0:3], v[200:203], v[168:171], v[0:3]
	v_mfma_f32_16x16x32_bf16 v[52:55], v[196:199], v[148:151], v[52:55]
	v_mfma_f32_16x16x32_bf16 v[48:51], v[204:207], v[148:151], v[48:51]
	v_mfma_f32_16x16x32_bf16 v[36:39], v[196:199], v[156:159], v[36:39]
	v_mfma_f32_16x16x32_bf16 v[32:35], v[204:207], v[156:159], v[32:35]
	v_mfma_f32_16x16x32_bf16 v[20:23], v[196:199], v[164:167], v[20:23]
	v_mfma_f32_16x16x32_bf16 v[16:19], v[204:207], v[164:167], v[16:19]
	v_mfma_f32_16x16x32_bf16 v[4:7], v[196:199], v[172:175], v[4:7]
	s_barrier
	v_mfma_f32_16x16x32_bf16 v[0:3], v[204:207], v[172:175], v[0:3]
	s_setprio 0
	s_add_i32 s47, 0, 0x18000
	ds_read_b128 v[128:131], v247 offset:32768
	ds_read_b128 v[132:135], v247 offset:33792
	ds_read_b128 v[136:139], v247 offset:34816
	ds_read_b128 v[140:143], v247 offset:35840
	s_add_u32 s26, s26, 0x80000
	s_addc_u32 s27, s27, 0
	s_mov_b32 m0, s31
	ds_read_b128 v[144:147], v212 offset:32768
	ds_read_b128 v[148:151], v212 offset:33792
	ds_read_b128 v[152:155], v212 offset:34816
	ds_read_b128 v[156:159], v212 offset:35840
	ds_read_b128 v[160:163], v212 offset:36864
	ds_read_b128 v[164:167], v212 offset:37888
	ds_read_b128 v[168:171], v212 offset:38912
	ds_read_b128 v[172:175], v212 offset:39936
	global_load_lds_dwordx4 v176, s[26:27]
	s_mov_b32 m0, s33
	s_nop 0
	global_load_lds_dwordx4 v180, s[26:27]
	s_waitcnt lgkmcnt(8)
	s_waitcnt vmcnt(10)
	s_barrier
	s_waitcnt lgkmcnt(0)
	s_setprio 1
	s_waitcnt lgkmcnt(0)
	v_mfma_f32_16x16x32_bf16 v[124:127], v[128:131], v[144:147], v[124:127]
	v_mfma_f32_16x16x32_bf16 v[120:123], v[136:139], v[144:147], v[120:123]
	v_mfma_f32_16x16x32_bf16 v[108:111], v[128:131], v[152:155], v[108:111]
	v_mfma_f32_16x16x32_bf16 v[104:107], v[136:139], v[152:155], v[104:107]
	v_mfma_f32_16x16x32_bf16 v[92:95], v[128:131], v[160:163], v[92:95]
	v_mfma_f32_16x16x32_bf16 v[88:91], v[136:139], v[160:163], v[88:91]
	v_mfma_f32_16x16x32_bf16 v[76:79], v[128:131], v[168:171], v[76:79]
	v_mfma_f32_16x16x32_bf16 v[72:75], v[136:139], v[168:171], v[72:75]
	v_mfma_f32_16x16x32_bf16 v[124:127], v[132:135], v[148:151], v[124:127]
	v_mfma_f32_16x16x32_bf16 v[120:123], v[140:143], v[148:151], v[120:123]
	v_mfma_f32_16x16x32_bf16 v[108:111], v[132:135], v[156:159], v[108:111]
	v_mfma_f32_16x16x32_bf16 v[104:107], v[140:143], v[156:159], v[104:107]
	v_mfma_f32_16x16x32_bf16 v[92:95], v[132:135], v[164:167], v[92:95]
	v_mfma_f32_16x16x32_bf16 v[88:91], v[140:143], v[164:167], v[88:91]
	v_mfma_f32_16x16x32_bf16 v[76:79], v[132:135], v[172:175], v[76:79]
	s_barrier
	v_mfma_f32_16x16x32_bf16 v[72:75], v[140:143], v[172:175], v[72:75]
	s_setprio 0
	s_add_i32 s26, 0, 0x1c000
	s_add_i32 s27, s47, s29
	s_mov_b32 m0, s27
	ds_read_b128 v[192:195], v247 offset:49152
	ds_read_b128 v[196:199], v247 offset:50176
	ds_read_b128 v[200:203], v247 offset:51200
	ds_read_b128 v[204:207], v247 offset:52224
	global_load_lds_dwordx4 v178, s[98:99]
	s_add_i32 m0, s27, 0x2000
	s_nop 0
	global_load_lds_dwordx4 v182, s[98:99]
	s_waitcnt vmcnt(10)
	s_barrier
	s_waitcnt lgkmcnt(0)
	s_setprio 1
	s_waitcnt lgkmcnt(0)
	v_mfma_f32_16x16x32_bf16 v[116:119], v[192:195], v[144:147], v[116:119]
	v_mfma_f32_16x16x32_bf16 v[112:115], v[200:203], v[144:147], v[112:115]
	v_mfma_f32_16x16x32_bf16 v[100:103], v[192:195], v[152:155], v[100:103]
	v_mfma_f32_16x16x32_bf16 v[96:99], v[200:203], v[152:155], v[96:99]
	v_mfma_f32_16x16x32_bf16 v[84:87], v[192:195], v[160:163], v[84:87]
	v_mfma_f32_16x16x32_bf16 v[80:83], v[200:203], v[160:163], v[80:83]
	v_mfma_f32_16x16x32_bf16 v[68:71], v[192:195], v[168:171], v[68:71]
	v_mfma_f32_16x16x32_bf16 v[64:67], v[200:203], v[168:171], v[64:67]
	v_mfma_f32_16x16x32_bf16 v[116:119], v[196:199], v[148:151], v[116:119]
	v_mfma_f32_16x16x32_bf16 v[112:115], v[204:207], v[148:151], v[112:115]
	v_mfma_f32_16x16x32_bf16 v[100:103], v[196:199], v[156:159], v[100:103]
	v_mfma_f32_16x16x32_bf16 v[96:99], v[204:207], v[156:159], v[96:99]
	v_mfma_f32_16x16x32_bf16 v[84:87], v[196:199], v[164:167], v[84:87]
	v_mfma_f32_16x16x32_bf16 v[80:83], v[204:207], v[164:167], v[80:83]
	v_mfma_f32_16x16x32_bf16 v[68:71], v[196:199], v[172:175], v[68:71]
	s_barrier
	v_mfma_f32_16x16x32_bf16 v[64:67], v[204:207], v[172:175], v[64:67]
	s_setprio 0
	s_mov_b32 m0, s35
	ds_read_b128 v[144:147], v212 offset:49152
	ds_read_b128 v[148:151], v212 offset:50176
	ds_read_b128 v[152:155], v212 offset:51200
	ds_read_b128 v[156:159], v212 offset:52224
	ds_read_b128 v[160:163], v212 offset:53248
	ds_read_b128 v[164:167], v212 offset:54272
	ds_read_b128 v[168:171], v212 offset:55296
	ds_read_b128 v[172:175], v212 offset:56320
	global_load_lds_dwordx4 v176, s[100:101]
	s_mov_b32 m0, s36
	s_nop 0
	global_load_lds_dwordx4 v180, s[100:101]
	s_waitcnt vmcnt(10)
	s_barrier
; #define PG8_STAGE(bufoff, gbase, voff) do { _Pragma("unroll") for (int _i = 0; _i < 2; ++_i) \
;         __builtin_amdgcn_global_load_lds((const unsigned*)((const char*)(gbase) + (voff)[_i]), (LAS unsigned*)(lds + (bufoff) + ldsw + _i * 8192), 16, 0, 0); } while (0)
; #define PG8_MMA(ai, bj, At, Bt) do { __builtin_amdgcn_s_setprio(1); _Pragma("unroll") for (int m = 0; m < 4; ++m) _Pragma("unroll") for (int n = 0; n < 2; ++n) _Pragma("unroll") for (int k = 0; k < 2; ++k) \
;         acc[ai][bj][m][n] = __builtin_amdgcn_mfma_f32_16x16x32_bf16(Bt[n][k], At[m][k], acc[ai][bj][m][n], 0, 0, 0); __builtin_amdgcn_s_setprio(0); } while (0)
; #define PG8_WAIT_V(n) asm volatile("s_waitcnt vmcnt(" #n ")" ::: "memory")
; #define PG8_WAIT_L(n) asm volatile("s_waitcnt lgkmcnt(" #n ")" ::: "memory")
; #define PG8_BAR __builtin_amdgcn_s_barrier()
; #define PG8_SCHED __builtin_amdgcn_sched_barrier(0)
; template <class Epi>
; __device__ __forceinline__ void gemm_phase(ldsp lds, const Gemm g, const StaticOrder& S, const Epi& E) {
;     ...
;             PG8_WAIT_V(10); PG8_BAR; PG8_WAIT_L(0); PG8_MMA(1, 0, At, B0); PG8_BAR; PG8_SCHED;
;             PG8_STAGE(PG8_SB(1, 1), b3 + hstep, voffB);
;             PG8_WAIT_V(10); PG8_BAR; PG8_MMA(1, 1, At, B1); PG8_BAR;
	s_waitcnt lgkmcnt(0)
	s_setprio 1
	s_waitcnt lgkmcnt(0)
	v_mfma_f32_16x16x32_bf16 v[60:63], v[128:131], v[144:147], v[60:63]
	v_mfma_f32_16x16x32_bf16 v[56:59], v[136:139], v[144:147], v[56:59]
	v_mfma_f32_16x16x32_bf16 v[44:47], v[128:131], v[152:155], v[44:47]
	v_mfma_f32_16x16x32_bf16 v[40:43], v[136:139], v[152:155], v[40:43]
	v_mfma_f32_16x16x32_bf16 v[28:31], v[128:131], v[160:163], v[28:31]
	v_mfma_f32_16x16x32_bf16 v[24:27], v[136:139], v[160:163], v[24:27]
	v_mfma_f32_16x16x32_bf16 v[12:15], v[128:131], v[168:171], v[12:15]
	v_mfma_f32_16x16x32_bf16 v[8:11], v[136:139], v[168:171], v[8:11]
	v_mfma_f32_16x16x32_bf16 v[60:63], v[132:135], v[148:151], v[60:63]
	v_mfma_f32_16x16x32_bf16 v[56:59], v[140:143], v[148:151], v[56:59]
	v_mfma_f32_16x16x32_bf16 v[44:47], v[132:135], v[156:159], v[44:47]
	v_mfma_f32_16x16x32_bf16 v[40:43], v[140:143], v[156:159], v[40:43]
	v_mfma_f32_16x16x32_bf16 v[28:31], v[132:135], v[164:167], v[28:31]
	v_mfma_f32_16x16x32_bf16 v[24:27], v[140:143], v[164:167], v[24:27]
	v_mfma_f32_16x16x32_bf16 v[12:15], v[132:135], v[172:175], v[12:15]
	s_barrier
	v_mfma_f32_16x16x32_bf16 v[8:11], v[140:143], v[172:175], v[8:11]
	s_setprio 0
	s_add_u32 s24, s24, 0x80080
	s_addc_u32 s25, s25, 0
	s_add_i32 s26, s26, s29
	s_mov_b32 m0, s26
	s_nop 0
	global_load_lds_dwordx4 v178, s[24:25]
	s_add_i32 m0, s26, 0x2000
	s_nop 0
	global_load_lds_dwordx4 v182, s[24:25]
	s_waitcnt vmcnt(10)
	s_barrier
	s_nop 3
	s_setprio 1
	v_mfma_f32_16x16x32_bf16 v[52:55], v[192:195], v[144:147], v[52:55]
	v_mfma_f32_16x16x32_bf16 v[48:51], v[200:203], v[144:147], v[48:51]
	v_mfma_f32_16x16x32_bf16 v[36:39], v[192:195], v[152:155], v[36:39]
	v_mfma_f32_16x16x32_bf16 v[32:35], v[200:203], v[152:155], v[32:35]
	v_mfma_f32_16x16x32_bf16 v[20:23], v[192:195], v[160:163], v[20:23]
	v_mfma_f32_16x16x32_bf16 v[16:19], v[200:203], v[160:163], v[16:19]
	v_mfma_f32_16x16x32_bf16 v[4:7], v[192:195], v[168:171], v[4:7]
	v_mfma_f32_16x16x32_bf16 v[0:3], v[200:203], v[168:171], v[0:3]
	v_mfma_f32_16x16x32_bf16 v[52:55], v[196:199], v[148:151], v[52:55]
	v_mfma_f32_16x16x32_bf16 v[48:51], v[204:207], v[148:151], v[48:51]
	v_mfma_f32_16x16x32_bf16 v[36:39], v[196:199], v[156:159], v[36:39]
	v_mfma_f32_16x16x32_bf16 v[32:35], v[204:207], v[156:159], v[32:35]
	v_mfma_f32_16x16x32_bf16 v[20:23], v[196:199], v[164:167], v[20:23]
	v_mfma_f32_16x16x32_bf16 v[16:19], v[204:207], v[164:167], v[16:19]
	v_mfma_f32_16x16x32_bf16 v[4:7], v[196:199], v[172:175], v[4:7]
	s_barrier
	v_mfma_f32_16x16x32_bf16 v[0:3], v[204:207], v[172:175], v[0:3]
	s_setprio 0
	s_add_i32 s46, s46, 2
	s_add_u32 s22, s22, 0x100
	s_addc_u32 s23, s23, 0
	s_add_u32 s44, s44, 0x100
	s_addc_u32 s45, s45, 0
	s_cmp_gt_u32 s46, 29
	s_cbranch_scc0 .LBB0_733
;     __device__ __forceinline__ void ld(f32x4 (&xv)[2][2][2], int row0, int col0, int ai, int mh) const {
; #pragma unroll
;         for (int mm = 0; mm < 2; ++mm)
; #pragma unroll
;             for (int bj = 0; bj < 2; ++bj) { const size_t off = (size_t)(row0 + ai * 128 + (2 * mh + mm) * 16) * 2048 + col0 + bj * 128;
;                 xv[mm][bj][0] = *(const f32x4*)(base + off); xv[mm][bj][1] = *(const f32x4*)(base + off + 4); }
;     }
;     __device__ __forceinline__ void fin(const f32x4 (&acc)[2][2][4][2], const f32x4 (&xv)[2][2][2], int row0, int col0, int fq, int ai, int mh) const {
; #pragma unroll
;         for (int mm = 0; mm < 2; ++mm) { const int m = 2 * mh + mm; const int row = row0 + ai * 128 + m * 16; float sq = 0.f;
; #pragma unroll
;             for (int bj = 0; bj < 2; ++bj) { const size_t off = (size_t)row * 2048 + col0 + bj * 128;
;                 const f32x4 y0 = xv[mm][bj][0] + acc[ai][bj][m][0], y1 = xv[mm][bj][1] + acc[ai][bj][m][1];
;                 *(f32x4*)(out + off) = y0; *(f32x4*)(out + off + 4) = y1;
;                 if (ob) *(u32x4*)(ob + off) = pack8(y0, y1);
;                 sq += (y0[0] * y0[0] + y0[1] * y0[1]) + (y0[2] * y0[2] + y0[3] * y0[3]) + (y1[0] * y1[0] + y1[1] * y1[1]) + (y1[2] * y1[2] + y1[3] * y1[3]); }
;             sq += __shfl_xor(sq, 16); sq += __shfl_xor(sq, 32);
;             if (fq == 0) atomicAdd(ssq + row, (unsigned long long)(sq * 16777216.0f + 0.5f)); }
	v_lshl_add_u32 v194, s18, 8, v208
	v_lshl_or_b32 v192, s20, 8, v210
	v_ashrrev_i32_e32 v195, 31, v194
	v_ashrrev_i32_e32 v193, 31, v192
	v_lshlrev_b64 v[128:129], 11, v[194:195]
	v_lshl_add_u64 v[218:219], v[128:129], 0, v[192:193]
	v_lshlrev_b64 v[238:239], 2, v[218:219]
	v_lshl_add_u64 v[128:129], s[64:65], 0, v[238:239]
	global_load_dwordx4 v[222:225], v[128:129], off
	global_load_dwordx4 v[226:229], v[128:129], off offset:16
	global_load_dwordx4 v[230:233], v[128:129], off offset:512
	global_load_dwordx4 v[234:237], v[128:129], off offset:528
	v_or_b32_e32 v204, 16, v194
	v_or_b32_e32 v200, 32, v194
	v_or_b32_e32 v196, 48, v194
	v_ashrrev_i32_e32 v205, 31, v204
	v_ashrrev_i32_e32 v201, 31, v200
	v_ashrrev_i32_e32 v197, 31, v196
	v_lshlrev_b64 v[128:129], 11, v[204:205]
	v_lshlrev_b64 v[130:131], 11, v[200:201]
	v_lshlrev_b64 v[132:133], 11, v[196:197]
	v_lshl_add_u64 v[206:207], v[128:129], 0, v[192:193]
	v_lshl_add_u64 v[202:203], v[130:131], 0, v[192:193]
	v_lshl_add_u64 v[198:199], v[132:133], 0, v[192:193]
	v_lshl_add_u64 v[128:129], v[206:207], 2, s[64:65]
	v_lshl_add_u64 v[130:131], v[202:203], 2, s[64:65]
	v_lshl_add_u64 v[132:133], v[198:199], 2, s[64:65]
	global_load_dwordx4 v[168:171], v[128:129], off offset:16
	global_load_dwordx4 v[172:175], v[128:129], off
	global_load_dwordx4 v[160:163], v[128:129], off offset:528
	global_load_dwordx4 v[164:167], v[128:129], off offset:512
	global_load_dwordx4 v[152:155], v[130:131], off offset:16
	global_load_dwordx4 v[156:159], v[130:131], off
	global_load_dwordx4 v[144:147], v[130:131], off offset:528
	global_load_dwordx4 v[148:151], v[130:131], off offset:512
	global_load_dwordx4 v[136:139], v[132:133], off offset:16
	global_load_dwordx4 v[140:143], v[132:133], off
	s_nop 0
	global_load_dwordx4 v[128:131], v[132:133], off offset:528
	s_nop 0
	global_load_dwordx4 v[132:135], v[132:133], off offset:512
	v_and_b32_e32 v216, 64, v214
	v_xor_b32_e32 v215, 16, v214
	v_add_u32_e32 v216, 64, v216
	v_xor_b32_e32 v217, 32, v214
	v_cmp_lt_i32_e32 vcc, v215, v216
	v_lshl_add_u64 v[238:239], s[70:71], 0, v[238:239]
	v_lshlrev_b64 v[218:219], 1, v[218:219]
	v_cndmask_b32_e32 v215, v214, v215, vcc
	v_cmp_lt_i32_e32 vcc, v217, v216
	v_lshlrev_b32_e32 v216, 2, v215
	v_lshl_add_u64 v[240:241], s[58:59], 0, v[218:219]
	v_cndmask_b32_e32 v217, v214, v217, vcc
	v_lshlrev_b32_e32 v215, 2, v217
	v_or_b32_e32 v218, 0x100, v218
	s_waitcnt vmcnt(0)
	v_pk_add_f32 v[126:127], v[126:127], v[224:225]
	v_pk_add_f32 v[124:125], v[124:125], v[222:223]
	v_pk_add_f32 v[118:119], v[118:119], v[232:233]
	v_pk_add_f32 v[116:117], v[116:117], v[230:231]
	v_pk_add_f32 v[122:123], v[122:123], v[228:229]
	v_pk_add_f32 v[120:121], v[120:121], v[226:227]
	v_pk_add_f32 v[112:113], v[112:113], v[234:235]
	global_store_dwordx4 v[238:239], v[124:127], off
	global_store_dwordx4 v[238:239], v[120:123], off offset:16
	v_cvt_pk_bf16_f32 v222, v124, v125
	v_cvt_pk_bf16_f32 v223, v126, v127
	v_mul_f32_e32 v125, v125, v125
	v_mul_f32_e32 v127, v127, v127
	v_mul_f32_e32 v217, v117, v117
	v_mul_f32_e32 v221, v119, v119
	v_pk_add_f32 v[114:115], v[114:115], v[236:237]
	v_cvt_pk_bf16_f32 v224, v120, v121
	v_cvt_pk_bf16_f32 v225, v122, v123
	v_mul_f32_e32 v121, v121, v121
	v_mul_f32_e32 v123, v123, v123
	v_mul_f32_e32 v226, v113, v113
	v_fmac_f32_e32 v125, v124, v124
	v_fmac_f32_e32 v127, v126, v126
	v_fmac_f32_e32 v217, v116, v116
	v_fmac_f32_e32 v221, v118, v118
	v_mul_f32_e32 v227, v115, v115
	v_fmac_f32_e32 v121, v120, v120
	v_fmac_f32_e32 v123, v122, v122
	v_fmac_f32_e32 v226, v112, v112
	v_add_f32_e32 v120, v125, v127
	v_add_f32_e32 v122, v217, v221
	v_fmac_f32_e32 v227, v114, v114
	v_add_f32_e32 v120, v120, v121
	v_add_f32_e32 v121, v122, v226
	v_add_f32_e32 v120, v123, v120
	v_add_f32_e32 v121, v227, v121
	v_add_f32_e32 v120, v120, v121
	ds_bpermute_b32 v121, v216, v120
	global_store_dwordx4 v[240:241], v[222:225], off
	global_store_dwordx4 v[238:239], v[116:119], off offset:512
	global_store_dwordx4 v[238:239], v[112:115], off offset:528
	s_nop 0
	v_cvt_pk_bf16_f32 v116, v116, v117
	v_cvt_pk_bf16_f32 v117, v118, v119
	v_cvt_pk_bf16_f32 v118, v112, v113
	s_waitcnt lgkmcnt(0)
	v_add_f32_e32 v112, v120, v121
	ds_bpermute_b32 v113, v215, v112
	v_cvt_pk_bf16_f32 v119, v114, v115
	v_lshl_add_u64 v[114:115], s[58:59], 0, v[218:219]
	global_store_dwordx4 v[114:115], v[116:119], off
	s_and_saveexec_b64 s[18:19], s[2:3]
	s_cbranch_execz .LBB0_736
	s_waitcnt lgkmcnt(0)
	v_add_f32_e32 v112, v112, v113
	v_fma_f32 v112, v112, s42, 0.5
	v_trunc_f32_e32 v112, v112
	v_mul_f32_e32 v113, 0x2f800000, v112
	v_floor_f32_e32 v113, v113
	v_fmac_f32_e32 v112, 0xcf800000, v113
	v_cvt_u32_f32_e32 v112, v112
	v_cvt_u32_f32_e32 v113, v113
	v_lshl_add_u64 v[114:115], v[194:195], 3, s[0:1]
	global_atomic_add_x2 v[114:115], v[112:113], off

; #define PG8_STAGE(bufoff, gbase, voff) do { _Pragma("unroll") for (int _i = 0; _i < 2; ++_i) \
;         __builtin_amdgcn_global_load_lds((const unsigned*)((const char*)(gbase) + (voff)[_i]), (LAS unsigned*)(lds + (bufoff) + ldsw + _i * 8192), 16, 0, 0); } while (0)
; #define PG8_LDA(dst, b, h) do { _Pragma("unroll") for (int m = 0; m < 4; ++m) _Pragma("unroll") for (int k = 0; k < 2; ++k) dst[m][k] = *(const LAS bf16x8*)(lds + PG8_SA(b, h) + aoff + m * 2048 + k * 1024); } while (0)
; #define PG8_LDB(dst, b, h) do { _Pragma("unroll") for (int n = 0; n < 2; ++n) _Pragma("unroll") for (int k = 0; k < 2; ++k) dst[n][k] = *(const LAS bf16x8*)(lds + PG8_SB(b, h) + boff + n * 2048 + k * 1024); } while (0)
; #define PG8_MMA(ai, bj, At, Bt) do { __builtin_amdgcn_s_setprio(1); _Pragma("unroll") for (int m = 0; m < 4; ++m) _Pragma("unroll") for (int n = 0; n < 2; ++n) _Pragma("unroll") for (int k = 0; k < 2; ++k) \
;         acc[ai][bj][m][n] = __builtin_amdgcn_mfma_f32_16x16x32_bf16(Bt[n][k], At[m][k], acc[ai][bj][m][n], 0, 0, 0); __builtin_amdgcn_s_setprio(0); } while (0)
; #define PG8_WAIT_V(n) asm volatile("s_waitcnt vmcnt(" #n ")" ::: "memory")
; #define PG8_BAR __builtin_amdgcn_s_barrier()
; template <class Epi>
; __device__ __forceinline__ void gemm_phase(ldsp lds, const Gemm g, const StaticOrder& S, const Epi& E) {
;     ...
;             const bool last = (t == nt - 2);
;             const char* a1 = cA + (size_t)(t + 1) * kstep;
;             const char* a2 = last ? nA : cA + (size_t)(t + 2) * kstep; const char* b2 = last ? nB : cB + (size_t)(t + 2) * kstep;
;             const char* a3 = a2 + kstep; const char* b3 = b2 + kstep;
;             if constexpr (Epi::NPRE > 0) { if (last) E.pre(pre, cur, wr, fr); }
;             if constexpr (Epi::MID_T > 0) { if (t == Epi::MID_T) E.mid(acc, cur, wr, wc, fr, fq); }
;             PG8_LDB(B0, 0, 0); PG8_SCHED; PG8_LDA(At, 0, 0); PG8_STAGE(PG8_SA(1, 1), a1 + hstep, voffA);
;             PG8_WAIT_L(8); PG8_WAIT_V(10); PG8_BAR; PG8_WAIT_L(0); PG8_MMA(0, 0, At, B0); PG8_BAR; PG8_SCHED;
;             PG8_LDB(B1, 0, 1); PG8_STAGE(PG8_SB(0, 0), b2, voffB);
;             PG8_WAIT_V(10); PG8_BAR; PG8_WAIT_L(0); PG8_MMA(0, 1, At, B1); PG8_BAR;
;             PG8_LDA(At, 0, 1); PG8_STAGE(PG8_SA(0, 0), a2, voffA);
;             PG8_WAIT_V(10); PG8_BAR; PG8_WAIT_L(0); PG8_MMA(1, 0, At, B0); PG8_BAR; PG8_SCHED;
.LBB0_816:
	ds_read_b128 v[164:167], v247 offset:0
	ds_read_b128 v[168:171], v247 offset:1024
	ds_read_b128 v[178:181], v247 offset:2048
	ds_read_b128 v[182:185], v247 offset:3072
	s_add_u32 s26, s22, 0xfff80080
	s_addc_u32 s27, s23, -1
	s_and_b64 s[24:25], s[24:25], exec
	s_cselect_b32 s27, s17, s27
	s_cselect_b32 s26, s44, s26
	s_cselect_b32 s25, s15, s47
	s_cselect_b32 s24, s45, s46
	s_add_i32 m0, s29, 0xc000
	ds_read_b128 v[186:189], v177
	ds_read_b128 v[190:193], v177 offset:1024
	ds_read_b128 v[194:197], v177 offset:2048
	ds_read_b128 v[198:201], v177 offset:3072
	ds_read_b128 v[202:205], v177 offset:4096
	ds_read_b128 v[206:209], v177 offset:5120
	ds_read_b128 v[210:213], v177 offset:6144
	ds_read_b128 v[214:217], v177 offset:7168
	global_load_lds_dwordx4 v136, s[22:23]
	s_add_i32 m0, s29, 0xe000
	s_nop 0
	global_load_lds_dwordx4 v138, s[22:23]
	s_waitcnt lgkmcnt(8)
	s_waitcnt vmcnt(10)
	s_barrier
	s_waitcnt lgkmcnt(0)
	s_setprio 1
	s_waitcnt lgkmcnt(0)
	v_mfma_f32_16x16x32_bf16 v[124:127], v[164:167], v[186:189], v[124:127]
	v_mfma_f32_16x16x32_bf16 v[120:123], v[178:181], v[186:189], v[120:123]
	v_mfma_f32_16x16x32_bf16 v[112:115], v[164:167], v[194:197], v[112:115]
	v_mfma_f32_16x16x32_bf16 v[104:107], v[178:181], v[194:197], v[104:107]
	v_mfma_f32_16x16x32_bf16 v[92:95], v[164:167], v[202:205], v[92:95]
	v_mfma_f32_16x16x32_bf16 v[88:91], v[178:181], v[202:205], v[88:91]
	v_mfma_f32_16x16x32_bf16 v[80:83], v[164:167], v[210:213], v[80:83]
	v_mfma_f32_16x16x32_bf16 v[72:75], v[178:181], v[210:213], v[72:75]
	v_mfma_f32_16x16x32_bf16 v[124:127], v[168:171], v[190:193], v[124:127]
	v_mfma_f32_16x16x32_bf16 v[120:123], v[182:185], v[190:193], v[120:123]
	v_mfma_f32_16x16x32_bf16 v[112:115], v[168:171], v[198:201], v[112:115]
	v_mfma_f32_16x16x32_bf16 v[104:107], v[182:185], v[198:201], v[104:107]
	v_mfma_f32_16x16x32_bf16 v[92:95], v[168:171], v[206:209], v[92:95]
	v_mfma_f32_16x16x32_bf16 v[88:91], v[182:185], v[206:209], v[88:91]
	v_mfma_f32_16x16x32_bf16 v[80:83], v[168:171], v[214:217], v[80:83]
	s_barrier
	v_mfma_f32_16x16x32_bf16 v[72:75], v[182:185], v[214:217], v[72:75]
	s_setprio 0
	s_add_i32 s51, s39, s11
	s_add_u32 s98, s24, 0x80
	s_addc_u32 s99, s25, 0
	s_mov_b32 m0, s51
	ds_read_b128 v[222:225], v247 offset:16384
	ds_read_b128 v[226:229], v247 offset:17408
	ds_read_b128 v[230:233], v247 offset:18432
	ds_read_b128 v[234:237], v247 offset:19456
	global_load_lds_dwordx4 v132, s[24:25]
	s_add_i32 m0, s51, 0x2000
	s_nop 0
	global_load_lds_dwordx4 v128, s[24:25]
	s_waitcnt vmcnt(10)
	s_barrier
	s_waitcnt lgkmcnt(0)
	s_setprio 1
	s_waitcnt lgkmcnt(0)
	v_mfma_f32_16x16x32_bf16 v[116:119], v[222:225], v[186:189], v[116:119]
	v_mfma_f32_16x16x32_bf16 v[108:111], v[230:233], v[186:189], v[108:111]
	v_mfma_f32_16x16x32_bf16 v[100:103], v[222:225], v[194:197], v[100:103]
	v_mfma_f32_16x16x32_bf16 v[96:99], v[230:233], v[194:197], v[96:99]
	v_mfma_f32_16x16x32_bf16 v[84:87], v[222:225], v[202:205], v[84:87]
	v_mfma_f32_16x16x32_bf16 v[76:79], v[230:233], v[202:205], v[76:79]
	v_mfma_f32_16x16x32_bf16 v[68:71], v[222:225], v[210:213], v[68:71]
	v_mfma_f32_16x16x32_bf16 v[64:67], v[230:233], v[210:213], v[64:67]
	v_mfma_f32_16x16x32_bf16 v[116:119], v[226:229], v[190:193], v[116:119]
	v_mfma_f32_16x16x32_bf16 v[108:111], v[234:237], v[190:193], v[108:111]
	v_mfma_f32_16x16x32_bf16 v[100:103], v[226:229], v[198:201], v[100:103]
	v_mfma_f32_16x16x32_bf16 v[96:99], v[234:237], v[198:201], v[96:99]
	v_mfma_f32_16x16x32_bf16 v[84:87], v[226:229], v[206:209], v[84:87]
	v_mfma_f32_16x16x32_bf16 v[76:79], v[234:237], v[206:209], v[76:79]
	v_mfma_f32_16x16x32_bf16 v[68:71], v[226:229], v[214:217], v[68:71]
	s_barrier
	v_mfma_f32_16x16x32_bf16 v[64:67], v[234:237], v[214:217], v[64:67]
	s_setprio 0
	s_mov_b32 m0, s29
	s_add_u32 s100, s26, 0x80
	s_addc_u32 s101, s27, 0
	ds_read_b128 v[186:189], v177 offset:16384
	ds_read_b128 v[190:193], v177 offset:17408
	ds_read_b128 v[194:197], v177 offset:18432
	ds_read_b128 v[198:201], v177 offset:19456
	ds_read_b128 v[202:205], v177 offset:20480
	ds_read_b128 v[206:209], v177 offset:21504
	ds_read_b128 v[210:213], v177 offset:22528
	ds_read_b128 v[214:217], v177 offset:23552
	global_load_lds_dwordx4 v134, s[26:27]
	s_mov_b32 m0, s30
	s_nop 0
	global_load_lds_dwordx4 v130, s[26:27]
	s_waitcnt vmcnt(10)
	s_barrier
	s_waitcnt lgkmcnt(0)
	s_setprio 1
	s_waitcnt lgkmcnt(0)
	v_mfma_f32_16x16x32_bf16 v[60:63], v[164:167], v[186:189], v[60:63]
	v_mfma_f32_16x16x32_bf16 v[56:59], v[178:181], v[186:189], v[56:59]
	v_mfma_f32_16x16x32_bf16 v[48:51], v[164:167], v[194:197], v[48:51]
	v_mfma_f32_16x16x32_bf16 v[40:43], v[178:181], v[194:197], v[40:43]
	v_mfma_f32_16x16x32_bf16 v[28:31], v[164:167], v[202:205], v[28:31]
	v_mfma_f32_16x16x32_bf16 v[24:27], v[178:181], v[202:205], v[24:27]
	v_mfma_f32_16x16x32_bf16 v[16:19], v[164:167], v[210:213], v[16:19]
	v_mfma_f32_16x16x32_bf16 v[8:11], v[178:181], v[210:213], v[8:11]
	v_mfma_f32_16x16x32_bf16 v[60:63], v[168:171], v[190:193], v[60:63]
	v_mfma_f32_16x16x32_bf16 v[56:59], v[182:185], v[190:193], v[56:59]
	v_mfma_f32_16x16x32_bf16 v[48:51], v[168:171], v[198:201], v[48:51]
	v_mfma_f32_16x16x32_bf16 v[40:43], v[182:185], v[198:201], v[40:43]
	v_mfma_f32_16x16x32_bf16 v[28:31], v[168:171], v[206:209], v[28:31]
	v_mfma_f32_16x16x32_bf16 v[24:27], v[182:185], v[206:209], v[24:27]
	v_mfma_f32_16x16x32_bf16 v[16:19], v[168:171], v[214:217], v[16:19]
	s_barrier
	v_mfma_f32_16x16x32_bf16 v[8:11], v[182:185], v[214:217], v[8:11]
	s_setprio 0
	s_add_u32 s52, s24, 0x80000
	s_addc_u32 s53, s25, 0
	s_add_i32 s51, s40, s11
	s_mov_b32 m0, s51
	s_nop 0
	global_load_lds_dwordx4 v132, s[52:53]
	s_add_i32 m0, s51, 0x2000
	s_nop 0
	global_load_lds_dwordx4 v128, s[52:53]
	s_waitcnt vmcnt(10)
	s_barrier
; #define PG8_STAGE(bufoff, gbase, voff) do { _Pragma("unroll") for (int _i = 0; _i < 2; ++_i) \
;         __builtin_amdgcn_global_load_lds((const unsigned*)((const char*)(gbase) + (voff)[_i]), (LAS unsigned*)(lds + (bufoff) + ldsw + _i * 8192), 16, 0, 0); } while (0)
; #define PG8_LDA(dst, b, h) do { _Pragma("unroll") for (int m = 0; m < 4; ++m) _Pragma("unroll") for (int k = 0; k < 2; ++k) dst[m][k] = *(const LAS bf16x8*)(lds + PG8_SA(b, h) + aoff + m * 2048 + k * 1024); } while (0)
; #define PG8_LDB(dst, b, h) do { _Pragma("unroll") for (int n = 0; n < 2; ++n) _Pragma("unroll") for (int k = 0; k < 2; ++k) dst[n][k] = *(const LAS bf16x8*)(lds + PG8_SB(b, h) + boff + n * 2048 + k * 1024); } while (0)
; #define PG8_MMA(ai, bj, At, Bt) do { __builtin_amdgcn_s_setprio(1); _Pragma("unroll") for (int m = 0; m < 4; ++m) _Pragma("unroll") for (int n = 0; n < 2; ++n) _Pragma("unroll") for (int k = 0; k < 2; ++k) \
;         acc[ai][bj][m][n] = __builtin_amdgcn_mfma_f32_16x16x32_bf16(Bt[n][k], At[m][k], acc[ai][bj][m][n], 0, 0, 0); __builtin_amdgcn_s_setprio(0); } while (0)
; #define PG8_WAIT_V(n) asm volatile("s_waitcnt vmcnt(" #n ")" ::: "memory")
; #define PG8_WAIT_L(n) asm volatile("s_waitcnt lgkmcnt(" #n ")" ::: "memory")
; #define PG8_BAR __builtin_amdgcn_s_barrier()
; #define PG8_SCHED __builtin_amdgcn_sched_barrier(0)
; template <class Epi>
; __device__ __forceinline__ void gemm_phase(ldsp lds, const Gemm g, const StaticOrder& S, const Epi& E) {
;     ...
;             PG8_WAIT_V(10); PG8_BAR; PG8_MMA(1, 1, At, B1); PG8_BAR;
;             PG8_LDB(B0, 1, 0); PG8_SCHED; PG8_LDA(At, 1, 0); PG8_STAGE(PG8_SA(0, 1), a2 + hstep, voffA);
;             PG8_WAIT_L(8); PG8_WAIT_V(10); PG8_BAR; PG8_WAIT_L(0); PG8_MMA(0, 0, At, B0); PG8_BAR; PG8_SCHED;
;             PG8_LDB(B1, 1, 1); PG8_STAGE(PG8_SB(1, 0), b3, voffB);
;             PG8_WAIT_V(10); PG8_BAR; PG8_WAIT_L(0); PG8_MMA(0, 1, At, B1); PG8_BAR;
	s_nop 3
	s_setprio 1
	v_mfma_f32_16x16x32_bf16 v[52:55], v[222:225], v[186:189], v[52:55]
	v_mfma_f32_16x16x32_bf16 v[44:47], v[230:233], v[186:189], v[44:47]
	v_mfma_f32_16x16x32_bf16 v[36:39], v[222:225], v[194:197], v[36:39]
	v_mfma_f32_16x16x32_bf16 v[32:35], v[230:233], v[194:197], v[32:35]
	v_mfma_f32_16x16x32_bf16 v[20:23], v[222:225], v[202:205], v[20:23]
	v_mfma_f32_16x16x32_bf16 v[12:15], v[230:233], v[202:205], v[12:15]
	v_mfma_f32_16x16x32_bf16 v[4:7], v[222:225], v[210:213], v[4:7]
	v_mfma_f32_16x16x32_bf16 v[0:3], v[230:233], v[210:213], v[0:3]
	v_mfma_f32_16x16x32_bf16 v[52:55], v[226:229], v[190:193], v[52:55]
	v_mfma_f32_16x16x32_bf16 v[44:47], v[234:237], v[190:193], v[44:47]
	v_mfma_f32_16x16x32_bf16 v[36:39], v[226:229], v[198:201], v[36:39]
	v_mfma_f32_16x16x32_bf16 v[32:35], v[234:237], v[198:201], v[32:35]
	v_mfma_f32_16x16x32_bf16 v[20:23], v[226:229], v[206:209], v[20:23]
	v_mfma_f32_16x16x32_bf16 v[12:15], v[234:237], v[206:209], v[12:15]
	v_mfma_f32_16x16x32_bf16 v[4:7], v[226:229], v[214:217], v[4:7]
	s_barrier
	v_mfma_f32_16x16x32_bf16 v[0:3], v[234:237], v[214:217], v[0:3]
	s_setprio 0
	s_add_i32 s51, 0, 0x18000
	ds_read_b128 v[164:167], v247 offset:32768
	ds_read_b128 v[168:171], v247 offset:33792
	ds_read_b128 v[178:181], v247 offset:34816
	ds_read_b128 v[182:185], v247 offset:35840
	s_add_u32 s26, s26, 0x80000
	s_addc_u32 s27, s27, 0
	s_mov_b32 m0, s31
	ds_read_b128 v[186:189], v177 offset:32768
	ds_read_b128 v[190:193], v177 offset:33792
	ds_read_b128 v[194:197], v177 offset:34816
	ds_read_b128 v[198:201], v177 offset:35840
	ds_read_b128 v[202:205], v177 offset:36864
	ds_read_b128 v[206:209], v177 offset:37888
	ds_read_b128 v[210:213], v177 offset:38912
	ds_read_b128 v[214:217], v177 offset:39936
	global_load_lds_dwordx4 v134, s[26:27]
	s_mov_b32 m0, s33
	s_nop 0
	global_load_lds_dwordx4 v130, s[26:27]
	s_waitcnt lgkmcnt(8)
	s_waitcnt vmcnt(10)
	s_barrier
	s_waitcnt lgkmcnt(0)
	s_setprio 1
	s_waitcnt lgkmcnt(0)
	v_mfma_f32_16x16x32_bf16 v[124:127], v[164:167], v[186:189], v[124:127]
	v_mfma_f32_16x16x32_bf16 v[120:123], v[178:181], v[186:189], v[120:123]
	v_mfma_f32_16x16x32_bf16 v[112:115], v[164:167], v[194:197], v[112:115]
	v_mfma_f32_16x16x32_bf16 v[104:107], v[178:181], v[194:197], v[104:107]
	v_mfma_f32_16x16x32_bf16 v[92:95], v[164:167], v[202:205], v[92:95]
	v_mfma_f32_16x16x32_bf16 v[88:91], v[178:181], v[202:205], v[88:91]
	v_mfma_f32_16x16x32_bf16 v[80:83], v[164:167], v[210:213], v[80:83]
	v_mfma_f32_16x16x32_bf16 v[72:75], v[178:181], v[210:213], v[72:75]
	v_mfma_f32_16x16x32_bf16 v[124:127], v[168:171], v[190:193], v[124:127]
	v_mfma_f32_16x16x32_bf16 v[120:123], v[182:185], v[190:193], v[120:123]
	v_mfma_f32_16x16x32_bf16 v[112:115], v[168:171], v[198:201], v[112:115]
	v_mfma_f32_16x16x32_bf16 v[104:107], v[182:185], v[198:201], v[104:107]
	v_mfma_f32_16x16x32_bf16 v[92:95], v[168:171], v[206:209], v[92:95]
	v_mfma_f32_16x16x32_bf16 v[88:91], v[182:185], v[206:209], v[88:91]
	v_mfma_f32_16x16x32_bf16 v[80:83], v[168:171], v[214:217], v[80:83]
	s_barrier
	v_mfma_f32_16x16x32_bf16 v[72:75], v[182:185], v[214:217], v[72:75]
	s_setprio 0
	s_add_i32 s26, 0, 0x1c000
	s_add_i32 s27, s51, s11
	s_mov_b32 m0, s27
	ds_read_b128 v[222:225], v247 offset:49152
	ds_read_b128 v[226:229], v247 offset:50176
	ds_read_b128 v[230:233], v247 offset:51200
	ds_read_b128 v[234:237], v247 offset:52224
	global_load_lds_dwordx4 v132, s[98:99]
	s_add_i32 m0, s27, 0x2000
	s_nop 0
	global_load_lds_dwordx4 v128, s[98:99]
	s_waitcnt vmcnt(10)
	s_barrier
; #define PG8_STAGE(bufoff, gbase, voff) do { _Pragma("unroll") for (int _i = 0; _i < 2; ++_i) \
;         __builtin_amdgcn_global_load_lds((const unsigned*)((const char*)(gbase) + (voff)[_i]), (LAS unsigned*)(lds + (bufoff) + ldsw + _i * 8192), 16, 0, 0); } while (0)
; #define PG8_LDA(dst, b, h) do { _Pragma("unroll") for (int m = 0; m < 4; ++m) _Pragma("unroll") for (int k = 0; k < 2; ++k) dst[m][k] = *(const LAS bf16x8*)(lds + PG8_SA(b, h) + aoff + m * 2048 + k * 1024); } while (0)
; #define PG8_MMA(ai, bj, At, Bt) do { __builtin_amdgcn_s_setprio(1); _Pragma("unroll") for (int m = 0; m < 4; ++m) _Pragma("unroll") for (int n = 0; n < 2; ++n) _Pragma("unroll") for (int k = 0; k < 2; ++k) \
;         acc[ai][bj][m][n] = __builtin_amdgcn_mfma_f32_16x16x32_bf16(Bt[n][k], At[m][k], acc[ai][bj][m][n], 0, 0, 0); __builtin_amdgcn_s_setprio(0); } while (0)
; #define PG8_WAIT_V(n) asm volatile("s_waitcnt vmcnt(" #n ")" ::: "memory")
; #define PG8_WAIT_L(n) asm volatile("s_waitcnt lgkmcnt(" #n ")" ::: "memory")
; #define PG8_BAR __builtin_amdgcn_s_barrier()
; #define PG8_SCHED __builtin_amdgcn_sched_barrier(0)
; template <class Epi>
; __device__ __forceinline__ void gemm_phase(ldsp lds, const Gemm g, const StaticOrder& S, const Epi& E) {
;     ...
;             PG8_WAIT_V(10); PG8_BAR; PG8_WAIT_L(0); PG8_MMA(0, 1, At, B1); PG8_BAR;
;             PG8_LDA(At, 1, 1); PG8_STAGE(PG8_SA(1, 0), a3, voffA);
;             PG8_WAIT_V(10); PG8_BAR; PG8_WAIT_L(0); PG8_MMA(1, 0, At, B0); PG8_BAR; PG8_SCHED;
;             PG8_STAGE(PG8_SB(1, 1), b3 + hstep, voffB);
;             PG8_WAIT_V(10); PG8_BAR; PG8_MMA(1, 1, At, B1); PG8_BAR;
	s_waitcnt lgkmcnt(0)
	s_setprio 1
	s_waitcnt lgkmcnt(0)
	v_mfma_f32_16x16x32_bf16 v[116:119], v[222:225], v[186:189], v[116:119]
	v_mfma_f32_16x16x32_bf16 v[108:111], v[230:233], v[186:189], v[108:111]
	v_mfma_f32_16x16x32_bf16 v[100:103], v[222:225], v[194:197], v[100:103]
	v_mfma_f32_16x16x32_bf16 v[96:99], v[230:233], v[194:197], v[96:99]
	v_mfma_f32_16x16x32_bf16 v[84:87], v[222:225], v[202:205], v[84:87]
	v_mfma_f32_16x16x32_bf16 v[76:79], v[230:233], v[202:205], v[76:79]
	v_mfma_f32_16x16x32_bf16 v[68:71], v[222:225], v[210:213], v[68:71]
	v_mfma_f32_16x16x32_bf16 v[64:67], v[230:233], v[210:213], v[64:67]
	v_mfma_f32_16x16x32_bf16 v[116:119], v[226:229], v[190:193], v[116:119]
	v_mfma_f32_16x16x32_bf16 v[108:111], v[234:237], v[190:193], v[108:111]
	v_mfma_f32_16x16x32_bf16 v[100:103], v[226:229], v[198:201], v[100:103]
	v_mfma_f32_16x16x32_bf16 v[96:99], v[234:237], v[198:201], v[96:99]
	v_mfma_f32_16x16x32_bf16 v[84:87], v[226:229], v[206:209], v[84:87]
	v_mfma_f32_16x16x32_bf16 v[76:79], v[234:237], v[206:209], v[76:79]
	v_mfma_f32_16x16x32_bf16 v[68:71], v[226:229], v[214:217], v[68:71]
	s_barrier
	v_mfma_f32_16x16x32_bf16 v[64:67], v[234:237], v[214:217], v[64:67]
	s_setprio 0
	s_mov_b32 m0, s35
	ds_read_b128 v[186:189], v177 offset:49152
	ds_read_b128 v[190:193], v177 offset:50176
	ds_read_b128 v[194:197], v177 offset:51200
	ds_read_b128 v[198:201], v177 offset:52224
	ds_read_b128 v[202:205], v177 offset:53248
	ds_read_b128 v[206:209], v177 offset:54272
	ds_read_b128 v[210:213], v177 offset:55296
	ds_read_b128 v[214:217], v177 offset:56320
	global_load_lds_dwordx4 v134, s[100:101]
	s_mov_b32 m0, s36
	s_nop 0
	global_load_lds_dwordx4 v130, s[100:101]
	s_waitcnt vmcnt(10)
	s_barrier
	s_waitcnt lgkmcnt(0)
	s_setprio 1
	s_waitcnt lgkmcnt(0)
	v_mfma_f32_16x16x32_bf16 v[60:63], v[164:167], v[186:189], v[60:63]
	v_mfma_f32_16x16x32_bf16 v[56:59], v[178:181], v[186:189], v[56:59]
	v_mfma_f32_16x16x32_bf16 v[48:51], v[164:167], v[194:197], v[48:51]
	v_mfma_f32_16x16x32_bf16 v[40:43], v[178:181], v[194:197], v[40:43]
	v_mfma_f32_16x16x32_bf16 v[28:31], v[164:167], v[202:205], v[28:31]
	v_mfma_f32_16x16x32_bf16 v[24:27], v[178:181], v[202:205], v[24:27]
	v_mfma_f32_16x16x32_bf16 v[16:19], v[164:167], v[210:213], v[16:19]
	v_mfma_f32_16x16x32_bf16 v[8:11], v[178:181], v[210:213], v[8:11]
	v_mfma_f32_16x16x32_bf16 v[60:63], v[168:171], v[190:193], v[60:63]
	v_mfma_f32_16x16x32_bf16 v[56:59], v[182:185], v[190:193], v[56:59]
	v_mfma_f32_16x16x32_bf16 v[48:51], v[168:171], v[198:201], v[48:51]
	v_mfma_f32_16x16x32_bf16 v[40:43], v[182:185], v[198:201], v[40:43]
	v_mfma_f32_16x16x32_bf16 v[28:31], v[168:171], v[206:209], v[28:31]
	v_mfma_f32_16x16x32_bf16 v[24:27], v[182:185], v[206:209], v[24:27]
	v_mfma_f32_16x16x32_bf16 v[16:19], v[168:171], v[214:217], v[16:19]
	s_barrier
	v_mfma_f32_16x16x32_bf16 v[8:11], v[182:185], v[214:217], v[8:11]
	s_setprio 0
	s_add_u32 s24, s24, 0x80080
	s_addc_u32 s25, s25, 0
	s_add_i32 s26, s26, s11
	s_mov_b32 m0, s26
	s_nop 0
	global_load_lds_dwordx4 v132, s[24:25]
	s_add_i32 m0, s26, 0x2000
	s_nop 0
	global_load_lds_dwordx4 v128, s[24:25]
	s_waitcnt vmcnt(10)
	s_barrier
	s_nop 3
	s_setprio 1
	v_mfma_f32_16x16x32_bf16 v[52:55], v[222:225], v[186:189], v[52:55]
	v_mfma_f32_16x16x32_bf16 v[44:47], v[230:233], v[186:189], v[44:47]
	v_mfma_f32_16x16x32_bf16 v[36:39], v[222:225], v[194:197], v[36:39]
	v_mfma_f32_16x16x32_bf16 v[32:35], v[230:233], v[194:197], v[32:35]
	v_mfma_f32_16x16x32_bf16 v[20:23], v[222:225], v[202:205], v[20:23]
	v_mfma_f32_16x16x32_bf16 v[12:15], v[230:233], v[202:205], v[12:15]
	v_mfma_f32_16x16x32_bf16 v[4:7], v[222:225], v[210:213], v[4:7]
	v_mfma_f32_16x16x32_bf16 v[0:3], v[230:233], v[210:213], v[0:3]
	v_mfma_f32_16x16x32_bf16 v[52:55], v[226:229], v[190:193], v[52:55]
	v_mfma_f32_16x16x32_bf16 v[44:47], v[234:237], v[190:193], v[44:47]
	v_mfma_f32_16x16x32_bf16 v[36:39], v[226:229], v[198:201], v[36:39]
	v_mfma_f32_16x16x32_bf16 v[32:35], v[234:237], v[198:201], v[32:35]
	v_mfma_f32_16x16x32_bf16 v[20:23], v[226:229], v[206:209], v[20:23]
	v_mfma_f32_16x16x32_bf16 v[12:15], v[234:237], v[206:209], v[12:15]
	v_mfma_f32_16x16x32_bf16 v[4:7], v[226:229], v[214:217], v[4:7]
	s_barrier
	v_mfma_f32_16x16x32_bf16 v[0:3], v[234:237], v[214:217], v[0:3]
	s_setprio 0
	s_add_i32 s50, s50, 2
	s_add_u32 s22, s22, 0x100
	s_addc_u32 s23, s23, 0
	s_add_u32 s46, s46, 0x100
	s_addc_u32 s47, s47, 0
	s_cmp_gt_u32 s50, 29
	s_cbranch_scc1 .LBB0_812

; #define PG8_STAGE(bufoff, gbase, voff) do { _Pragma("unroll") for (int _i = 0; _i < 2; ++_i) \
;         __builtin_amdgcn_global_load_lds((const unsigned*)((const char*)(gbase) + (voff)[_i]), (LAS unsigned*)(lds + (bufoff) + ldsw + _i * 8192), 16, 0, 0); } while (0)
; #define PG8_LDA(dst, b, h) do { _Pragma("unroll") for (int m = 0; m < 4; ++m) _Pragma("unroll") for (int k = 0; k < 2; ++k) dst[m][k] = *(const LAS bf16x8*)(lds + PG8_SA(b, h) + aoff + m * 2048 + k * 1024); } while (0)
; #define PG8_LDB(dst, b, h) do { _Pragma("unroll") for (int n = 0; n < 2; ++n) _Pragma("unroll") for (int k = 0; k < 2; ++k) dst[n][k] = *(const LAS bf16x8*)(lds + PG8_SB(b, h) + boff + n * 2048 + k * 1024); } while (0)
; #define PG8_MMA(ai, bj, At, Bt) do { __builtin_amdgcn_s_setprio(1); _Pragma("unroll") for (int m = 0; m < 4; ++m) _Pragma("unroll") for (int n = 0; n < 2; ++n) _Pragma("unroll") for (int k = 0; k < 2; ++k) \
;         acc[ai][bj][m][n] = __builtin_amdgcn_mfma_f32_16x16x32_bf16(Bt[n][k], At[m][k], acc[ai][bj][m][n], 0, 0, 0); __builtin_amdgcn_s_setprio(0); } while (0)
; #define PG8_WAIT_V(n) asm volatile("s_waitcnt vmcnt(" #n ")" ::: "memory")
; #define PG8_BAR __builtin_amdgcn_s_barrier()
; template <class Epi>
; __device__ __forceinline__ void gemm_phase(ldsp lds, const Gemm g, const StaticOrder& S, const Epi& E) {
;     ...
;             const bool last = (t == nt - 2);
;             const char* a1 = cA + (size_t)(t + 1) * kstep;
;             const char* a2 = last ? nA : cA + (size_t)(t + 2) * kstep; const char* b2 = last ? nB : cB + (size_t)(t + 2) * kstep;
;             const char* a3 = a2 + kstep; const char* b3 = b2 + kstep;
;             if constexpr (Epi::NPRE > 0) { if (last) E.pre(pre, cur, wr, fr); }
;             if constexpr (Epi::MID_T > 0) { if (t == Epi::MID_T) E.mid(acc, cur, wr, wc, fr, fq); }
;             PG8_LDB(B0, 0, 0); PG8_SCHED; PG8_LDA(At, 0, 0); PG8_STAGE(PG8_SA(1, 1), a1 + hstep, voffA);
;             PG8_WAIT_L(8); PG8_WAIT_V(10); PG8_BAR; PG8_WAIT_L(0); PG8_MMA(0, 0, At, B0); PG8_BAR; PG8_SCHED;
;             PG8_LDB(B1, 0, 1); PG8_STAGE(PG8_SB(0, 0), b2, voffB);
;             PG8_WAIT_V(10); PG8_BAR; PG8_WAIT_L(0); PG8_MMA(0, 1, At, B1); PG8_BAR;
;             PG8_LDA(At, 0, 1); PG8_STAGE(PG8_SA(0, 0), a2, voffA);
;             PG8_WAIT_V(10); PG8_BAR; PG8_WAIT_L(0); PG8_MMA(1, 0, At, B0); PG8_BAR; PG8_SCHED;
.LBB0_899:
	ds_read_b128 v[128:131], v211
	ds_read_b128 v[132:135], v211 offset:1024
	ds_read_b128 v[136:139], v211 offset:2048
	ds_read_b128 v[140:143], v211 offset:3072
	s_add_u32 s16, s14, 0xffea0080
	s_addc_u32 s17, s15, -1
	s_cmpk_eq_i32 s42, 0x54
	s_cselect_b32 s19, s1, s17
	s_cselect_b32 s18, s0, s16
	s_cselect_b32 s17, s7, s41
	s_cselect_b32 s16, s6, s40
	s_add_i32 m0, s22, 0xc000
	ds_read_b128 v[144:147], v212
	ds_read_b128 v[148:151], v212 offset:1024
	ds_read_b128 v[152:155], v212 offset:2048
	ds_read_b128 v[156:159], v212 offset:3072
	ds_read_b128 v[160:163], v212 offset:4096
	ds_read_b128 v[164:167], v212 offset:5120
	ds_read_b128 v[168:171], v212 offset:6144
	ds_read_b128 v[172:175], v212 offset:7168
	global_load_lds_dwordx4 v184, s[14:15]
	s_add_i32 m0, s22, 0xe000
	s_nop 0
	global_load_lds_dwordx4 v186, s[14:15]
	s_waitcnt lgkmcnt(8)
	s_waitcnt vmcnt(10)
	s_barrier
	s_waitcnt lgkmcnt(0)
	s_setprio 1
	s_waitcnt lgkmcnt(0)
	v_mfma_f32_16x16x32_bf16 v[124:127], v[128:131], v[144:147], v[124:127]
	v_mfma_f32_16x16x32_bf16 v[120:123], v[136:139], v[144:147], v[120:123]
	v_mfma_f32_16x16x32_bf16 v[108:111], v[128:131], v[152:155], v[108:111]
	v_mfma_f32_16x16x32_bf16 v[104:107], v[136:139], v[152:155], v[104:107]
	v_mfma_f32_16x16x32_bf16 v[92:95], v[128:131], v[160:163], v[92:95]
	v_mfma_f32_16x16x32_bf16 v[88:91], v[136:139], v[160:163], v[88:91]
	v_mfma_f32_16x16x32_bf16 v[76:79], v[128:131], v[168:171], v[76:79]
	v_mfma_f32_16x16x32_bf16 v[72:75], v[136:139], v[168:171], v[72:75]
	v_mfma_f32_16x16x32_bf16 v[124:127], v[132:135], v[148:151], v[124:127]
	v_mfma_f32_16x16x32_bf16 v[120:123], v[140:143], v[148:151], v[120:123]
	v_mfma_f32_16x16x32_bf16 v[108:111], v[132:135], v[156:159], v[108:111]
	v_mfma_f32_16x16x32_bf16 v[104:107], v[140:143], v[156:159], v[104:107]
	v_mfma_f32_16x16x32_bf16 v[92:95], v[132:135], v[164:167], v[92:95]
	v_mfma_f32_16x16x32_bf16 v[88:91], v[140:143], v[164:167], v[88:91]
	v_mfma_f32_16x16x32_bf16 v[76:79], v[132:135], v[172:175], v[76:79]
	s_barrier
	v_mfma_f32_16x16x32_bf16 v[72:75], v[140:143], v[172:175], v[72:75]
	s_setprio 0
	s_add_i32 s43, s33, s21
	s_add_u32 s98, s16, 0x80
	s_addc_u32 s99, s17, 0
	s_mov_b32 m0, s43
	ds_read_b128 v[192:195], v213
	ds_read_b128 v[196:199], v213 offset:1024
	ds_read_b128 v[200:203], v213 offset:2048
	ds_read_b128 v[204:207], v213 offset:3072
	global_load_lds_dwordx4 v178, s[16:17]
	s_add_i32 m0, s43, 0x2000
	s_nop 0
	global_load_lds_dwordx4 v182, s[16:17]
	s_waitcnt vmcnt(10)
	s_barrier
	s_waitcnt lgkmcnt(0)
	s_setprio 1
	s_waitcnt lgkmcnt(0)
	v_mfma_f32_16x16x32_bf16 v[116:119], v[192:195], v[144:147], v[116:119]
	v_mfma_f32_16x16x32_bf16 v[112:115], v[200:203], v[144:147], v[112:115]
	v_mfma_f32_16x16x32_bf16 v[100:103], v[192:195], v[152:155], v[100:103]
	v_mfma_f32_16x16x32_bf16 v[96:99], v[200:203], v[152:155], v[96:99]
	v_mfma_f32_16x16x32_bf16 v[84:87], v[192:195], v[160:163], v[84:87]
	v_mfma_f32_16x16x32_bf16 v[80:83], v[200:203], v[160:163], v[80:83]
	v_mfma_f32_16x16x32_bf16 v[68:71], v[192:195], v[168:171], v[68:71]
	v_mfma_f32_16x16x32_bf16 v[64:67], v[200:203], v[168:171], v[64:67]
	v_mfma_f32_16x16x32_bf16 v[116:119], v[196:199], v[148:151], v[116:119]
	v_mfma_f32_16x16x32_bf16 v[112:115], v[204:207], v[148:151], v[112:115]
	v_mfma_f32_16x16x32_bf16 v[100:103], v[196:199], v[156:159], v[100:103]
	v_mfma_f32_16x16x32_bf16 v[96:99], v[204:207], v[156:159], v[96:99]
	v_mfma_f32_16x16x32_bf16 v[84:87], v[196:199], v[164:167], v[84:87]
	v_mfma_f32_16x16x32_bf16 v[80:83], v[204:207], v[164:167], v[80:83]
	v_mfma_f32_16x16x32_bf16 v[68:71], v[196:199], v[172:175], v[68:71]
	s_barrier
	v_mfma_f32_16x16x32_bf16 v[64:67], v[204:207], v[172:175], v[64:67]
	s_setprio 0
	s_mov_b32 m0, s22
	s_add_u32 s100, s18, 0x80
	s_addc_u32 s101, s19, 0
	ds_read_b128 v[144:147], v212 offset:16384
	ds_read_b128 v[148:151], v212 offset:17408
	ds_read_b128 v[152:155], v212 offset:18432
	ds_read_b128 v[156:159], v212 offset:19456
	ds_read_b128 v[160:163], v212 offset:20480
	ds_read_b128 v[164:167], v212 offset:21504
	ds_read_b128 v[168:171], v212 offset:22528
	ds_read_b128 v[172:175], v212 offset:23552
	global_load_lds_dwordx4 v176, s[18:19]
	s_mov_b32 m0, s23
	s_nop 0
	global_load_lds_dwordx4 v180, s[18:19]
	s_waitcnt vmcnt(10)
	s_barrier
	s_waitcnt lgkmcnt(0)
	s_setprio 1
	s_waitcnt lgkmcnt(0)
	v_mfma_f32_16x16x32_bf16 v[60:63], v[128:131], v[144:147], v[60:63]
	v_mfma_f32_16x16x32_bf16 v[56:59], v[136:139], v[144:147], v[56:59]
	v_mfma_f32_16x16x32_bf16 v[44:47], v[128:131], v[152:155], v[44:47]
	v_mfma_f32_16x16x32_bf16 v[40:43], v[136:139], v[152:155], v[40:43]
	v_mfma_f32_16x16x32_bf16 v[28:31], v[128:131], v[160:163], v[28:31]
	v_mfma_f32_16x16x32_bf16 v[24:27], v[136:139], v[160:163], v[24:27]
	v_mfma_f32_16x16x32_bf16 v[12:15], v[128:131], v[168:171], v[12:15]
	v_mfma_f32_16x16x32_bf16 v[8:11], v[136:139], v[168:171], v[8:11]
	v_mfma_f32_16x16x32_bf16 v[60:63], v[132:135], v[148:151], v[60:63]
	v_mfma_f32_16x16x32_bf16 v[56:59], v[140:143], v[148:151], v[56:59]
	v_mfma_f32_16x16x32_bf16 v[44:47], v[132:135], v[156:159], v[44:47]
	v_mfma_f32_16x16x32_bf16 v[40:43], v[140:143], v[156:159], v[40:43]
	v_mfma_f32_16x16x32_bf16 v[28:31], v[132:135], v[164:167], v[28:31]
	v_mfma_f32_16x16x32_bf16 v[24:27], v[140:143], v[164:167], v[24:27]
	v_mfma_f32_16x16x32_bf16 v[12:15], v[132:135], v[172:175], v[12:15]
	s_barrier
	v_mfma_f32_16x16x32_bf16 v[8:11], v[140:143], v[172:175], v[8:11]
	s_setprio 0
	s_add_u32 s44, s16, 0x160000
	s_addc_u32 s45, s17, 0
	s_add_i32 s43, s34, s21
	s_mov_b32 m0, s43
	s_nop 0
	global_load_lds_dwordx4 v178, s[44:45]
	s_add_i32 m0, s43, 0x2000
	s_nop 0
	global_load_lds_dwordx4 v182, s[44:45]
	s_waitcnt vmcnt(10)
	s_barrier
; #define PG8_STAGE(bufoff, gbase, voff) do { _Pragma("unroll") for (int _i = 0; _i < 2; ++_i) \
;         __builtin_amdgcn_global_load_lds((const unsigned*)((const char*)(gbase) + (voff)[_i]), (LAS unsigned*)(lds + (bufoff) + ldsw + _i * 8192), 16, 0, 0); } while (0)
; #define PG8_LDA(dst, b, h) do { _Pragma("unroll") for (int m = 0; m < 4; ++m) _Pragma("unroll") for (int k = 0; k < 2; ++k) dst[m][k] = *(const LAS bf16x8*)(lds + PG8_SA(b, h) + aoff + m * 2048 + k * 1024); } while (0)
; #define PG8_LDB(dst, b, h) do { _Pragma("unroll") for (int n = 0; n < 2; ++n) _Pragma("unroll") for (int k = 0; k < 2; ++k) dst[n][k] = *(const LAS bf16x8*)(lds + PG8_SB(b, h) + boff + n * 2048 + k * 1024); } while (0)
; #define PG8_MMA(ai, bj, At, Bt) do { __builtin_amdgcn_s_setprio(1); _Pragma("unroll") for (int m = 0; m < 4; ++m) _Pragma("unroll") for (int n = 0; n < 2; ++n) _Pragma("unroll") for (int k = 0; k < 2; ++k) \
;         acc[ai][bj][m][n] = __builtin_amdgcn_mfma_f32_16x16x32_bf16(Bt[n][k], At[m][k], acc[ai][bj][m][n], 0, 0, 0); __builtin_amdgcn_s_setprio(0); } while (0)
; #define PG8_WAIT_V(n) asm volatile("s_waitcnt vmcnt(" #n ")" ::: "memory")
; #define PG8_WAIT_L(n) asm volatile("s_waitcnt lgkmcnt(" #n ")" ::: "memory")
; #define PG8_BAR __builtin_amdgcn_s_barrier()
; #define PG8_SCHED __builtin_amdgcn_sched_barrier(0)
; template <class Epi>
; __device__ __forceinline__ void gemm_phase(ldsp lds, const Gemm g, const StaticOrder& S, const Epi& E) {
;     ...
;             PG8_WAIT_V(10); PG8_BAR; PG8_MMA(1, 1, At, B1); PG8_BAR;
;             PG8_LDB(B0, 1, 0); PG8_SCHED; PG8_LDA(At, 1, 0); PG8_STAGE(PG8_SA(0, 1), a2 + hstep, voffA);
;             PG8_WAIT_L(8); PG8_WAIT_V(10); PG8_BAR; PG8_WAIT_L(0); PG8_MMA(0, 0, At, B0); PG8_BAR; PG8_SCHED;
;             PG8_LDB(B1, 1, 1); PG8_STAGE(PG8_SB(1, 0), b3, voffB);
;             PG8_WAIT_V(10); PG8_BAR; PG8_WAIT_L(0); PG8_MMA(0, 1, At, B1); PG8_BAR;
;             PG8_LDA(At, 1, 1); PG8_STAGE(PG8_SA(1, 0), a3, voffA);
;             PG8_WAIT_V(10); PG8_BAR; PG8_WAIT_L(0); PG8_MMA(1, 0, At, B0); PG8_BAR; PG8_SCHED;
	s_nop 3
	s_setprio 1
	v_mfma_f32_16x16x32_bf16 v[52:55], v[192:195], v[144:147], v[52:55]
	v_mfma_f32_16x16x32_bf16 v[48:51], v[200:203], v[144:147], v[48:51]
	v_mfma_f32_16x16x32_bf16 v[36:39], v[192:195], v[152:155], v[36:39]
	v_mfma_f32_16x16x32_bf16 v[32:35], v[200:203], v[152:155], v[32:35]
	v_mfma_f32_16x16x32_bf16 v[20:23], v[192:195], v[160:163], v[20:23]
	v_mfma_f32_16x16x32_bf16 v[16:19], v[200:203], v[160:163], v[16:19]
	v_mfma_f32_16x16x32_bf16 v[4:7], v[192:195], v[168:171], v[4:7]
	v_mfma_f32_16x16x32_bf16 v[0:3], v[200:203], v[168:171], v[0:3]
	v_mfma_f32_16x16x32_bf16 v[52:55], v[196:199], v[148:151], v[52:55]
	v_mfma_f32_16x16x32_bf16 v[48:51], v[204:207], v[148:151], v[48:51]
	v_mfma_f32_16x16x32_bf16 v[36:39], v[196:199], v[156:159], v[36:39]
	v_mfma_f32_16x16x32_bf16 v[32:35], v[204:207], v[156:159], v[32:35]
	v_mfma_f32_16x16x32_bf16 v[20:23], v[196:199], v[164:167], v[20:23]
	v_mfma_f32_16x16x32_bf16 v[16:19], v[204:207], v[164:167], v[16:19]
	v_mfma_f32_16x16x32_bf16 v[4:7], v[196:199], v[172:175], v[4:7]
	s_barrier
	v_mfma_f32_16x16x32_bf16 v[0:3], v[204:207], v[172:175], v[0:3]
	s_setprio 0
	s_add_i32 s43, 0, 0x18000
	ds_read_b128 v[128:131], v247 offset:32768
	ds_read_b128 v[132:135], v247 offset:33792
	ds_read_b128 v[136:139], v247 offset:34816
	ds_read_b128 v[140:143], v247 offset:35840
	s_add_u32 s18, s18, 0x160000
	s_addc_u32 s19, s19, 0
	s_mov_b32 m0, s24
	ds_read_b128 v[144:147], v212 offset:32768
	ds_read_b128 v[148:151], v212 offset:33792
	ds_read_b128 v[152:155], v212 offset:34816
	ds_read_b128 v[156:159], v212 offset:35840
	ds_read_b128 v[160:163], v212 offset:36864
	ds_read_b128 v[164:167], v212 offset:37888
	ds_read_b128 v[168:171], v212 offset:38912
	ds_read_b128 v[172:175], v212 offset:39936
	global_load_lds_dwordx4 v176, s[18:19]
	s_mov_b32 m0, s25
	s_nop 0
	global_load_lds_dwordx4 v180, s[18:19]
	s_waitcnt lgkmcnt(8)
	s_waitcnt vmcnt(10)
	s_barrier
	s_waitcnt lgkmcnt(0)
	s_setprio 1
	s_waitcnt lgkmcnt(0)
	v_mfma_f32_16x16x32_bf16 v[124:127], v[128:131], v[144:147], v[124:127]
	v_mfma_f32_16x16x32_bf16 v[120:123], v[136:139], v[144:147], v[120:123]
	v_mfma_f32_16x16x32_bf16 v[108:111], v[128:131], v[152:155], v[108:111]
	v_mfma_f32_16x16x32_bf16 v[104:107], v[136:139], v[152:155], v[104:107]
	v_mfma_f32_16x16x32_bf16 v[92:95], v[128:131], v[160:163], v[92:95]
	v_mfma_f32_16x16x32_bf16 v[88:91], v[136:139], v[160:163], v[88:91]
	v_mfma_f32_16x16x32_bf16 v[76:79], v[128:131], v[168:171], v[76:79]
	v_mfma_f32_16x16x32_bf16 v[72:75], v[136:139], v[168:171], v[72:75]
	v_mfma_f32_16x16x32_bf16 v[124:127], v[132:135], v[148:151], v[124:127]
	v_mfma_f32_16x16x32_bf16 v[120:123], v[140:143], v[148:151], v[120:123]
	v_mfma_f32_16x16x32_bf16 v[108:111], v[132:135], v[156:159], v[108:111]
	v_mfma_f32_16x16x32_bf16 v[104:107], v[140:143], v[156:159], v[104:107]
	v_mfma_f32_16x16x32_bf16 v[92:95], v[132:135], v[164:167], v[92:95]
	v_mfma_f32_16x16x32_bf16 v[88:91], v[140:143], v[164:167], v[88:91]
	v_mfma_f32_16x16x32_bf16 v[76:79], v[132:135], v[172:175], v[76:79]
	s_barrier
	v_mfma_f32_16x16x32_bf16 v[72:75], v[140:143], v[172:175], v[72:75]
	s_setprio 0
	s_add_i32 s18, 0, 0x1c000
	s_add_i32 s19, s43, s21
	s_mov_b32 m0, s19
	ds_read_b128 v[192:195], v247 offset:49152
	ds_read_b128 v[196:199], v247 offset:50176
	ds_read_b128 v[200:203], v247 offset:51200
	ds_read_b128 v[204:207], v247 offset:52224
	global_load_lds_dwordx4 v178, s[98:99]
	s_add_i32 m0, s19, 0x2000
	s_nop 0
	global_load_lds_dwordx4 v182, s[98:99]
	s_waitcnt vmcnt(10)
	s_barrier
	s_waitcnt lgkmcnt(0)
	s_setprio 1
	s_waitcnt lgkmcnt(0)
	v_mfma_f32_16x16x32_bf16 v[116:119], v[192:195], v[144:147], v[116:119]
	v_mfma_f32_16x16x32_bf16 v[112:115], v[200:203], v[144:147], v[112:115]
	v_mfma_f32_16x16x32_bf16 v[100:103], v[192:195], v[152:155], v[100:103]
	v_mfma_f32_16x16x32_bf16 v[96:99], v[200:203], v[152:155], v[96:99]
	v_mfma_f32_16x16x32_bf16 v[84:87], v[192:195], v[160:163], v[84:87]
	v_mfma_f32_16x16x32_bf16 v[80:83], v[200:203], v[160:163], v[80:83]
	v_mfma_f32_16x16x32_bf16 v[68:71], v[192:195], v[168:171], v[68:71]
	v_mfma_f32_16x16x32_bf16 v[64:67], v[200:203], v[168:171], v[64:67]
	v_mfma_f32_16x16x32_bf16 v[116:119], v[196:199], v[148:151], v[116:119]
	v_mfma_f32_16x16x32_bf16 v[112:115], v[204:207], v[148:151], v[112:115]
	v_mfma_f32_16x16x32_bf16 v[100:103], v[196:199], v[156:159], v[100:103]
	v_mfma_f32_16x16x32_bf16 v[96:99], v[204:207], v[156:159], v[96:99]
	v_mfma_f32_16x16x32_bf16 v[84:87], v[196:199], v[164:167], v[84:87]
	v_mfma_f32_16x16x32_bf16 v[80:83], v[204:207], v[164:167], v[80:83]
	v_mfma_f32_16x16x32_bf16 v[68:71], v[196:199], v[172:175], v[68:71]
	s_barrier
	v_mfma_f32_16x16x32_bf16 v[64:67], v[204:207], v[172:175], v[64:67]
	s_setprio 0
	s_mov_b32 m0, s27
	ds_read_b128 v[144:147], v212 offset:49152
	ds_read_b128 v[148:151], v212 offset:50176
	ds_read_b128 v[152:155], v212 offset:51200
	ds_read_b128 v[156:159], v212 offset:52224
	ds_read_b128 v[160:163], v212 offset:53248
	ds_read_b128 v[164:167], v212 offset:54272
	ds_read_b128 v[168:171], v212 offset:55296
	ds_read_b128 v[172:175], v212 offset:56320
	global_load_lds_dwordx4 v176, s[100:101]
	s_mov_b32 m0, s28
	s_nop 0
	global_load_lds_dwordx4 v180, s[100:101]
	s_waitcnt vmcnt(10)
	s_barrier
; #define PG8_STAGE(bufoff, gbase, voff) do { _Pragma("unroll") for (int _i = 0; _i < 2; ++_i) \
;         __builtin_amdgcn_global_load_lds((const unsigned*)((const char*)(gbase) + (voff)[_i]), (LAS unsigned*)(lds + (bufoff) + ldsw + _i * 8192), 16, 0, 0); } while (0)
; #define PG8_WAIT_V(n) asm volatile("s_waitcnt vmcnt(" #n ")" ::: "memory")
; #define PG8_WAIT_L(n) asm volatile("s_waitcnt lgkmcnt(" #n ")" ::: "memory")
; #define PG8_BAR __builtin_amdgcn_s_barrier()
; #define PG8_SCHED __builtin_amdgcn_sched_barrier(0)
; template <class Epi>
; __device__ __forceinline__ void gemm_phase(ldsp lds, const Gemm g, const StaticOrder& S, const Epi& E) {
;     ...
;             PG8_WAIT_V(10); PG8_BAR; PG8_WAIT_L(0); PG8_MMA(1, 0, At, B0); PG8_BAR; PG8_SCHED;
;             PG8_STAGE(PG8_SB(1, 1), b3 + hstep, voffB);
;             PG8_WAIT_V(10); PG8_BAR; PG8_MMA(1, 1, At, B1); PG8_BAR;
;     __device__ __forceinline__ void ld(f32x4 (&xv)[2][2][2], int row0, int col0, int ai, int mh) const {
; #pragma unroll
;         for (int mm = 0; mm < 2; ++mm)
; #pragma unroll
;             for (int bj = 0; bj < 2; ++bj) { const size_t off = (size_t)(row0 + ai * 128 + (2 * mh + mm) * 16) * 2048 + col0 + bj * 128;
;                 xv[mm][bj][0] = *(const f32x4*)(base + off); xv[mm][bj][1] = *(const f32x4*)(base + off + 4); }
;     }
;     __device__ __forceinline__ void fin(const f32x4 (&acc)[2][2][4][2], const f32x4 (&xv)[2][2][2], int row0, int col0, int fq, int ai, int mh) const {
; #pragma unroll
;         for (int mm = 0; mm < 2; ++mm) { const int m = 2 * mh + mm; const int row = row0 + ai * 128 + m * 16; float sq = 0.f;
; #pragma unroll
;             for (int bj = 0; bj < 2; ++bj) { const size_t off = (size_t)row * 2048 + col0 + bj * 128;
;                 const f32x4 y0 = xv[mm][bj][0] + acc[ai][bj][m][0], y1 = xv[mm][bj][1] + acc[ai][bj][m][1];
;                 *(f32x4*)(out + off) = y0; *(f32x4*)(out + off + 4) = y1;
;                 if (ob) *(u32x4*)(ob + off) = pack8(y0, y1);
;                 sq += (y0[0] * y0[0] + y0[1] * y0[1]) + (y0[2] * y0[2] + y0[3] * y0[3]) + (y1[0] * y1[0] + y1[1] * y1[1]) + (y1[2] * y1[2] + y1[3] * y1[3]); }
;             sq += __shfl_xor(sq, 16); sq += __shfl_xor(sq, 32);
;             if (fq == 0) atomicAdd(ssq + row, (unsigned long long)(sq * 16777216.0f + 0.5f)); }
	s_waitcnt lgkmcnt(0)
	s_setprio 1
	s_waitcnt lgkmcnt(0)
	v_mfma_f32_16x16x32_bf16 v[60:63], v[128:131], v[144:147], v[60:63]
	v_mfma_f32_16x16x32_bf16 v[56:59], v[136:139], v[144:147], v[56:59]
	v_mfma_f32_16x16x32_bf16 v[44:47], v[128:131], v[152:155], v[44:47]
	v_mfma_f32_16x16x32_bf16 v[40:43], v[136:139], v[152:155], v[40:43]
	v_mfma_f32_16x16x32_bf16 v[28:31], v[128:131], v[160:163], v[28:31]
	v_mfma_f32_16x16x32_bf16 v[24:27], v[136:139], v[160:163], v[24:27]
	v_mfma_f32_16x16x32_bf16 v[12:15], v[128:131], v[168:171], v[12:15]
	v_mfma_f32_16x16x32_bf16 v[8:11], v[136:139], v[168:171], v[8:11]
	v_mfma_f32_16x16x32_bf16 v[60:63], v[132:135], v[148:151], v[60:63]
	v_mfma_f32_16x16x32_bf16 v[56:59], v[140:143], v[148:151], v[56:59]
	v_mfma_f32_16x16x32_bf16 v[44:47], v[132:135], v[156:159], v[44:47]
	v_mfma_f32_16x16x32_bf16 v[40:43], v[140:143], v[156:159], v[40:43]
	v_mfma_f32_16x16x32_bf16 v[28:31], v[132:135], v[164:167], v[28:31]
	v_mfma_f32_16x16x32_bf16 v[24:27], v[140:143], v[164:167], v[24:27]
	v_mfma_f32_16x16x32_bf16 v[12:15], v[132:135], v[172:175], v[12:15]
	s_barrier
	v_mfma_f32_16x16x32_bf16 v[8:11], v[140:143], v[172:175], v[8:11]
	s_setprio 0
	s_add_u32 s16, s16, 0x160080
	s_addc_u32 s17, s17, 0
	s_add_i32 s18, s18, s21
	s_mov_b32 m0, s18
	s_nop 0
	global_load_lds_dwordx4 v178, s[16:17]
	s_add_i32 m0, s18, 0x2000
	s_nop 0
	global_load_lds_dwordx4 v182, s[16:17]
	s_waitcnt vmcnt(10)
	s_barrier
	s_nop 3
	s_setprio 1
	v_mfma_f32_16x16x32_bf16 v[52:55], v[192:195], v[144:147], v[52:55]
	v_mfma_f32_16x16x32_bf16 v[48:51], v[200:203], v[144:147], v[48:51]
	v_mfma_f32_16x16x32_bf16 v[36:39], v[192:195], v[152:155], v[36:39]
	v_mfma_f32_16x16x32_bf16 v[32:35], v[200:203], v[152:155], v[32:35]
	v_mfma_f32_16x16x32_bf16 v[20:23], v[192:195], v[160:163], v[20:23]
	v_mfma_f32_16x16x32_bf16 v[16:19], v[200:203], v[160:163], v[16:19]
	v_mfma_f32_16x16x32_bf16 v[4:7], v[192:195], v[168:171], v[4:7]
	v_mfma_f32_16x16x32_bf16 v[0:3], v[200:203], v[168:171], v[0:3]
	v_mfma_f32_16x16x32_bf16 v[52:55], v[196:199], v[148:151], v[52:55]
	v_mfma_f32_16x16x32_bf16 v[48:51], v[204:207], v[148:151], v[48:51]
	v_mfma_f32_16x16x32_bf16 v[36:39], v[196:199], v[156:159], v[36:39]
	v_mfma_f32_16x16x32_bf16 v[32:35], v[204:207], v[156:159], v[32:35]
	v_mfma_f32_16x16x32_bf16 v[20:23], v[196:199], v[164:167], v[20:23]
	v_mfma_f32_16x16x32_bf16 v[16:19], v[204:207], v[164:167], v[16:19]
	v_mfma_f32_16x16x32_bf16 v[4:7], v[196:199], v[172:175], v[4:7]
	s_barrier
	v_mfma_f32_16x16x32_bf16 v[0:3], v[204:207], v[172:175], v[0:3]
	s_setprio 0
	s_add_i32 s42, s42, 2
	s_add_u32 s14, s14, 0x100
	s_addc_u32 s15, s15, 0
	s_add_u32 s40, s40, 0x100
	s_addc_u32 s41, s41, 0
	s_cmpk_gt_u32 s42, 0x55
	s_cbranch_scc0 .LBB0_899
	v_lshl_add_u32 v192, s38, 8, v208
	v_lshl_or_b32 v128, s39, 8, v210
	v_ashrrev_i32_e32 v193, 31, v192
	v_ashrrev_i32_e32 v129, 31, v128
	v_lshlrev_b64 v[130:131], 13, v[192:193]
	v_lshl_add_u64 v[130:131], s[70:71], 0, v[130:131]
	v_lshlrev_b64 v[194:195], 2, v[128:129]
	v_lshl_add_u64 v[234:235], v[130:131], 0, v[194:195]
	global_load_dwordx4 v[216:219], v[234:235], off
	global_load_dwordx4 v[222:225], v[234:235], off offset:16
	global_load_dwordx4 v[226:229], v[234:235], off offset:512
	global_load_dwordx4 v[230:233], v[234:235], off offset:528
	v_or_b32_e32 v204, 16, v192
	v_or_b32_e32 v200, 32, v192
	v_or_b32_e32 v196, 48, v192
	v_ashrrev_i32_e32 v205, 31, v204
	v_ashrrev_i32_e32 v201, 31, v200
	v_ashrrev_i32_e32 v197, 31, v196
	v_lshlrev_b64 v[128:129], 13, v[204:205]
	v_lshlrev_b64 v[130:131], 13, v[200:201]
	v_lshlrev_b64 v[132:133], 13, v[196:197]
	v_lshl_add_u64 v[128:129], s[70:71], 0, v[128:129]
	v_lshl_add_u64 v[130:131], s[70:71], 0, v[130:131]
	v_lshl_add_u64 v[132:133], s[70:71], 0, v[132:133]
	v_lshl_add_u64 v[206:207], v[128:129], 0, v[194:195]
	v_lshl_add_u64 v[202:203], v[130:131], 0, v[194:195]
	v_lshl_add_u64 v[198:199], v[132:133], 0, v[194:195]
	global_load_dwordx4 v[168:171], v[206:207], off offset:16
	global_load_dwordx4 v[172:175], v[206:207], off
	global_load_dwordx4 v[160:163], v[206:207], off offset:528
	global_load_dwordx4 v[164:167], v[206:207], off offset:512
	global_load_dwordx4 v[152:155], v[202:203], off offset:16
	global_load_dwordx4 v[156:159], v[202:203], off
	global_load_dwordx4 v[144:147], v[202:203], off offset:528
	global_load_dwordx4 v[148:151], v[202:203], off offset:512
	global_load_dwordx4 v[136:139], v[198:199], off offset:16
	global_load_dwordx4 v[140:143], v[198:199], off
	global_load_dwordx4 v[128:131], v[198:199], off offset:528
	global_load_dwordx4 v[132:135], v[198:199], off offset:512
	v_and_b32_e32 v221, 64, v214
	v_xor_b32_e32 v215, 16, v214
	v_add_u32_e32 v221, 64, v221
	v_cmp_lt_i32_e32 vcc, v215, v221
	s_waitcnt vmcnt(0)
	v_pk_add_f32 v[126:127], v[126:127], v[218:219]
	v_pk_add_f32 v[124:125], v[124:125], v[216:217]
	v_pk_add_f32 v[118:119], v[118:119], v[228:229]
	v_pk_add_f32 v[116:117], v[116:117], v[226:227]
	v_pk_add_f32 v[120:121], v[120:121], v[222:223]
	v_pk_add_f32 v[222:223], v[112:113], v[230:231]
	v_mul_f32_e32 v112, v125, v125
	v_mul_f32_e32 v113, v127, v127
	v_mul_f32_e32 v216, v117, v117
	v_mul_f32_e32 v217, v119, v119
	v_pk_add_f32 v[122:123], v[122:123], v[224:225]
	v_pk_add_f32 v[224:225], v[114:115], v[232:233]
	v_mul_f32_e32 v114, v121, v121
	v_mul_f32_e32 v218, v223, v223
	v_fmac_f32_e32 v112, v124, v124
	v_fmac_f32_e32 v113, v126, v126
	v_fmac_f32_e32 v216, v116, v116
	v_fmac_f32_e32 v217, v118, v118
	v_mul_f32_e32 v115, v123, v123
	v_mul_f32_e32 v219, v225, v225
	v_fmac_f32_e32 v114, v120, v120
	v_fmac_f32_e32 v218, v222, v222
	v_add_f32_e32 v112, v112, v113
	v_add_f32_e32 v113, v216, v217
	v_fmac_f32_e32 v115, v122, v122
	v_fmac_f32_e32 v219, v224, v224
	v_add_f32_e32 v112, v112, v114
	v_add_f32_e32 v113, v113, v218
	v_cndmask_b32_e32 v215, v214, v215, vcc
	v_add_f32_e32 v112, v115, v112
	v_add_f32_e32 v113, v219, v113
	v_lshlrev_b32_e32 v215, 2, v215
	v_add_f32_e32 v112, v112, v113
	ds_bpermute_b32 v113, v215, v112
	v_xor_b32_e32 v114, 32, v214
	v_cmp_lt_i32_e32 vcc, v114, v221
	global_store_dwordx4 v[234:235], v[124:127], off
	global_store_dwordx4 v[234:235], v[120:123], off offset:16
	global_store_dwordx4 v[234:235], v[116:119], off offset:512
	global_store_dwordx4 v[234:235], v[222:225], off offset:528
	v_cndmask_b32_e32 v114, v214, v114, vcc
	v_lshlrev_b32_e32 v216, 2, v114
	s_waitcnt lgkmcnt(0)
	v_add_f32_e32 v112, v112, v113
	ds_bpermute_b32 v113, v216, v112
	s_and_saveexec_b64 s[14:15], s[2:3]
	s_cbranch_execz .LBB0_902
	s_waitcnt lgkmcnt(0)
	v_add_f32_e32 v112, v112, v113
	v_fma_f32 v112, v112, s35, 0.5
	v_trunc_f32_e32 v112, v112
	v_mul_f32_e32 v113, 0x2f800000, v112
	v_floor_f32_e32 v113, v113
	v_fmac_f32_e32 v112, 0xcf800000, v113
	v_cvt_u32_f32_e32 v112, v112
	v_cvt_u32_f32_e32 v113, v113
	v_lshl_add_u64 v[114:115], v[192:193], 3, s[8:9]
	global_atomic_add_x2 v[114:115], v[112:113], off
